# c4 plus P1 tile-header wait removed, Q/K epilogue table prefetch, P5 row-sum as add tree, P5 bias-minus-ref as packed adds, 8-byte code placement kept
# speedup vs baseline: 1.0062x; 1.0062x over previous
.LBB0_317:
	s_ashr_i32 s27, s26, 31
	s_lshl_b64 s[28:29], s[26:27], 20
	s_add_u32 s28, s42, s28
	s_addc_u32 s29, s43, s29
	s_and_b64 s[30:31], s[4:5], exec
	s_cselect_b32 s9, s29, s7
	s_cselect_b32 s27, s28, s6
	s_ashr_i32 s25, s24, 31
	s_lshl_b64 s[30:31], s[24:25], 20
	s_add_u32 s30, s44, s30
	s_addc_u32 s31, s45, s31
	s_and_b64 s[38:39], s[4:5], exec
	s_cselect_b32 s25, s31, s37
	s_cselect_b32 s62, s30, s36
	s_ashr_i32 s35, s34, 31
	s_lshl_b64 s[38:39], s[34:35], 13
	s_add_u32 s35, s36, 0x100
	v_mov_b32_e32 v0, 0
	v_mov_b32_e32 v179, v178
	v_mov_b32_e32 v178, v191
	v_mov_b32_e32 v191, v190
	v_mov_b32_e32 v190, v185
	v_mov_b32_e32 v185, v215
	v_mov_b32_e32 v203, v214
	v_lshl_add_u64 v[128:129], v[164:165], 0, s[38:39]
	v_lshl_add_u64 v[130:131], s[6:7], 0, v[170:171]
	s_nop 0
	v_lshl_add_u64 v[132:133], s[6:7], 0, v[172:173]
	s_addc_u32 s63, s37, 0
	s_mov_b32 s64, -2
	s_mov_b64 s[36:37], 0
	v_mov_b32_e32 v1, v0
	v_mov_b32_e32 v2, v0
	v_mov_b32_e32 v3, v0
	v_mov_b32_e32 v4, v0
	v_mov_b32_e32 v5, v0
	v_mov_b32_e32 v6, v0
	v_mov_b32_e32 v7, v0
	v_mov_b32_e32 v8, v0
	v_mov_b32_e32 v9, v0
	v_mov_b32_e32 v10, v0
	v_mov_b32_e32 v11, v0
	v_mov_b32_e32 v12, v0
	v_mov_b32_e32 v13, v0
	v_mov_b32_e32 v14, v0
	v_mov_b32_e32 v15, v0
	v_mov_b32_e32 v20, v0
	v_mov_b32_e32 v21, v0
	v_mov_b32_e32 v22, v0
	v_mov_b32_e32 v23, v0
	v_mov_b32_e32 v24, v0
	v_mov_b32_e32 v25, v0
	v_mov_b32_e32 v26, v0
	v_mov_b32_e32 v27, v0
	v_mov_b32_e32 v36, v0
	v_mov_b32_e32 v37, v0
	v_mov_b32_e32 v38, v0
	v_mov_b32_e32 v39, v0
	v_mov_b32_e32 v40, v0
	v_mov_b32_e32 v41, v0
	v_mov_b32_e32 v42, v0
	v_mov_b32_e32 v43, v0
	v_mov_b32_e32 v112, v0
	v_mov_b32_e32 v113, v0
	v_mov_b32_e32 v114, v0
	v_mov_b32_e32 v115, v0
	v_mov_b32_e32 v116, v0
	v_mov_b32_e32 v117, v0
	v_mov_b32_e32 v118, v0
	v_mov_b32_e32 v119, v0
	v_mov_b32_e32 v16, v0
	v_mov_b32_e32 v17, v0
	v_mov_b32_e32 v18, v0
	v_mov_b32_e32 v19, v0
	v_mov_b32_e32 v28, v0
	v_mov_b32_e32 v29, v0
	v_mov_b32_e32 v30, v0
	v_mov_b32_e32 v31, v0
	v_mov_b32_e32 v32, v0
	v_mov_b32_e32 v33, v0
	v_mov_b32_e32 v34, v0
	v_mov_b32_e32 v35, v0
	v_mov_b32_e32 v44, v0
	v_mov_b32_e32 v45, v0
	v_mov_b32_e32 v46, v0
	v_mov_b32_e32 v47, v0
	v_mov_b32_e32 v48, v0
	v_mov_b32_e32 v49, v0
	v_mov_b32_e32 v50, v0
	v_mov_b32_e32 v51, v0
	v_mov_b32_e32 v52, v0
	v_mov_b32_e32 v53, v0
	v_mov_b32_e32 v54, v0
	v_mov_b32_e32 v55, v0
	v_mov_b32_e32 v56, v0
	v_mov_b32_e32 v57, v0
	v_mov_b32_e32 v58, v0
	v_mov_b32_e32 v59, v0
	v_mov_b32_e32 v60, v0
	v_mov_b32_e32 v61, v0
	v_mov_b32_e32 v62, v0
	v_mov_b32_e32 v63, v0
	v_mov_b32_e32 v68, v0
	v_mov_b32_e32 v69, v0
	v_mov_b32_e32 v70, v0
	v_mov_b32_e32 v71, v0
	v_mov_b32_e32 v72, v0
	v_mov_b32_e32 v73, v0
	v_mov_b32_e32 v74, v0
	v_mov_b32_e32 v75, v0
	v_mov_b32_e32 v84, v0
	v_mov_b32_e32 v85, v0
	v_mov_b32_e32 v86, v0
	v_mov_b32_e32 v87, v0
	v_mov_b32_e32 v88, v0
	v_mov_b32_e32 v89, v0
	v_mov_b32_e32 v90, v0
	v_mov_b32_e32 v91, v0
	v_mov_b32_e32 v100, v0
	v_mov_b32_e32 v101, v0
	v_mov_b32_e32 v102, v0
	v_mov_b32_e32 v103, v0
	v_mov_b32_e32 v104, v0
	v_mov_b32_e32 v105, v0
	v_mov_b32_e32 v106, v0
	v_mov_b32_e32 v107, v0
	v_mov_b32_e32 v64, v0
	v_mov_b32_e32 v65, v0
	v_mov_b32_e32 v66, v0
	v_mov_b32_e32 v67, v0
	v_mov_b32_e32 v76, v0
	v_mov_b32_e32 v77, v0
	v_mov_b32_e32 v78, v0
	v_mov_b32_e32 v79, v0
	v_mov_b32_e32 v80, v0
	v_mov_b32_e32 v81, v0
	v_mov_b32_e32 v82, v0
	v_mov_b32_e32 v83, v0
	v_mov_b32_e32 v92, v0
	v_mov_b32_e32 v93, v0
	v_mov_b32_e32 v94, v0
	v_mov_b32_e32 v95, v0
	v_mov_b32_e32 v96, v0
	v_mov_b32_e32 v97, v0
	v_mov_b32_e32 v98, v0
	v_mov_b32_e32 v99, v0
	v_mov_b32_e32 v108, v0
	v_mov_b32_e32 v109, v0
	v_mov_b32_e32 v110, v0
	v_mov_b32_e32 v111, v0
	v_mov_b32_e32 v120, v0
	v_mov_b32_e32 v121, v0
	v_mov_b32_e32 v122, v0
	v_mov_b32_e32 v123, v0
	v_mov_b32_e32 v124, v0
	v_mov_b32_e32 v125, v0
	v_mov_b32_e32 v126, v0
	v_mov_b32_e32 v127, v0
	s_branch .LBB0_319

.LBB0_359:
	s_cmp_lt_u32 s8, 8
	s_cselect_b32 s37, s13, s15
	s_cselect_b32 s36, s12, s14
	s_lshl_b32 s38, s52, 2
	s_add_u32 s36, s36, s38
	s_addc_u32 s37, s37, 0
	v_lshlrev_b32_e32 v244, 2, v162
	global_load_dwordx4 v[232:235], v244, s[36:37] offset:16
	global_load_dwordx4 v[236:239], v244, s[36:37]
	s_and_b64 vcc, exec, s[22:23]
	s_cbranch_vccz .Lp1qk_pre_done
	s_lshl_b32 s38, s34, 8
	v_add_u32_e32 v240, s38, v163
	v_ashrrev_i32_e32 v241, 31, v240
	v_lshlrev_b64 v[240:241], 6, v[240:241]
	v_lshl_add_u64 v[242:243], v[166:167], 0, v[240:241]
	v_lshl_add_u64 v[240:241], v[168:169], 0, v[240:241]
	s_mov_b64 s[38:39], 0x2000
	global_load_dwordx4 v[136:139], v[240:241], off
	global_load_dwordx4 v[140:143], v[240:241], off offset:16
	global_load_dwordx4 v[124:127], v[242:243], off offset:16
	global_load_dwordx4 v[132:135], v[242:243], off
	global_load_dwordx4 v[216:219], v[240:241], off offset:1024
	global_load_dwordx4 v[220:223], v[240:241], off offset:1040
	global_load_dwordx4 v[228:231], v[242:243], off offset:1040
	global_load_dwordx4 v[224:227], v[242:243], off offset:1024
.Lp1qk_pre_done:
	v_mul_f32_e32 v112, v145, v145
	v_mul_f32_e32 v113, v147, v147
	v_fmac_f32_e32 v112, v144, v144
	v_fmac_f32_e32 v113, v146, v146
	v_add_f32_e32 v112, v112, v113
	v_mul_f32_e32 v113, v149, v149
	v_fmac_f32_e32 v113, v148, v148
	v_add_f32_e32 v112, v113, v112
	v_mul_f32_e32 v113, v151, v151
	v_fmac_f32_e32 v113, v150, v150
	v_add_f32_e32 v112, v113, v112
	v_mov_b32_e32 v113, v112
	s_nop 1
	v_permlane16_swap_b32_e32 v112, v113
	v_add_f32_e32 v112, v112, v113
	v_mov_b32_e32 v113, v112
	s_nop 1
	v_permlane32_swap_b32_e32 v112, v113
	s_and_saveexec_b64 s[6:7], s[0:1]
	v_add_f32_e32 v112, v112, v113
	ds_write_b32 v193, v112
	s_or_b64 exec, exec, s[6:7]
	v_mul_f32_e32 v112, v121, v121
	v_mul_f32_e32 v113, v123, v123
	v_fmac_f32_e32 v112, v120, v120
	v_fmac_f32_e32 v113, v122, v122
	v_add_f32_e32 v112, v112, v113
	v_mul_f32_e32 v113, v129, v129
	v_fmac_f32_e32 v113, v128, v128
	v_add_f32_e32 v112, v113, v112
	v_mul_f32_e32 v113, v131, v131
	v_fmac_f32_e32 v113, v130, v130
	v_add_f32_e32 v112, v113, v112
	v_mov_b32_e32 v113, v112
	s_nop 1
	v_permlane16_swap_b32_e32 v112, v113
	v_add_f32_e32 v112, v112, v113
	v_mov_b32_e32 v113, v112
	s_nop 1
	v_permlane32_swap_b32_e32 v112, v113
	s_and_saveexec_b64 s[6:7], s[0:1]
	v_add_f32_e32 v112, v112, v113
	ds_write_b32 v193, v112 offset:16
	s_or_b64 exec, exec, s[6:7]
	v_mul_f32_e32 v112, v105, v105
	v_mul_f32_e32 v113, v107, v107
	v_fmac_f32_e32 v112, v104, v104
	v_fmac_f32_e32 v113, v106, v106
	v_add_f32_e32 v112, v112, v113
	v_mul_f32_e32 v113, v109, v109
	v_fmac_f32_e32 v113, v108, v108
	v_add_f32_e32 v112, v113, v112
	v_mul_f32_e32 v113, v111, v111
	v_fmac_f32_e32 v113, v110, v110
	v_add_f32_e32 v112, v113, v112
	v_mov_b32_e32 v113, v112
	s_nop 1
	v_permlane16_swap_b32_e32 v112, v113
	v_add_f32_e32 v112, v112, v113
	v_mov_b32_e32 v113, v112
	s_nop 1
	v_permlane32_swap_b32_e32 v112, v113
	s_and_saveexec_b64 s[6:7], s[0:1]
	v_add_f32_e32 v112, v112, v113
	ds_write_b32 v194, v112
	s_or_b64 exec, exec, s[6:7]
	v_mul_f32_e32 v112, v97, v97
	v_mul_f32_e32 v113, v99, v99
	v_fmac_f32_e32 v112, v96, v96
	v_fmac_f32_e32 v113, v98, v98
	v_add_f32_e32 v112, v112, v113
	v_mul_f32_e32 v113, v101, v101
	v_fmac_f32_e32 v113, v100, v100
	v_add_f32_e32 v112, v113, v112
	v_mul_f32_e32 v113, v103, v103
	v_fmac_f32_e32 v113, v102, v102
	v_add_f32_e32 v112, v113, v112
	v_mov_b32_e32 v113, v112
	s_nop 1
	v_permlane16_swap_b32_e32 v112, v113
	v_add_f32_e32 v112, v112, v113
	v_mov_b32_e32 v113, v112
	s_nop 1
	v_permlane32_swap_b32_e32 v112, v113
	s_and_saveexec_b64 s[6:7], s[0:1]
	v_add_f32_e32 v112, v112, v113
	ds_write_b32 v194, v112 offset:16
	s_or_b64 exec, exec, s[6:7]
	v_mul_f32_e32 v112, v89, v89
	v_mul_f32_e32 v113, v91, v91
	v_fmac_f32_e32 v112, v88, v88
	v_fmac_f32_e32 v113, v90, v90
	v_add_f32_e32 v112, v112, v113
	v_mul_f32_e32 v113, v93, v93
	v_fmac_f32_e32 v113, v92, v92
	v_add_f32_e32 v112, v113, v112
	v_mul_f32_e32 v113, v95, v95
	v_fmac_f32_e32 v113, v94, v94
	v_add_f32_e32 v112, v113, v112
	v_mov_b32_e32 v113, v112
	s_nop 1
	v_permlane16_swap_b32_e32 v112, v113
	v_add_f32_e32 v112, v112, v113
	v_mov_b32_e32 v113, v112
	s_nop 1
	v_permlane32_swap_b32_e32 v112, v113
	s_and_saveexec_b64 s[6:7], s[0:1]
	v_add_f32_e32 v112, v112, v113
	ds_write_b32 v195, v112
	s_or_b64 exec, exec, s[6:7]
	v_mul_f32_e32 v112, v81, v81
	v_mul_f32_e32 v113, v83, v83
	v_fmac_f32_e32 v112, v80, v80
	v_fmac_f32_e32 v113, v82, v82
	v_add_f32_e32 v112, v112, v113
	v_mul_f32_e32 v113, v85, v85
	v_fmac_f32_e32 v113, v84, v84
	v_add_f32_e32 v112, v113, v112
	v_mul_f32_e32 v113, v87, v87
	v_fmac_f32_e32 v113, v86, v86
	v_add_f32_e32 v112, v113, v112
	v_mov_b32_e32 v113, v112
	s_nop 1
	v_permlane16_swap_b32_e32 v112, v113
	v_add_f32_e32 v112, v112, v113
	v_mov_b32_e32 v113, v112
	s_nop 1
	v_permlane32_swap_b32_e32 v112, v113
	s_and_saveexec_b64 s[6:7], s[0:1]
	v_add_f32_e32 v112, v112, v113
	ds_write_b32 v195, v112 offset:16
	s_or_b64 exec, exec, s[6:7]
	v_mul_f32_e32 v112, v73, v73
	v_mul_f32_e32 v113, v75, v75
	v_fmac_f32_e32 v112, v72, v72
	v_fmac_f32_e32 v113, v74, v74
	v_add_f32_e32 v112, v112, v113
	v_mul_f32_e32 v113, v77, v77
	v_fmac_f32_e32 v113, v76, v76
	v_add_f32_e32 v112, v113, v112
	v_mul_f32_e32 v113, v79, v79
	v_fmac_f32_e32 v113, v78, v78
	v_add_f32_e32 v112, v113, v112
	v_mov_b32_e32 v113, v112
	s_nop 1
	v_permlane16_swap_b32_e32 v112, v113
	v_add_f32_e32 v112, v112, v113
	v_mov_b32_e32 v113, v112
	s_nop 1
	v_permlane32_swap_b32_e32 v112, v113
	s_and_saveexec_b64 s[6:7], s[0:1]
	v_add_f32_e32 v112, v112, v113
	ds_write_b32 v196, v112
	s_or_b64 exec, exec, s[6:7]
	v_mul_f32_e32 v112, v65, v65
	v_mul_f32_e32 v113, v67, v67
	v_fmac_f32_e32 v112, v64, v64
	v_fmac_f32_e32 v113, v66, v66
	v_add_f32_e32 v112, v112, v113
	v_mul_f32_e32 v113, v69, v69
	v_fmac_f32_e32 v113, v68, v68
	v_add_f32_e32 v112, v113, v112
	v_mul_f32_e32 v113, v71, v71
	v_fmac_f32_e32 v113, v70, v70
	v_add_f32_e32 v112, v113, v112
	v_mov_b32_e32 v113, v112
	s_nop 1
	v_permlane16_swap_b32_e32 v112, v113
	v_add_f32_e32 v112, v112, v113
	v_mov_b32_e32 v113, v112
	s_nop 1
	v_permlane32_swap_b32_e32 v112, v113
	s_and_saveexec_b64 s[6:7], s[0:1]
	v_add_f32_e32 v112, v112, v113
	ds_write_b32 v196, v112 offset:16
	s_or_b64 exec, exec, s[6:7]
	v_mul_f32_e32 v112, v57, v57
	v_mul_f32_e32 v113, v59, v59
	v_fmac_f32_e32 v112, v56, v56
	v_fmac_f32_e32 v113, v58, v58
	v_add_f32_e32 v112, v112, v113
	v_mul_f32_e32 v113, v61, v61
	v_fmac_f32_e32 v113, v60, v60
	v_add_f32_e32 v112, v113, v112
	v_mul_f32_e32 v113, v63, v63
	v_fmac_f32_e32 v113, v62, v62
	v_add_f32_e32 v112, v113, v112
	v_mov_b32_e32 v113, v112
	s_nop 1
	v_permlane16_swap_b32_e32 v112, v113
	v_add_f32_e32 v112, v112, v113
	v_mov_b32_e32 v113, v112
	s_nop 1
	v_permlane32_swap_b32_e32 v112, v113
	s_and_saveexec_b64 s[6:7], s[0:1]
	v_add_f32_e32 v112, v112, v113
	ds_write_b32 v197, v112
	s_or_b64 exec, exec, s[6:7]
	v_mul_f32_e32 v112, v49, v49
	v_mul_f32_e32 v113, v51, v51
	v_fmac_f32_e32 v112, v48, v48
	v_fmac_f32_e32 v113, v50, v50
	v_add_f32_e32 v112, v112, v113
	v_mul_f32_e32 v113, v53, v53
	v_fmac_f32_e32 v113, v52, v52
	v_add_f32_e32 v112, v113, v112
	v_mul_f32_e32 v113, v55, v55
	v_fmac_f32_e32 v113, v54, v54
	v_add_f32_e32 v112, v113, v112
	v_mov_b32_e32 v113, v112
	s_nop 1
	v_permlane16_swap_b32_e32 v112, v113
	v_add_f32_e32 v112, v112, v113
	v_mov_b32_e32 v113, v112
	s_nop 1
	v_permlane32_swap_b32_e32 v112, v113
	s_and_saveexec_b64 s[6:7], s[0:1]
	v_add_f32_e32 v112, v112, v113
	ds_write_b32 v197, v112 offset:16
	s_or_b64 exec, exec, s[6:7]
	v_mul_f32_e32 v112, v41, v41
	v_mul_f32_e32 v113, v43, v43
	v_fmac_f32_e32 v112, v40, v40
	v_fmac_f32_e32 v113, v42, v42
	v_add_f32_e32 v112, v112, v113
	v_mul_f32_e32 v113, v45, v45
	v_fmac_f32_e32 v113, v44, v44
	v_add_f32_e32 v112, v113, v112
	v_mul_f32_e32 v113, v47, v47
	v_fmac_f32_e32 v113, v46, v46
	v_add_f32_e32 v112, v113, v112
	v_mov_b32_e32 v113, v112
	s_nop 1
	v_permlane16_swap_b32_e32 v112, v113
	v_add_f32_e32 v112, v112, v113
	v_mov_b32_e32 v113, v112
	s_nop 1
	v_permlane32_swap_b32_e32 v112, v113
	s_and_saveexec_b64 s[6:7], s[0:1]
	v_add_f32_e32 v112, v112, v113
	ds_write_b32 v198, v112
	s_or_b64 exec, exec, s[6:7]
	v_mul_f32_e32 v112, v33, v33
	v_mul_f32_e32 v113, v35, v35
	v_fmac_f32_e32 v112, v32, v32
	v_fmac_f32_e32 v113, v34, v34
	v_add_f32_e32 v112, v112, v113
	v_mul_f32_e32 v113, v37, v37
	v_fmac_f32_e32 v113, v36, v36
	v_add_f32_e32 v112, v113, v112
	v_mul_f32_e32 v113, v39, v39
	v_fmac_f32_e32 v113, v38, v38
	v_add_f32_e32 v112, v113, v112
	v_mov_b32_e32 v113, v112
	s_nop 1
	v_permlane16_swap_b32_e32 v112, v113
	v_add_f32_e32 v112, v112, v113
	v_mov_b32_e32 v113, v112
	s_nop 1
	v_permlane32_swap_b32_e32 v112, v113
	s_and_saveexec_b64 s[6:7], s[0:1]
	v_add_f32_e32 v112, v112, v113
	ds_write_b32 v198, v112 offset:16
	s_or_b64 exec, exec, s[6:7]
	v_mul_f32_e32 v112, v25, v25
	v_mul_f32_e32 v113, v27, v27
	v_fmac_f32_e32 v112, v24, v24
	v_fmac_f32_e32 v113, v26, v26
	v_add_f32_e32 v112, v112, v113
	v_mul_f32_e32 v113, v29, v29
	v_fmac_f32_e32 v113, v28, v28
	v_add_f32_e32 v112, v113, v112
	v_mul_f32_e32 v113, v31, v31
	v_fmac_f32_e32 v113, v30, v30
	v_add_f32_e32 v112, v113, v112
	v_mov_b32_e32 v113, v112
	s_nop 1
	v_permlane16_swap_b32_e32 v112, v113
	v_add_f32_e32 v112, v112, v113
	v_mov_b32_e32 v113, v112
	s_nop 1
	v_permlane32_swap_b32_e32 v112, v113
	s_and_saveexec_b64 s[6:7], s[0:1]
	v_add_f32_e32 v112, v112, v113
	ds_write_b32 v199, v112
	s_or_b64 exec, exec, s[6:7]
	v_mul_f32_e32 v112, v17, v17
	v_mul_f32_e32 v113, v19, v19
	v_fmac_f32_e32 v112, v16, v16
	v_fmac_f32_e32 v113, v18, v18
	v_add_f32_e32 v112, v112, v113
	v_mul_f32_e32 v113, v21, v21
	v_fmac_f32_e32 v113, v20, v20
	v_add_f32_e32 v112, v113, v112
	v_mul_f32_e32 v113, v23, v23
	v_fmac_f32_e32 v113, v22, v22
	v_add_f32_e32 v112, v113, v112
	v_mov_b32_e32 v113, v112
	s_nop 1
	v_permlane16_swap_b32_e32 v112, v113
	v_add_f32_e32 v112, v112, v113
	v_mov_b32_e32 v113, v112
	s_nop 1
	v_permlane32_swap_b32_e32 v112, v113
	s_and_saveexec_b64 s[6:7], s[0:1]
	v_add_f32_e32 v112, v112, v113
	ds_write_b32 v199, v112 offset:16
	s_or_b64 exec, exec, s[6:7]
	v_mul_f32_e32 v112, v13, v13
	v_mul_f32_e32 v113, v15, v15
	v_fmac_f32_e32 v112, v12, v12
	v_fmac_f32_e32 v113, v14, v14
	v_add_f32_e32 v112, v112, v113
	v_mul_f32_e32 v113, v9, v9
	v_fmac_f32_e32 v113, v8, v8
	v_add_f32_e32 v112, v113, v112
	v_mul_f32_e32 v113, v11, v11
	v_fmac_f32_e32 v113, v10, v10
	v_add_f32_e32 v112, v113, v112
	v_mov_b32_e32 v113, v112
	s_nop 1
	v_permlane16_swap_b32_e32 v112, v113
	v_add_f32_e32 v112, v112, v113
	v_mov_b32_e32 v113, v112
	s_nop 1
	v_permlane32_swap_b32_e32 v112, v113
	s_and_saveexec_b64 s[6:7], s[0:1]
	v_add_f32_e32 v112, v112, v113
	ds_write_b32 v200, v112
	s_or_b64 exec, exec, s[6:7]
	v_mul_f32_e32 v112, v5, v5
	v_mul_f32_e32 v113, v7, v7
	v_fmac_f32_e32 v112, v4, v4
	v_fmac_f32_e32 v113, v6, v6
	v_add_f32_e32 v112, v112, v113
	v_mul_f32_e32 v113, v1, v1
	v_fmac_f32_e32 v113, v0, v0
	v_add_f32_e32 v112, v113, v112
	v_mul_f32_e32 v113, v3, v3
	v_fmac_f32_e32 v113, v2, v2
	v_add_f32_e32 v112, v113, v112
	v_mov_b32_e32 v113, v112
	s_nop 1
	v_permlane16_swap_b32_e32 v112, v113
	v_add_f32_e32 v112, v112, v113
	v_mov_b32_e32 v113, v112
	s_nop 1
	v_permlane32_swap_b32_e32 v112, v113
	s_and_saveexec_b64 s[6:7], s[0:1]
	v_add_f32_e32 v112, v112, v113
	ds_write_b32 v200, v112 offset:16
	s_or_b64 exec, exec, s[6:7]
	s_cmp_lt_u32 s8, 8
	s_cselect_b64 s[8:9], -1, 0
	s_and_b64 s[6:7], s[8:9], exec
	s_cselect_b32 s7, s13, s15
	s_cselect_b32 s6, s12, s14
	s_lshl_b32 s25, s52, 2
	s_add_u32 s6, s6, s25
	s_waitcnt lgkmcnt(0)
	s_barrier
	s_addc_u32 s7, s7, 0
	s_lshl_b32 s25, s34, 8
	v_add_u32_e32 v174, s25, v163
	s_andn2_b64 s[6:7], exec, s[22:23]
	s_andn2_b64 vcc, exec, s[22:23]
	v_ashrrev_i32_e32 v175, 31, v174
	s_cbranch_vccnz .LBB0_393
	s_waitcnt vmcnt(4)
	v_xor_b32_e32 v160, 0x80000000, v136
	v_xor_b32_e32 v186, 0x80000000, v137
	v_xor_b32_e32 v187, 0x80000000, v138
	v_xor_b32_e32 v188, 0x80000000, v139
	v_xor_b32_e32 v189, 0x80000000, v140
	v_xor_b32_e32 v203, 0x80000000, v141
	v_xor_b32_e32 v204, 0x80000000, v142
	v_xor_b32_e32 v205, 0x80000000, v143
	v_cndmask_b32_e64 v139, v139, v188, s[2:3]
	v_cndmask_b32_e64 v138, v138, v187, s[2:3]
	v_cndmask_b32_e64 v137, v137, v186, s[2:3]
	v_cndmask_b32_e64 v136, v136, v160, s[2:3]
	v_cndmask_b32_e64 v143, v143, v205, s[2:3]
	v_cndmask_b32_e64 v142, v142, v204, s[2:3]
	v_cndmask_b32_e64 v141, v141, v203, s[2:3]
	v_cndmask_b32_e64 v140, v140, v189, s[2:3]
.LBB0_393:
	ds_read_b128 v[204:207], v192
	s_and_b64 vcc, exec, s[6:7]
	s_waitcnt lgkmcnt(0)
	v_mov_b32_e32 v186, v205
	v_mov_b32_e32 v187, v206
	v_mov_b32_e32 v205, v207
	v_pk_add_f32 v[186:187], v[186:187], v[204:205]
	s_nop 0
	v_add_f32_e32 v160, v186, v187
	v_fmamk_f32 v160, v160, 0x3c000000, v202
	v_rsq_f32_e32 v160, v160
	v_mov_b32_e32 v186, 0x3e0293ee
	v_cndmask_b32_e64 v203, 1.0, v186, s[8:9]
	v_mul_f32_e32 v160, v203, v160
	v_pk_mul_f32 v[186:187], v[144:145], v[160:161] op_sel_hi:[1,0]
	v_pk_mul_f32 v[144:145], v[146:147], v[160:161] op_sel_hi:[1,0]
	v_pk_mul_f32 v[188:189], v[148:149], v[160:161] op_sel_hi:[1,0]
	v_pk_mul_f32 v[146:147], v[150:151], v[160:161] op_sel_hi:[1,0]
	s_cbranch_vccz .Lp1qk_wdone
	s_waitcnt vmcnt(0)
.Lp1qk_wdone:
	v_mov_b32_e32 v112, v232
	v_mov_b32_e32 v113, v233
	v_mov_b32_e32 v114, v234
	v_mov_b32_e32 v115, v235
	v_mov_b32_e32 v116, v236
	v_mov_b32_e32 v117, v237
	v_mov_b32_e32 v118, v238
	v_mov_b32_e32 v119, v239
	v_pk_mul_f32 v[144:145], v[118:119], v[144:145]
	v_pk_mul_f32 v[148:149], v[116:117], v[186:187]
	v_pk_mul_f32 v[146:147], v[114:115], v[146:147]
	v_pk_mul_f32 v[150:151], v[112:113], v[188:189]
	s_cbranch_vccnz .LBB0_395
	v_mov_b32_e32 v160, v148
	v_mov_b32_e32 v186, v148
	v_mov_b32_e32 v188, v150
	v_mov_b32_e32 v204, v150
	v_permlane32_swap_b32_e32 v160, v186
	s_nop 0
	v_permlane32_swap_b32_e32 v188, v204
	v_mov_b32_e32 v187, v149
	v_mov_b32_e32 v189, v149
	v_mov_b32_e32 v205, v151
	v_mov_b32_e32 v206, v151
	v_cndmask_b32_e64 v186, v160, v186, s[2:3]
	v_cndmask_b32_e64 v188, v188, v204, s[2:3]
	v_mov_b32_e32 v160, v144
	v_mov_b32_e32 v204, v144
	v_permlane32_swap_b32_e32 v187, v189
	v_permlane32_swap_b32_e32 v205, v206
	v_permlane32_swap_b32_e32 v160, v204
	v_cndmask_b32_e64 v187, v187, v189, s[2:3]
	v_cndmask_b32_e64 v189, v205, v206, s[2:3]
	v_cndmask_b32_e64 v160, v160, v204, s[2:3]
	v_mov_b32_e32 v204, v146
	v_mov_b32_e32 v205, v146
	s_nop 1
	v_permlane32_swap_b32_e32 v204, v205
	v_cndmask_b32_e64 v205, v204, v205, s[2:3]
	v_mul_f32_e32 v204, v138, v160
	v_mul_f32_e32 v206, v142, v205
	v_mov_b32_e32 v160, v145
	v_mov_b32_e32 v205, v145
	s_nop 1
	v_permlane32_swap_b32_e32 v160, v205
	v_cndmask_b32_e64 v209, v160, v205, s[2:3]
	v_mov_b32_e32 v160, v147
	v_mov_b32_e32 v205, v147
	v_pk_mul_f32 v[148:149], v[132:133], v[148:149]
	s_nop 0
	v_permlane32_swap_b32_e32 v160, v205
	v_cndmask_b32_e64 v211, v160, v205, s[2:3]
	v_mov_b32_e32 v212, v135
	v_mov_b32_e32 v213, v139
	v_mov_b32_e32 v208, v145
	v_pk_fma_f32 v[148:149], v[136:137], v[186:187], v[148:149]
	v_mov_b32_e32 v186, v127
	v_mov_b32_e32 v187, v143
	v_mov_b32_e32 v210, v147
	v_pk_mul_f32 v[208:209], v[212:213], v[208:209]
	v_pk_mul_f32 v[186:187], v[186:187], v[210:211]
	v_pk_mul_f32 v[150:151], v[124:125], v[150:151]
	v_mul_f32_e32 v144, v134, v144
	v_mul_f32_e32 v146, v126, v146
	v_mov_b32_e32 v145, v208
	v_mov_b32_e32 v205, v209
	v_mov_b32_e32 v147, v186
	v_mov_b32_e32 v207, v187
	v_pk_add_f32 v[144:145], v[144:145], v[204:205]
	v_pk_fma_f32 v[150:151], v[140:141], v[188:189], v[150:151]
	v_pk_add_f32 v[146:147], v[146:147], v[206:207]

.LBB0_397:
	v_cvt_pk_bf16_f32 v148, v148, v149
	v_cvt_pk_bf16_f32 v149, v120, v121
	v_or_b32_e32 v120, 16, v163
	v_add_u32_e32 v120, s25, v120
	s_and_b64 vcc, exec, s[6:7]
	v_ashrrev_i32_e32 v121, 31, v120
	v_cvt_pk_bf16_f32 v150, v128, v129
	v_cvt_pk_bf16_f32 v151, v122, v123
	global_store_dwordx4 v[146:147], v[148:151], off offset:256 nt
	s_cbranch_vccnz .LBB0_399
	s_waitcnt vmcnt(2)
	v_mov_b32_e32 v132, v224
	v_mov_b32_e32 v133, v225
	v_mov_b32_e32 v134, v226
	v_mov_b32_e32 v135, v227
	v_mov_b32_e32 v124, v228
	v_mov_b32_e32 v125, v229
	v_mov_b32_e32 v126, v230
	v_mov_b32_e32 v127, v231
	v_cndmask_b32_e64 v136, v216, -v216, s[2:3]
	v_cndmask_b32_e64 v137, v217, -v217, s[2:3]
	v_cndmask_b32_e64 v138, v218, -v218, s[2:3]
	v_cndmask_b32_e64 v139, v219, -v219, s[2:3]
	v_cndmask_b32_e64 v140, v220, -v220, s[2:3]
	v_cndmask_b32_e64 v141, v221, -v221, s[2:3]
	v_cndmask_b32_e64 v142, v222, -v222, s[2:3]
	v_cndmask_b32_e64 v143, v223, -v223, s[2:3]
	global_load_dwordx4 v[216:219], v[240:241], off offset:2048
	global_load_dwordx4 v[220:223], v[240:241], off offset:2064
	global_load_dwordx4 v[228:231], v[242:243], off offset:2064
	global_load_dwordx4 v[224:227], v[242:243], off offset:2048
.LBB0_399:
	v_add_u32_e32 v122, 0, v214
	v_add_u32_e32 v122, 0x20000, v122
	ds_read_b128 v[128:131], v122
	s_and_b64 vcc, exec, s[6:7]
	s_waitcnt lgkmcnt(0)
	v_mov_b32_e32 v122, v129
	v_mov_b32_e32 v123, v130
	v_mov_b32_e32 v129, v131
	v_pk_add_f32 v[122:123], v[122:123], v[128:129]
	s_nop 0
	v_add_f32_e32 v122, v122, v123
	v_fmamk_f32 v122, v122, 0x3c000000, v202
	v_rsq_f32_e32 v122, v122
	s_nop 0
	v_mul_f32_e32 v122, v203, v122
	v_pk_mul_f32 v[128:129], v[104:105], v[122:123] op_sel_hi:[1,0]
	v_pk_mul_f32 v[104:105], v[106:107], v[122:123] op_sel_hi:[1,0]
	v_pk_mul_f32 v[130:131], v[108:109], v[122:123] op_sel_hi:[1,0]
	v_pk_mul_f32 v[106:107], v[110:111], v[122:123] op_sel_hi:[1,0]
	v_pk_mul_f32 v[104:105], v[118:119], v[104:105]
	v_pk_mul_f32 v[108:109], v[116:117], v[128:129]
	v_pk_mul_f32 v[106:107], v[114:115], v[106:107]
	v_pk_mul_f32 v[110:111], v[112:113], v[130:131]
	s_cbranch_vccnz .LBB0_401
	v_mov_b32_e32 v122, v108
	v_mov_b32_e32 v128, v108
	v_mov_b32_e32 v130, v110
	v_mov_b32_e32 v131, v110
	v_permlane32_swap_b32_e32 v122, v128
	s_nop 0
	v_permlane32_swap_b32_e32 v130, v131
	v_mov_b32_e32 v123, v109
	v_mov_b32_e32 v129, v109
	v_mov_b32_e32 v146, v111
	v_mov_b32_e32 v147, v111
	v_cndmask_b32_e64 v122, v122, v128, s[2:3]
	v_cndmask_b32_e64 v128, v130, v131, s[2:3]
	v_mov_b32_e32 v130, v104
	v_mov_b32_e32 v131, v104
	v_permlane32_swap_b32_e32 v123, v129
	v_permlane32_swap_b32_e32 v146, v147
	v_permlane32_swap_b32_e32 v130, v131
	v_cndmask_b32_e64 v123, v123, v129, s[2:3]
	v_cndmask_b32_e64 v129, v146, v147, s[2:3]
	v_cndmask_b32_e64 v130, v130, v131, s[2:3]
	v_mov_b32_e32 v131, v106
	v_mov_b32_e32 v146, v106
	s_nop 1
	v_permlane32_swap_b32_e32 v131, v146
	v_cndmask_b32_e64 v131, v131, v146, s[2:3]
	v_mul_f32_e32 v146, v142, v131
	v_mov_b32_e32 v131, v105
	v_mov_b32_e32 v147, v105
	s_nop 1
	v_permlane32_swap_b32_e32 v131, v147
	v_cndmask_b32_e64 v149, v131, v147, s[2:3]
	v_mov_b32_e32 v131, v107
	v_mov_b32_e32 v147, v107
	v_pk_mul_f32 v[108:109], v[132:133], v[108:109]
	v_permlane32_swap_b32_e32 v131, v147
	v_cndmask_b32_e64 v151, v131, v147, s[2:3]
	v_mov_b32_e32 v174, v135
	v_mov_b32_e32 v175, v139
	v_mov_b32_e32 v148, v105
	v_pk_fma_f32 v[108:109], v[136:137], v[122:123], v[108:109]
	v_mov_b32_e32 v122, v127
	v_mov_b32_e32 v123, v143
	v_mov_b32_e32 v150, v107
	v_pk_mul_f32 v[148:149], v[174:175], v[148:149]
	v_pk_mul_f32 v[122:123], v[122:123], v[150:151]
	v_pk_mul_f32 v[110:111], v[124:125], v[110:111]
	v_mul_f32_e32 v104, v134, v104
	v_mul_f32_e32 v130, v138, v130
	v_mul_f32_e32 v106, v126, v106
	v_mov_b32_e32 v105, v148
	v_mov_b32_e32 v131, v149
	v_mov_b32_e32 v107, v122
	v_mov_b32_e32 v147, v123
	v_pk_add_f32 v[104:105], v[104:105], v[130:131]
	v_pk_fma_f32 v[110:111], v[140:141], v[128:129], v[110:111]
	v_pk_add_f32 v[106:107], v[106:107], v[146:147]
.LBB0_401:
	v_cvt_pk_bf16_f32 v108, v108, v109
	v_cvt_pk_bf16_f32 v109, v104, v105
	v_add_u32_e32 v104, s57, v214
	v_cvt_pk_bf16_f32 v110, v110, v111
	v_cvt_pk_bf16_f32 v111, v106, v107
	ds_read_b128 v[104:107], v104 offset:16
	s_and_b64 vcc, exec, s[6:7]
	s_waitcnt lgkmcnt(0)
	v_mov_b32_e32 v122, v105
	v_mov_b32_e32 v123, v106
	v_mov_b32_e32 v105, v107
	v_pk_add_f32 v[104:105], v[122:123], v[104:105]
	s_nop 0
	v_add_f32_e32 v104, v104, v105
	v_fmamk_f32 v104, v104, 0x3c000000, v202
	v_rsq_f32_e32 v106, v104
	v_lshlrev_b64 v[104:105], 12, v[120:121]
	v_lshl_add_u64 v[104:105], v[144:145], 0, v[104:105]
	global_store_dwordx4 v[104:105], v[108:111], off nt
	s_nop 1
	v_mul_f32_e32 v108, v203, v106
	v_pk_mul_f32 v[106:107], v[96:97], v[108:109] op_sel_hi:[1,0]
	v_pk_mul_f32 v[96:97], v[98:99], v[108:109] op_sel_hi:[1,0]
	v_pk_mul_f32 v[100:101], v[100:101], v[108:109] op_sel_hi:[1,0]
	v_pk_mul_f32 v[98:99], v[102:103], v[108:109] op_sel_hi:[1,0]
	v_pk_mul_f32 v[96:97], v[118:119], v[96:97]
	v_pk_mul_f32 v[106:107], v[116:117], v[106:107]
	v_pk_mul_f32 v[98:99], v[114:115], v[98:99]
	v_pk_mul_f32 v[100:101], v[112:113], v[100:101]
	s_cbranch_vccnz .LBB0_403
	v_mov_b32_e32 v102, v106
	v_mov_b32_e32 v108, v106
	v_mov_b32_e32 v110, v100
	v_mov_b32_e32 v111, v100
	v_permlane32_swap_b32_e32 v102, v108
	s_nop 0
	v_permlane32_swap_b32_e32 v110, v111
	v_mov_b32_e32 v103, v107
	v_mov_b32_e32 v109, v107
	v_mov_b32_e32 v120, v101
	v_mov_b32_e32 v121, v101
	v_cndmask_b32_e64 v102, v102, v108, s[2:3]
	v_cndmask_b32_e64 v108, v110, v111, s[2:3]
	v_mov_b32_e32 v110, v96
	v_mov_b32_e32 v111, v96
	v_permlane32_swap_b32_e32 v103, v109
	v_permlane32_swap_b32_e32 v120, v121
	v_permlane32_swap_b32_e32 v110, v111
	v_cndmask_b32_e64 v103, v103, v109, s[2:3]
	v_cndmask_b32_e64 v109, v120, v121, s[2:3]
	v_cndmask_b32_e64 v110, v110, v111, s[2:3]
	v_mov_b32_e32 v111, v98
	v_mov_b32_e32 v120, v98
	s_nop 1
	v_permlane32_swap_b32_e32 v111, v120
	v_cndmask_b32_e64 v111, v111, v120, s[2:3]
	v_mul_f32_e32 v120, v142, v111
	v_mov_b32_e32 v111, v97
	v_mov_b32_e32 v121, v97
	s_nop 1
	v_permlane32_swap_b32_e32 v111, v121
	v_cndmask_b32_e64 v123, v111, v121, s[2:3]
	v_mov_b32_e32 v111, v99
	v_mov_b32_e32 v121, v99
	v_pk_mul_f32 v[106:107], v[132:133], v[106:107]
	v_permlane32_swap_b32_e32 v111, v121
	v_cndmask_b32_e64 v129, v111, v121, s[2:3]
	v_mov_b32_e32 v130, v135
	v_mov_b32_e32 v131, v139
	v_mov_b32_e32 v122, v97
	v_pk_fma_f32 v[106:107], v[136:137], v[102:103], v[106:107]
	v_mov_b32_e32 v102, v127
	v_mov_b32_e32 v103, v143
	v_mov_b32_e32 v128, v99
	v_pk_mul_f32 v[122:123], v[130:131], v[122:123]
	v_pk_mul_f32 v[102:103], v[102:103], v[128:129]
	v_pk_mul_f32 v[100:101], v[124:125], v[100:101]
	v_mul_f32_e32 v96, v134, v96
	v_mul_f32_e32 v110, v138, v110
	v_mul_f32_e32 v98, v126, v98
	v_mov_b32_e32 v97, v122
	v_mov_b32_e32 v111, v123
	v_mov_b32_e32 v99, v102
	v_mov_b32_e32 v121, v103
	v_pk_add_f32 v[96:97], v[96:97], v[110:111]
	v_pk_fma_f32 v[100:101], v[140:141], v[108:109], v[100:101]
	v_pk_add_f32 v[98:99], v[98:99], v[120:121]
.LBB0_403:
	v_cvt_pk_bf16_f32 v106, v106, v107
	v_cvt_pk_bf16_f32 v107, v96, v97
	v_or_b32_e32 v96, 32, v163
	v_add_u32_e32 v96, s25, v96
	s_and_b64 vcc, exec, s[6:7]
	v_ashrrev_i32_e32 v97, 31, v96
	v_cvt_pk_bf16_f32 v108, v100, v101
	v_cvt_pk_bf16_f32 v109, v98, v99
	global_store_dwordx4 v[104:105], v[106:109], off offset:256 nt
	s_cbranch_vccnz .LBB0_405
	s_waitcnt vmcnt(2)
	v_mov_b32_e32 v132, v224
	v_mov_b32_e32 v133, v225
	v_mov_b32_e32 v134, v226
	v_mov_b32_e32 v135, v227
	v_mov_b32_e32 v124, v228
	v_mov_b32_e32 v125, v229
	v_mov_b32_e32 v126, v230
	v_mov_b32_e32 v127, v231
	v_cndmask_b32_e64 v136, v216, -v216, s[2:3]
	v_cndmask_b32_e64 v137, v217, -v217, s[2:3]
	v_cndmask_b32_e64 v138, v218, -v218, s[2:3]
	v_cndmask_b32_e64 v139, v219, -v219, s[2:3]
	v_cndmask_b32_e64 v140, v220, -v220, s[2:3]
	v_cndmask_b32_e64 v141, v221, -v221, s[2:3]
	v_cndmask_b32_e64 v142, v222, -v222, s[2:3]
	v_cndmask_b32_e64 v143, v223, -v223, s[2:3]
	global_load_dwordx4 v[216:219], v[240:241], off offset:3072
	global_load_dwordx4 v[220:223], v[240:241], off offset:3088
	global_load_dwordx4 v[228:231], v[242:243], off offset:3088
	global_load_dwordx4 v[224:227], v[242:243], off offset:3072
.LBB0_405:
	v_add_u32_e32 v98, 0, v215
	v_add_u32_e32 v98, 0x20000, v98
	ds_read_b128 v[98:101], v98
	s_and_b64 vcc, exec, s[6:7]
	s_waitcnt lgkmcnt(0)
	v_mov_b32_e32 v102, v99
	v_mov_b32_e32 v103, v100
	v_mov_b32_e32 v99, v101
	v_pk_add_f32 v[98:99], v[102:103], v[98:99]
	s_nop 0
	v_add_f32_e32 v98, v98, v99
	v_fmamk_f32 v98, v98, 0x3c000000, v202
	v_rsq_f32_e32 v98, v98
	s_nop 0
	v_mul_f32_e32 v98, v203, v98
	v_pk_mul_f32 v[100:101], v[88:89], v[98:99] op_sel_hi:[1,0]
	v_pk_mul_f32 v[88:89], v[90:91], v[98:99] op_sel_hi:[1,0]
	v_pk_mul_f32 v[102:103], v[92:93], v[98:99] op_sel_hi:[1,0]
	v_pk_mul_f32 v[90:91], v[94:95], v[98:99] op_sel_hi:[1,0]
	v_pk_mul_f32 v[88:89], v[118:119], v[88:89]
	v_pk_mul_f32 v[92:93], v[116:117], v[100:101]
	v_pk_mul_f32 v[90:91], v[114:115], v[90:91]
	v_pk_mul_f32 v[94:95], v[112:113], v[102:103]
	s_cbranch_vccnz .LBB0_407
	v_mov_b32_e32 v98, v92
	v_mov_b32_e32 v100, v92
	v_mov_b32_e32 v102, v94
	v_mov_b32_e32 v103, v94
	v_permlane32_swap_b32_e32 v98, v100
	s_nop 0
	v_permlane32_swap_b32_e32 v102, v103
	v_mov_b32_e32 v99, v93
	v_mov_b32_e32 v101, v93
	v_mov_b32_e32 v104, v95
	v_mov_b32_e32 v105, v95
	v_cndmask_b32_e64 v98, v98, v100, s[2:3]
	v_cndmask_b32_e64 v100, v102, v103, s[2:3]
	v_mov_b32_e32 v102, v88
	v_mov_b32_e32 v103, v88
	v_permlane32_swap_b32_e32 v99, v101
	v_permlane32_swap_b32_e32 v104, v105
	v_permlane32_swap_b32_e32 v102, v103
	v_cndmask_b32_e64 v99, v99, v101, s[2:3]
	v_cndmask_b32_e64 v101, v104, v105, s[2:3]
	v_cndmask_b32_e64 v102, v102, v103, s[2:3]
	v_mov_b32_e32 v103, v90
	v_mov_b32_e32 v104, v90
	s_nop 1
	v_permlane32_swap_b32_e32 v103, v104
	v_cndmask_b32_e64 v103, v103, v104, s[2:3]
	v_mul_f32_e32 v104, v142, v103
	v_mov_b32_e32 v103, v89
	v_mov_b32_e32 v105, v89
	s_nop 1
	v_permlane32_swap_b32_e32 v103, v105
	v_cndmask_b32_e64 v107, v103, v105, s[2:3]
	v_mov_b32_e32 v103, v91
	v_mov_b32_e32 v105, v91
	v_pk_mul_f32 v[92:93], v[132:133], v[92:93]
	v_permlane32_swap_b32_e32 v103, v105
	v_cndmask_b32_e64 v109, v103, v105, s[2:3]
	v_mov_b32_e32 v110, v135
	v_mov_b32_e32 v111, v139
	v_mov_b32_e32 v106, v89
	v_pk_fma_f32 v[92:93], v[136:137], v[98:99], v[92:93]
	v_mov_b32_e32 v98, v127
	v_mov_b32_e32 v99, v143
	v_mov_b32_e32 v108, v91
	v_pk_mul_f32 v[106:107], v[110:111], v[106:107]
	v_pk_mul_f32 v[98:99], v[98:99], v[108:109]
	v_pk_mul_f32 v[94:95], v[124:125], v[94:95]
	v_mul_f32_e32 v88, v134, v88
	v_mul_f32_e32 v102, v138, v102
	v_mul_f32_e32 v90, v126, v90
	v_mov_b32_e32 v89, v106
	v_mov_b32_e32 v103, v107
	v_mov_b32_e32 v91, v98
	v_mov_b32_e32 v105, v99
	v_pk_add_f32 v[88:89], v[88:89], v[102:103]
	v_pk_fma_f32 v[94:95], v[140:141], v[100:101], v[94:95]
	v_pk_add_f32 v[90:91], v[90:91], v[104:105]
.LBB0_407:
	v_cvt_pk_bf16_f32 v92, v92, v93
	v_cvt_pk_bf16_f32 v93, v88, v89
	v_add_u32_e32 v88, s57, v215
	v_cvt_pk_bf16_f32 v94, v94, v95
	v_cvt_pk_bf16_f32 v95, v90, v91
	ds_read_b128 v[88:91], v88 offset:16
	s_and_b64 vcc, exec, s[6:7]
	s_waitcnt lgkmcnt(0)
	v_mov_b32_e32 v98, v89
	v_mov_b32_e32 v99, v90
	v_mov_b32_e32 v89, v91
	v_pk_add_f32 v[88:89], v[98:99], v[88:89]
	s_nop 0
	v_add_f32_e32 v88, v88, v89
	v_fmamk_f32 v88, v88, 0x3c000000, v202
	v_rsq_f32_e32 v90, v88
	v_lshlrev_b64 v[88:89], 12, v[96:97]
	v_lshl_add_u64 v[88:89], v[144:145], 0, v[88:89]
	global_store_dwordx4 v[88:89], v[92:95], off nt
	s_nop 1
	v_mul_f32_e32 v92, v203, v90
	v_pk_mul_f32 v[90:91], v[80:81], v[92:93] op_sel_hi:[1,0]
	v_pk_mul_f32 v[80:81], v[82:83], v[92:93] op_sel_hi:[1,0]
	v_pk_mul_f32 v[84:85], v[84:85], v[92:93] op_sel_hi:[1,0]
	v_pk_mul_f32 v[82:83], v[86:87], v[92:93] op_sel_hi:[1,0]
	v_pk_mul_f32 v[80:81], v[118:119], v[80:81]
	v_pk_mul_f32 v[90:91], v[116:117], v[90:91]
	v_pk_mul_f32 v[82:83], v[114:115], v[82:83]
	v_pk_mul_f32 v[84:85], v[112:113], v[84:85]
	s_cbranch_vccnz .LBB0_409
	v_mov_b32_e32 v86, v90
	v_mov_b32_e32 v92, v90
	v_mov_b32_e32 v94, v84
	v_mov_b32_e32 v95, v84
	v_permlane32_swap_b32_e32 v86, v92
	s_nop 0
	v_permlane32_swap_b32_e32 v94, v95
	v_mov_b32_e32 v87, v91
	v_mov_b32_e32 v93, v91
	v_mov_b32_e32 v96, v85
	v_mov_b32_e32 v97, v85
	v_cndmask_b32_e64 v86, v86, v92, s[2:3]
	v_cndmask_b32_e64 v92, v94, v95, s[2:3]
	v_mov_b32_e32 v94, v80
	v_mov_b32_e32 v95, v80
	v_permlane32_swap_b32_e32 v87, v93
	v_permlane32_swap_b32_e32 v96, v97
	v_permlane32_swap_b32_e32 v94, v95
	v_cndmask_b32_e64 v87, v87, v93, s[2:3]
	v_cndmask_b32_e64 v93, v96, v97, s[2:3]
	v_cndmask_b32_e64 v94, v94, v95, s[2:3]
	v_mov_b32_e32 v95, v82
	v_mov_b32_e32 v96, v82
	s_nop 1
	v_permlane32_swap_b32_e32 v95, v96
	v_cndmask_b32_e64 v95, v95, v96, s[2:3]
	v_mul_f32_e32 v96, v142, v95
	v_mov_b32_e32 v95, v81
	v_mov_b32_e32 v97, v81
	s_nop 1
	v_permlane32_swap_b32_e32 v95, v97
	v_cndmask_b32_e64 v99, v95, v97, s[2:3]
	v_mov_b32_e32 v95, v83
	v_mov_b32_e32 v97, v83
	v_pk_mul_f32 v[90:91], v[132:133], v[90:91]
	v_permlane32_swap_b32_e32 v95, v97
	v_cndmask_b32_e64 v101, v95, v97, s[2:3]
	v_mov_b32_e32 v102, v135
	v_mov_b32_e32 v103, v139
	v_mov_b32_e32 v98, v81
	v_pk_fma_f32 v[90:91], v[136:137], v[86:87], v[90:91]
	v_mov_b32_e32 v86, v127
	v_mov_b32_e32 v87, v143
	v_mov_b32_e32 v100, v83
	v_pk_mul_f32 v[98:99], v[102:103], v[98:99]
	v_pk_mul_f32 v[86:87], v[86:87], v[100:101]
	v_pk_mul_f32 v[84:85], v[124:125], v[84:85]
	v_mul_f32_e32 v80, v134, v80
	v_mul_f32_e32 v94, v138, v94
	v_mul_f32_e32 v82, v126, v82
	v_mov_b32_e32 v81, v98
	v_mov_b32_e32 v95, v99
	v_mov_b32_e32 v83, v86
	v_mov_b32_e32 v97, v87
	v_pk_add_f32 v[80:81], v[80:81], v[94:95]
	v_pk_fma_f32 v[84:85], v[140:141], v[92:93], v[84:85]
	v_pk_add_f32 v[82:83], v[82:83], v[96:97]
.LBB0_409:
	v_cvt_pk_bf16_f32 v90, v90, v91
	v_cvt_pk_bf16_f32 v91, v80, v81
	v_or_b32_e32 v80, 48, v163
	v_add_u32_e32 v80, s25, v80
	s_and_b64 vcc, exec, s[6:7]
	v_ashrrev_i32_e32 v81, 31, v80
	v_cvt_pk_bf16_f32 v92, v84, v85
	v_cvt_pk_bf16_f32 v93, v82, v83
	global_store_dwordx4 v[88:89], v[90:93], off offset:256 nt
	s_cbranch_vccnz .LBB0_411
	s_waitcnt vmcnt(2)
	v_mov_b32_e32 v132, v224
	v_mov_b32_e32 v133, v225
	v_mov_b32_e32 v134, v226
	v_mov_b32_e32 v135, v227
	v_mov_b32_e32 v124, v228
	v_mov_b32_e32 v125, v229
	v_mov_b32_e32 v126, v230
	v_mov_b32_e32 v127, v231
	v_cndmask_b32_e64 v136, v216, -v216, s[2:3]
	v_cndmask_b32_e64 v137, v217, -v217, s[2:3]
	v_cndmask_b32_e64 v138, v218, -v218, s[2:3]
	v_cndmask_b32_e64 v139, v219, -v219, s[2:3]
	v_cndmask_b32_e64 v140, v220, -v220, s[2:3]
	v_cndmask_b32_e64 v141, v221, -v221, s[2:3]
	v_cndmask_b32_e64 v142, v222, -v222, s[2:3]
	v_cndmask_b32_e64 v143, v223, -v223, s[2:3]
	v_lshl_add_u64 v[240:241], v[240:241], 0, s[38:39]
	v_lshl_add_u64 v[242:243], v[242:243], 0, s[38:39]
	global_load_dwordx4 v[216:219], v[240:241], off
	global_load_dwordx4 v[220:223], v[240:241], off offset:16
	global_load_dwordx4 v[228:231], v[242:243], off offset:16
	global_load_dwordx4 v[224:227], v[242:243], off
.LBB0_411:
	v_add_u32_e32 v82, 0, v185
	v_add_u32_e32 v82, 0x20000, v82
	ds_read_b128 v[82:85], v82
	s_and_b64 vcc, exec, s[6:7]
	s_waitcnt lgkmcnt(0)
	v_mov_b32_e32 v86, v83
	v_mov_b32_e32 v87, v84
	v_mov_b32_e32 v83, v85
	v_pk_add_f32 v[82:83], v[86:87], v[82:83]
	s_nop 0
	v_add_f32_e32 v82, v82, v83
	v_fmamk_f32 v82, v82, 0x3c000000, v202
	v_rsq_f32_e32 v82, v82
	s_nop 0
	v_mul_f32_e32 v82, v203, v82
	v_pk_mul_f32 v[84:85], v[72:73], v[82:83] op_sel_hi:[1,0]
	v_pk_mul_f32 v[72:73], v[74:75], v[82:83] op_sel_hi:[1,0]
	v_pk_mul_f32 v[86:87], v[76:77], v[82:83] op_sel_hi:[1,0]
	v_pk_mul_f32 v[74:75], v[78:79], v[82:83] op_sel_hi:[1,0]
	v_pk_mul_f32 v[72:73], v[118:119], v[72:73]
	v_pk_mul_f32 v[76:77], v[116:117], v[84:85]
	v_pk_mul_f32 v[74:75], v[114:115], v[74:75]
	v_pk_mul_f32 v[78:79], v[112:113], v[86:87]
	s_cbranch_vccnz .LBB0_413
	v_mov_b32_e32 v82, v76
	v_mov_b32_e32 v84, v76
	v_mov_b32_e32 v86, v78
	v_mov_b32_e32 v87, v78
	v_permlane32_swap_b32_e32 v82, v84
	s_nop 0
	v_permlane32_swap_b32_e32 v86, v87
	v_mov_b32_e32 v83, v77
	v_mov_b32_e32 v85, v77
	v_mov_b32_e32 v88, v79
	v_mov_b32_e32 v89, v79
	v_cndmask_b32_e64 v82, v82, v84, s[2:3]
	v_cndmask_b32_e64 v84, v86, v87, s[2:3]
	v_mov_b32_e32 v86, v72
	v_mov_b32_e32 v87, v72
	v_permlane32_swap_b32_e32 v83, v85
	v_permlane32_swap_b32_e32 v88, v89
	v_permlane32_swap_b32_e32 v86, v87
	v_cndmask_b32_e64 v83, v83, v85, s[2:3]
	v_cndmask_b32_e64 v85, v88, v89, s[2:3]
	v_cndmask_b32_e64 v86, v86, v87, s[2:3]
	v_mov_b32_e32 v87, v74
	v_mov_b32_e32 v88, v74
	s_nop 1
	v_permlane32_swap_b32_e32 v87, v88
	v_cndmask_b32_e64 v87, v87, v88, s[2:3]
	v_mul_f32_e32 v88, v142, v87
	v_mov_b32_e32 v87, v73
	v_mov_b32_e32 v89, v73
	s_nop 1
	v_permlane32_swap_b32_e32 v87, v89
	v_cndmask_b32_e64 v91, v87, v89, s[2:3]
	v_mov_b32_e32 v87, v75
	v_mov_b32_e32 v89, v75
	v_pk_mul_f32 v[76:77], v[132:133], v[76:77]
	v_permlane32_swap_b32_e32 v87, v89
	v_cndmask_b32_e64 v93, v87, v89, s[2:3]
	v_mov_b32_e32 v94, v135
	v_mov_b32_e32 v95, v139
	v_mov_b32_e32 v90, v73
	v_pk_fma_f32 v[76:77], v[136:137], v[82:83], v[76:77]
	v_mov_b32_e32 v82, v127
	v_mov_b32_e32 v83, v143
	v_mov_b32_e32 v92, v75
	v_pk_mul_f32 v[90:91], v[94:95], v[90:91]
	v_pk_mul_f32 v[82:83], v[82:83], v[92:93]
	v_pk_mul_f32 v[78:79], v[124:125], v[78:79]
	v_mul_f32_e32 v72, v134, v72
	v_mul_f32_e32 v86, v138, v86
	v_mul_f32_e32 v74, v126, v74
	v_mov_b32_e32 v73, v90
	v_mov_b32_e32 v87, v91
	v_mov_b32_e32 v75, v82
	v_mov_b32_e32 v89, v83
	v_pk_add_f32 v[72:73], v[72:73], v[86:87]
	v_pk_fma_f32 v[78:79], v[140:141], v[84:85], v[78:79]
	v_pk_add_f32 v[74:75], v[74:75], v[88:89]
.LBB0_413:
	v_cvt_pk_bf16_f32 v76, v76, v77
	v_cvt_pk_bf16_f32 v77, v72, v73
	v_add_u32_e32 v72, s57, v185
	v_cvt_pk_bf16_f32 v78, v78, v79
	v_cvt_pk_bf16_f32 v79, v74, v75
	ds_read_b128 v[72:75], v72 offset:16
	s_and_b64 vcc, exec, s[6:7]
	s_waitcnt lgkmcnt(0)
	v_mov_b32_e32 v82, v73
	v_mov_b32_e32 v83, v74
	v_mov_b32_e32 v73, v75
	v_pk_add_f32 v[72:73], v[82:83], v[72:73]
	s_nop 0
	v_add_f32_e32 v72, v72, v73
	v_fmamk_f32 v72, v72, 0x3c000000, v202
	v_rsq_f32_e32 v74, v72
	v_lshlrev_b64 v[72:73], 12, v[80:81]
	v_lshl_add_u64 v[72:73], v[144:145], 0, v[72:73]
	global_store_dwordx4 v[72:73], v[76:79], off nt
	s_nop 1
	v_mul_f32_e32 v76, v203, v74
	v_pk_mul_f32 v[74:75], v[64:65], v[76:77] op_sel_hi:[1,0]
	v_pk_mul_f32 v[64:65], v[66:67], v[76:77] op_sel_hi:[1,0]
	v_pk_mul_f32 v[68:69], v[68:69], v[76:77] op_sel_hi:[1,0]
	v_pk_mul_f32 v[66:67], v[70:71], v[76:77] op_sel_hi:[1,0]
	v_pk_mul_f32 v[64:65], v[118:119], v[64:65]
	v_pk_mul_f32 v[74:75], v[116:117], v[74:75]
	v_pk_mul_f32 v[66:67], v[114:115], v[66:67]
	v_pk_mul_f32 v[68:69], v[112:113], v[68:69]
	s_cbranch_vccnz .LBB0_415
	v_mov_b32_e32 v70, v74
	v_mov_b32_e32 v76, v74
	v_mov_b32_e32 v78, v68
	v_mov_b32_e32 v79, v68
	v_permlane32_swap_b32_e32 v70, v76
	s_nop 0
	v_permlane32_swap_b32_e32 v78, v79
	v_mov_b32_e32 v71, v75
	v_mov_b32_e32 v77, v75
	v_mov_b32_e32 v80, v69
	v_mov_b32_e32 v81, v69
	v_cndmask_b32_e64 v70, v70, v76, s[2:3]
	v_cndmask_b32_e64 v76, v78, v79, s[2:3]
	v_mov_b32_e32 v78, v64
	v_mov_b32_e32 v79, v64
	v_permlane32_swap_b32_e32 v71, v77
	v_permlane32_swap_b32_e32 v80, v81
	v_permlane32_swap_b32_e32 v78, v79
	v_cndmask_b32_e64 v71, v71, v77, s[2:3]
	v_cndmask_b32_e64 v77, v80, v81, s[2:3]
	v_cndmask_b32_e64 v78, v78, v79, s[2:3]
	v_mov_b32_e32 v79, v66
	v_mov_b32_e32 v80, v66
	s_nop 1
	v_permlane32_swap_b32_e32 v79, v80
	v_cndmask_b32_e64 v79, v79, v80, s[2:3]
	v_mul_f32_e32 v80, v142, v79
	v_mov_b32_e32 v79, v65
	v_mov_b32_e32 v81, v65
	s_nop 1
	v_permlane32_swap_b32_e32 v79, v81
	v_cndmask_b32_e64 v83, v79, v81, s[2:3]
	v_mov_b32_e32 v79, v67
	v_mov_b32_e32 v81, v67
	v_pk_mul_f32 v[74:75], v[132:133], v[74:75]
	v_permlane32_swap_b32_e32 v79, v81
	v_cndmask_b32_e64 v85, v79, v81, s[2:3]
	v_mov_b32_e32 v86, v135
	v_mov_b32_e32 v87, v139
	v_mov_b32_e32 v82, v65
	v_pk_fma_f32 v[74:75], v[136:137], v[70:71], v[74:75]
	v_mov_b32_e32 v70, v127
	v_mov_b32_e32 v71, v143
	v_mov_b32_e32 v84, v67
	v_pk_mul_f32 v[82:83], v[86:87], v[82:83]
	v_pk_mul_f32 v[70:71], v[70:71], v[84:85]
	v_pk_mul_f32 v[68:69], v[124:125], v[68:69]
	v_mul_f32_e32 v64, v134, v64
	v_mul_f32_e32 v78, v138, v78
	v_mul_f32_e32 v66, v126, v66
	v_mov_b32_e32 v65, v82
	v_mov_b32_e32 v79, v83
	v_mov_b32_e32 v67, v70
	v_mov_b32_e32 v81, v71
	v_pk_add_f32 v[64:65], v[64:65], v[78:79]
	v_pk_fma_f32 v[68:69], v[140:141], v[76:77], v[68:69]
	v_pk_add_f32 v[66:67], v[66:67], v[80:81]
.LBB0_415:
	v_cvt_pk_bf16_f32 v74, v74, v75
	v_cvt_pk_bf16_f32 v75, v64, v65
	v_add_u32_e32 v64, s25, v181
	s_and_b64 vcc, exec, s[6:7]
	v_ashrrev_i32_e32 v65, 31, v64
	v_cvt_pk_bf16_f32 v76, v68, v69
	v_cvt_pk_bf16_f32 v77, v66, v67
	global_store_dwordx4 v[72:73], v[74:77], off offset:256 nt
	s_cbranch_vccnz .LBB0_417
	s_waitcnt vmcnt(2)
	v_mov_b32_e32 v132, v224
	v_mov_b32_e32 v133, v225
	v_mov_b32_e32 v134, v226
	v_mov_b32_e32 v135, v227
	v_mov_b32_e32 v124, v228
	v_mov_b32_e32 v125, v229
	v_mov_b32_e32 v126, v230
	v_mov_b32_e32 v127, v231
	v_cndmask_b32_e64 v136, v216, -v216, s[2:3]
	v_cndmask_b32_e64 v137, v217, -v217, s[2:3]
	v_cndmask_b32_e64 v138, v218, -v218, s[2:3]
	v_cndmask_b32_e64 v139, v219, -v219, s[2:3]
	v_cndmask_b32_e64 v140, v220, -v220, s[2:3]
	v_cndmask_b32_e64 v141, v221, -v221, s[2:3]
	v_cndmask_b32_e64 v142, v222, -v222, s[2:3]
	v_cndmask_b32_e64 v143, v223, -v223, s[2:3]
	global_load_dwordx4 v[216:219], v[240:241], off offset:1024
	global_load_dwordx4 v[220:223], v[240:241], off offset:1040
	global_load_dwordx4 v[228:231], v[242:243], off offset:1040
	global_load_dwordx4 v[224:227], v[242:243], off offset:1024
.LBB0_417:
	v_add_u32_e32 v66, 0, v190
	v_add_u32_e32 v66, 0x20000, v66
	ds_read_b128 v[66:69], v66
	s_and_b64 vcc, exec, s[6:7]
	s_waitcnt lgkmcnt(0)
	v_mov_b32_e32 v70, v67
	v_mov_b32_e32 v71, v68
	v_mov_b32_e32 v67, v69
	v_pk_add_f32 v[66:67], v[70:71], v[66:67]
	s_nop 0
	v_add_f32_e32 v66, v66, v67
	v_fmamk_f32 v66, v66, 0x3c000000, v202
	v_rsq_f32_e32 v66, v66
	s_nop 0
	v_mul_f32_e32 v66, v203, v66
	v_pk_mul_f32 v[68:69], v[56:57], v[66:67] op_sel_hi:[1,0]
	v_pk_mul_f32 v[56:57], v[58:59], v[66:67] op_sel_hi:[1,0]
	v_pk_mul_f32 v[70:71], v[60:61], v[66:67] op_sel_hi:[1,0]
	v_pk_mul_f32 v[58:59], v[62:63], v[66:67] op_sel_hi:[1,0]
	v_pk_mul_f32 v[56:57], v[118:119], v[56:57]
	v_pk_mul_f32 v[60:61], v[116:117], v[68:69]
	v_pk_mul_f32 v[58:59], v[114:115], v[58:59]
	v_pk_mul_f32 v[62:63], v[112:113], v[70:71]
	s_cbranch_vccnz .LBB0_419
	v_mov_b32_e32 v66, v60
	v_mov_b32_e32 v68, v60
	v_mov_b32_e32 v70, v62
	v_mov_b32_e32 v71, v62
	v_permlane32_swap_b32_e32 v66, v68
	s_nop 0
	v_permlane32_swap_b32_e32 v70, v71
	v_mov_b32_e32 v67, v61
	v_mov_b32_e32 v69, v61
	v_mov_b32_e32 v72, v63
	v_mov_b32_e32 v73, v63
	v_cndmask_b32_e64 v66, v66, v68, s[2:3]
	v_cndmask_b32_e64 v68, v70, v71, s[2:3]
	v_mov_b32_e32 v70, v56
	v_mov_b32_e32 v71, v56
	v_permlane32_swap_b32_e32 v67, v69
	v_permlane32_swap_b32_e32 v72, v73
	v_permlane32_swap_b32_e32 v70, v71
	v_cndmask_b32_e64 v67, v67, v69, s[2:3]
	v_cndmask_b32_e64 v69, v72, v73, s[2:3]
	v_cndmask_b32_e64 v70, v70, v71, s[2:3]
	v_mov_b32_e32 v71, v58
	v_mov_b32_e32 v72, v58
	s_nop 1
	v_permlane32_swap_b32_e32 v71, v72
	v_cndmask_b32_e64 v71, v71, v72, s[2:3]
	v_mul_f32_e32 v72, v142, v71
	v_mov_b32_e32 v71, v57
	v_mov_b32_e32 v73, v57
	s_nop 1
	v_permlane32_swap_b32_e32 v71, v73
	v_cndmask_b32_e64 v75, v71, v73, s[2:3]
	v_mov_b32_e32 v71, v59
	v_mov_b32_e32 v73, v59
	v_pk_mul_f32 v[60:61], v[132:133], v[60:61]
	v_permlane32_swap_b32_e32 v71, v73
	v_cndmask_b32_e64 v77, v71, v73, s[2:3]
	v_mov_b32_e32 v78, v135
	v_mov_b32_e32 v79, v139
	v_mov_b32_e32 v74, v57
	v_pk_fma_f32 v[60:61], v[136:137], v[66:67], v[60:61]
	v_mov_b32_e32 v66, v127
	v_mov_b32_e32 v67, v143
	v_mov_b32_e32 v76, v59
	v_pk_mul_f32 v[74:75], v[78:79], v[74:75]
	v_pk_mul_f32 v[66:67], v[66:67], v[76:77]
	v_pk_mul_f32 v[62:63], v[124:125], v[62:63]
	v_mul_f32_e32 v56, v134, v56
	v_mul_f32_e32 v70, v138, v70
	v_mul_f32_e32 v58, v126, v58
	v_mov_b32_e32 v57, v74
	v_mov_b32_e32 v71, v75
	v_mov_b32_e32 v59, v66
	v_mov_b32_e32 v73, v67
	v_pk_add_f32 v[56:57], v[56:57], v[70:71]
	v_pk_fma_f32 v[62:63], v[140:141], v[68:69], v[62:63]
	v_pk_add_f32 v[58:59], v[58:59], v[72:73]
.LBB0_419:
	v_cvt_pk_bf16_f32 v60, v60, v61
	v_cvt_pk_bf16_f32 v61, v56, v57
	v_add_u32_e32 v56, s57, v190
	v_cvt_pk_bf16_f32 v62, v62, v63
	v_cvt_pk_bf16_f32 v63, v58, v59
	ds_read_b128 v[56:59], v56 offset:16
	s_and_b64 vcc, exec, s[6:7]
	s_waitcnt lgkmcnt(0)
	v_mov_b32_e32 v66, v57
	v_mov_b32_e32 v67, v58
	v_mov_b32_e32 v57, v59
	v_pk_add_f32 v[56:57], v[66:67], v[56:57]
	s_nop 0
	v_add_f32_e32 v56, v56, v57
	v_fmamk_f32 v56, v56, 0x3c000000, v202
	v_rsq_f32_e32 v58, v56
	v_lshlrev_b64 v[56:57], 12, v[64:65]
	v_lshl_add_u64 v[56:57], v[144:145], 0, v[56:57]
	global_store_dwordx4 v[56:57], v[60:63], off nt
	s_nop 1
	v_mul_f32_e32 v60, v203, v58
	v_pk_mul_f32 v[58:59], v[48:49], v[60:61] op_sel_hi:[1,0]
	v_pk_mul_f32 v[48:49], v[50:51], v[60:61] op_sel_hi:[1,0]
	v_pk_mul_f32 v[52:53], v[52:53], v[60:61] op_sel_hi:[1,0]
	v_pk_mul_f32 v[50:51], v[54:55], v[60:61] op_sel_hi:[1,0]
	v_pk_mul_f32 v[48:49], v[118:119], v[48:49]
	v_pk_mul_f32 v[58:59], v[116:117], v[58:59]
	v_pk_mul_f32 v[50:51], v[114:115], v[50:51]
	v_pk_mul_f32 v[52:53], v[112:113], v[52:53]
	s_cbranch_vccnz .LBB0_421
	v_mov_b32_e32 v54, v58
	v_mov_b32_e32 v60, v58
	v_mov_b32_e32 v62, v52
	v_mov_b32_e32 v63, v52
	v_permlane32_swap_b32_e32 v54, v60
	s_nop 0
	v_permlane32_swap_b32_e32 v62, v63
	v_mov_b32_e32 v55, v59
	v_mov_b32_e32 v61, v59
	v_mov_b32_e32 v64, v53
	v_mov_b32_e32 v65, v53
	v_cndmask_b32_e64 v54, v54, v60, s[2:3]
	v_cndmask_b32_e64 v60, v62, v63, s[2:3]
	v_mov_b32_e32 v62, v48
	v_mov_b32_e32 v63, v48
	v_permlane32_swap_b32_e32 v55, v61
	v_permlane32_swap_b32_e32 v64, v65
	v_permlane32_swap_b32_e32 v62, v63
	v_cndmask_b32_e64 v55, v55, v61, s[2:3]
	v_cndmask_b32_e64 v61, v64, v65, s[2:3]
	v_cndmask_b32_e64 v62, v62, v63, s[2:3]
	v_mov_b32_e32 v63, v50
	v_mov_b32_e32 v64, v50
	s_nop 1
	v_permlane32_swap_b32_e32 v63, v64
	v_cndmask_b32_e64 v63, v63, v64, s[2:3]
	v_mul_f32_e32 v64, v142, v63
	v_mov_b32_e32 v63, v49
	v_mov_b32_e32 v65, v49
	s_nop 1
	v_permlane32_swap_b32_e32 v63, v65
	v_cndmask_b32_e64 v67, v63, v65, s[2:3]
	v_mov_b32_e32 v63, v51
	v_mov_b32_e32 v65, v51
	v_pk_mul_f32 v[58:59], v[132:133], v[58:59]
	v_permlane32_swap_b32_e32 v63, v65
	v_cndmask_b32_e64 v69, v63, v65, s[2:3]
	v_mov_b32_e32 v70, v135
	v_mov_b32_e32 v71, v139
	v_mov_b32_e32 v66, v49
	v_pk_fma_f32 v[58:59], v[136:137], v[54:55], v[58:59]
	v_mov_b32_e32 v54, v127
	v_mov_b32_e32 v55, v143
	v_mov_b32_e32 v68, v51
	v_pk_mul_f32 v[66:67], v[70:71], v[66:67]
	v_pk_mul_f32 v[54:55], v[54:55], v[68:69]
	v_pk_mul_f32 v[52:53], v[124:125], v[52:53]
	v_mul_f32_e32 v48, v134, v48
	v_mul_f32_e32 v62, v138, v62
	v_mul_f32_e32 v50, v126, v50
	v_mov_b32_e32 v49, v66
	v_mov_b32_e32 v63, v67
	v_mov_b32_e32 v51, v54
	v_mov_b32_e32 v65, v55
	v_pk_add_f32 v[48:49], v[48:49], v[62:63]
	v_pk_fma_f32 v[52:53], v[140:141], v[60:61], v[52:53]
	v_pk_add_f32 v[50:51], v[50:51], v[64:65]
.LBB0_421:
	v_cvt_pk_bf16_f32 v58, v58, v59
	v_cvt_pk_bf16_f32 v59, v48, v49
	v_add_u32_e32 v48, s25, v182
	s_and_b64 vcc, exec, s[6:7]
	v_ashrrev_i32_e32 v49, 31, v48
	v_cvt_pk_bf16_f32 v60, v52, v53
	v_cvt_pk_bf16_f32 v61, v50, v51
	global_store_dwordx4 v[56:57], v[58:61], off offset:256 nt
	s_cbranch_vccnz .LBB0_423
	s_waitcnt vmcnt(2)
	v_mov_b32_e32 v132, v224
	v_mov_b32_e32 v133, v225
	v_mov_b32_e32 v134, v226
	v_mov_b32_e32 v135, v227
	v_mov_b32_e32 v124, v228
	v_mov_b32_e32 v125, v229
	v_mov_b32_e32 v126, v230
	v_mov_b32_e32 v127, v231
	v_cndmask_b32_e64 v136, v216, -v216, s[2:3]
	v_cndmask_b32_e64 v137, v217, -v217, s[2:3]
	v_cndmask_b32_e64 v138, v218, -v218, s[2:3]
	v_cndmask_b32_e64 v139, v219, -v219, s[2:3]
	v_cndmask_b32_e64 v140, v220, -v220, s[2:3]
	v_cndmask_b32_e64 v141, v221, -v221, s[2:3]
	v_cndmask_b32_e64 v142, v222, -v222, s[2:3]
	v_cndmask_b32_e64 v143, v223, -v223, s[2:3]
	global_load_dwordx4 v[216:219], v[240:241], off offset:2048
	global_load_dwordx4 v[220:223], v[240:241], off offset:2064
	global_load_dwordx4 v[228:231], v[242:243], off offset:2064
	global_load_dwordx4 v[224:227], v[242:243], off offset:2048
.LBB0_423:
	v_add_u32_e32 v50, 0, v191
	v_add_u32_e32 v50, 0x20000, v50
	ds_read_b128 v[50:53], v50
	s_and_b64 vcc, exec, s[6:7]
	s_waitcnt lgkmcnt(0)
	v_mov_b32_e32 v54, v51
	v_mov_b32_e32 v55, v52
	v_mov_b32_e32 v51, v53
	v_pk_add_f32 v[50:51], v[54:55], v[50:51]
	s_nop 0
	v_add_f32_e32 v50, v50, v51
	v_fmamk_f32 v50, v50, 0x3c000000, v202
	v_rsq_f32_e32 v50, v50
	s_nop 0
	v_mul_f32_e32 v50, v203, v50
	v_pk_mul_f32 v[52:53], v[40:41], v[50:51] op_sel_hi:[1,0]
	v_pk_mul_f32 v[40:41], v[42:43], v[50:51] op_sel_hi:[1,0]
	v_pk_mul_f32 v[54:55], v[44:45], v[50:51] op_sel_hi:[1,0]
	v_pk_mul_f32 v[42:43], v[46:47], v[50:51] op_sel_hi:[1,0]
	v_pk_mul_f32 v[40:41], v[118:119], v[40:41]
	v_pk_mul_f32 v[44:45], v[116:117], v[52:53]
	v_pk_mul_f32 v[42:43], v[114:115], v[42:43]
	v_pk_mul_f32 v[46:47], v[112:113], v[54:55]
	s_cbranch_vccnz .LBB0_425
	v_mov_b32_e32 v50, v44
	v_mov_b32_e32 v52, v44
	v_mov_b32_e32 v54, v46
	v_mov_b32_e32 v55, v46
	v_permlane32_swap_b32_e32 v50, v52
	s_nop 0
	v_permlane32_swap_b32_e32 v54, v55
	v_mov_b32_e32 v51, v45
	v_mov_b32_e32 v53, v45
	v_mov_b32_e32 v56, v47
	v_mov_b32_e32 v57, v47
	v_cndmask_b32_e64 v50, v50, v52, s[2:3]
	v_cndmask_b32_e64 v52, v54, v55, s[2:3]
	v_mov_b32_e32 v54, v40
	v_mov_b32_e32 v55, v40
	v_permlane32_swap_b32_e32 v51, v53
	v_permlane32_swap_b32_e32 v56, v57
	v_permlane32_swap_b32_e32 v54, v55
	v_cndmask_b32_e64 v51, v51, v53, s[2:3]
	v_cndmask_b32_e64 v53, v56, v57, s[2:3]
	v_cndmask_b32_e64 v54, v54, v55, s[2:3]
	v_mov_b32_e32 v55, v42
	v_mov_b32_e32 v56, v42
	s_nop 1
	v_permlane32_swap_b32_e32 v55, v56
	v_cndmask_b32_e64 v55, v55, v56, s[2:3]
	v_mul_f32_e32 v56, v142, v55
	v_mov_b32_e32 v55, v41
	v_mov_b32_e32 v57, v41
	s_nop 1
	v_permlane32_swap_b32_e32 v55, v57
	v_cndmask_b32_e64 v59, v55, v57, s[2:3]
	v_mov_b32_e32 v55, v43
	v_mov_b32_e32 v57, v43
	v_pk_mul_f32 v[44:45], v[132:133], v[44:45]
	v_permlane32_swap_b32_e32 v55, v57
	v_cndmask_b32_e64 v61, v55, v57, s[2:3]
	v_mov_b32_e32 v62, v135
	v_mov_b32_e32 v63, v139
	v_mov_b32_e32 v58, v41
	v_pk_fma_f32 v[44:45], v[136:137], v[50:51], v[44:45]
	v_mov_b32_e32 v50, v127
	v_mov_b32_e32 v51, v143
	v_mov_b32_e32 v60, v43
	v_pk_mul_f32 v[58:59], v[62:63], v[58:59]
	v_pk_mul_f32 v[50:51], v[50:51], v[60:61]
	v_pk_mul_f32 v[46:47], v[124:125], v[46:47]
	v_mul_f32_e32 v40, v134, v40
	v_mul_f32_e32 v54, v138, v54
	v_mul_f32_e32 v42, v126, v42
	v_mov_b32_e32 v41, v58
	v_mov_b32_e32 v55, v59
	v_mov_b32_e32 v43, v50
	v_mov_b32_e32 v57, v51
	v_pk_add_f32 v[40:41], v[40:41], v[54:55]
	v_pk_fma_f32 v[46:47], v[140:141], v[52:53], v[46:47]
	v_pk_add_f32 v[42:43], v[42:43], v[56:57]
.LBB0_425:
	v_cvt_pk_bf16_f32 v44, v44, v45
	v_cvt_pk_bf16_f32 v45, v40, v41
	v_add_u32_e32 v40, s57, v191
	v_cvt_pk_bf16_f32 v46, v46, v47
	v_cvt_pk_bf16_f32 v47, v42, v43
	ds_read_b128 v[40:43], v40 offset:16
	s_and_b64 vcc, exec, s[6:7]
	s_waitcnt lgkmcnt(0)
	v_mov_b32_e32 v50, v41
	v_mov_b32_e32 v51, v42
	v_mov_b32_e32 v41, v43
	v_pk_add_f32 v[40:41], v[50:51], v[40:41]
	s_nop 0
	v_add_f32_e32 v40, v40, v41
	v_fmamk_f32 v40, v40, 0x3c000000, v202
	v_rsq_f32_e32 v42, v40
	v_lshlrev_b64 v[40:41], 12, v[48:49]
	v_lshl_add_u64 v[40:41], v[144:145], 0, v[40:41]
	global_store_dwordx4 v[40:41], v[44:47], off nt
	s_nop 1
	v_mul_f32_e32 v44, v203, v42
	v_pk_mul_f32 v[42:43], v[32:33], v[44:45] op_sel_hi:[1,0]
	v_pk_mul_f32 v[32:33], v[34:35], v[44:45] op_sel_hi:[1,0]
	v_pk_mul_f32 v[36:37], v[36:37], v[44:45] op_sel_hi:[1,0]
	v_pk_mul_f32 v[34:35], v[38:39], v[44:45] op_sel_hi:[1,0]
	v_pk_mul_f32 v[32:33], v[118:119], v[32:33]
	v_pk_mul_f32 v[42:43], v[116:117], v[42:43]
	v_pk_mul_f32 v[34:35], v[114:115], v[34:35]
	v_pk_mul_f32 v[36:37], v[112:113], v[36:37]
	s_cbranch_vccnz .LBB0_427
	v_mov_b32_e32 v38, v42
	v_mov_b32_e32 v44, v42
	v_mov_b32_e32 v46, v36
	v_mov_b32_e32 v47, v36
	v_permlane32_swap_b32_e32 v38, v44
	s_nop 0
	v_permlane32_swap_b32_e32 v46, v47
	v_mov_b32_e32 v39, v43
	v_mov_b32_e32 v45, v43
	v_mov_b32_e32 v48, v37
	v_mov_b32_e32 v49, v37
	v_cndmask_b32_e64 v38, v38, v44, s[2:3]
	v_cndmask_b32_e64 v44, v46, v47, s[2:3]
	v_mov_b32_e32 v46, v32
	v_mov_b32_e32 v47, v32
	v_permlane32_swap_b32_e32 v39, v45
	v_permlane32_swap_b32_e32 v48, v49
	v_permlane32_swap_b32_e32 v46, v47
	v_cndmask_b32_e64 v39, v39, v45, s[2:3]
	v_cndmask_b32_e64 v45, v48, v49, s[2:3]
	v_cndmask_b32_e64 v46, v46, v47, s[2:3]
	v_mov_b32_e32 v47, v34
	v_mov_b32_e32 v48, v34
	s_nop 1
	v_permlane32_swap_b32_e32 v47, v48
	v_cndmask_b32_e64 v47, v47, v48, s[2:3]
	v_mul_f32_e32 v48, v142, v47
	v_mov_b32_e32 v47, v33
	v_mov_b32_e32 v49, v33
	s_nop 1
	v_permlane32_swap_b32_e32 v47, v49
	v_cndmask_b32_e64 v51, v47, v49, s[2:3]
	v_mov_b32_e32 v47, v35
	v_mov_b32_e32 v49, v35
	v_pk_mul_f32 v[42:43], v[132:133], v[42:43]
	v_permlane32_swap_b32_e32 v47, v49
	v_cndmask_b32_e64 v53, v47, v49, s[2:3]
	v_mov_b32_e32 v54, v135
	v_mov_b32_e32 v55, v139
	v_mov_b32_e32 v50, v33
	v_pk_fma_f32 v[42:43], v[136:137], v[38:39], v[42:43]
	v_mov_b32_e32 v38, v127
	v_mov_b32_e32 v39, v143
	v_mov_b32_e32 v52, v35
	v_pk_mul_f32 v[50:51], v[54:55], v[50:51]
	v_pk_mul_f32 v[38:39], v[38:39], v[52:53]
	v_pk_mul_f32 v[36:37], v[124:125], v[36:37]
	v_mul_f32_e32 v32, v134, v32
	v_mul_f32_e32 v46, v138, v46
	v_mul_f32_e32 v34, v126, v34
	v_mov_b32_e32 v33, v50
	v_mov_b32_e32 v47, v51
	v_mov_b32_e32 v35, v38
	v_mov_b32_e32 v49, v39
	v_pk_add_f32 v[32:33], v[32:33], v[46:47]
	v_pk_fma_f32 v[36:37], v[140:141], v[44:45], v[36:37]
	v_pk_add_f32 v[34:35], v[34:35], v[48:49]
.LBB0_427:
	v_cvt_pk_bf16_f32 v42, v42, v43
	v_cvt_pk_bf16_f32 v43, v32, v33
	v_add_u32_e32 v32, s25, v183
	s_and_b64 vcc, exec, s[6:7]
	v_ashrrev_i32_e32 v33, 31, v32
	v_cvt_pk_bf16_f32 v44, v36, v37
	v_cvt_pk_bf16_f32 v45, v34, v35
	global_store_dwordx4 v[40:41], v[42:45], off offset:256 nt
	s_cbranch_vccnz .LBB0_429
	s_waitcnt vmcnt(2)
	v_mov_b32_e32 v132, v224
	v_mov_b32_e32 v133, v225
	v_mov_b32_e32 v134, v226
	v_mov_b32_e32 v135, v227
	v_mov_b32_e32 v124, v228
	v_mov_b32_e32 v125, v229
	v_mov_b32_e32 v126, v230
	v_mov_b32_e32 v127, v231
	v_cndmask_b32_e64 v136, v216, -v216, s[2:3]
	v_cndmask_b32_e64 v137, v217, -v217, s[2:3]
	v_cndmask_b32_e64 v138, v218, -v218, s[2:3]
	v_cndmask_b32_e64 v139, v219, -v219, s[2:3]
	v_cndmask_b32_e64 v140, v220, -v220, s[2:3]
	v_cndmask_b32_e64 v141, v221, -v221, s[2:3]
	v_cndmask_b32_e64 v142, v222, -v222, s[2:3]
	v_cndmask_b32_e64 v143, v223, -v223, s[2:3]
	global_load_dwordx4 v[216:219], v[240:241], off offset:3072
	global_load_dwordx4 v[220:223], v[240:241], off offset:3088
	global_load_dwordx4 v[228:231], v[242:243], off offset:3088
	global_load_dwordx4 v[224:227], v[242:243], off offset:3072
.LBB0_429:
	v_add_u32_e32 v34, 0, v178
	v_add_u32_e32 v34, 0x20000, v34
	ds_read_b128 v[34:37], v34
	s_and_b64 vcc, exec, s[6:7]
	s_waitcnt lgkmcnt(0)
	v_mov_b32_e32 v38, v35
	v_mov_b32_e32 v39, v36
	v_mov_b32_e32 v35, v37
	v_pk_add_f32 v[34:35], v[38:39], v[34:35]
	s_nop 0
	v_add_f32_e32 v34, v34, v35
	v_fmamk_f32 v34, v34, 0x3c000000, v202
	v_rsq_f32_e32 v34, v34
	s_nop 0
	v_mul_f32_e32 v34, v203, v34
	v_pk_mul_f32 v[36:37], v[24:25], v[34:35] op_sel_hi:[1,0]
	v_pk_mul_f32 v[24:25], v[26:27], v[34:35] op_sel_hi:[1,0]
	v_pk_mul_f32 v[38:39], v[28:29], v[34:35] op_sel_hi:[1,0]
	v_pk_mul_f32 v[26:27], v[30:31], v[34:35] op_sel_hi:[1,0]
	v_pk_mul_f32 v[24:25], v[118:119], v[24:25]
	v_pk_mul_f32 v[28:29], v[116:117], v[36:37]
	v_pk_mul_f32 v[26:27], v[114:115], v[26:27]
	v_pk_mul_f32 v[30:31], v[112:113], v[38:39]
	s_cbranch_vccnz .LBB0_431
	v_mov_b32_e32 v34, v28
	v_mov_b32_e32 v36, v28
	v_mov_b32_e32 v38, v30
	v_mov_b32_e32 v39, v30
	v_permlane32_swap_b32_e32 v34, v36
	s_nop 0
	v_permlane32_swap_b32_e32 v38, v39
	v_mov_b32_e32 v35, v29
	v_mov_b32_e32 v37, v29
	v_mov_b32_e32 v40, v31
	v_mov_b32_e32 v41, v31
	v_cndmask_b32_e64 v34, v34, v36, s[2:3]
	v_cndmask_b32_e64 v36, v38, v39, s[2:3]
	v_mov_b32_e32 v38, v24
	v_mov_b32_e32 v39, v24
	v_permlane32_swap_b32_e32 v35, v37
	v_permlane32_swap_b32_e32 v40, v41
	v_permlane32_swap_b32_e32 v38, v39
	v_cndmask_b32_e64 v35, v35, v37, s[2:3]
	v_cndmask_b32_e64 v37, v40, v41, s[2:3]
	v_cndmask_b32_e64 v38, v38, v39, s[2:3]
	v_mov_b32_e32 v39, v26
	v_mov_b32_e32 v40, v26
	s_nop 1
	v_permlane32_swap_b32_e32 v39, v40
	v_cndmask_b32_e64 v39, v39, v40, s[2:3]
	v_mul_f32_e32 v40, v142, v39
	v_mov_b32_e32 v39, v25
	v_mov_b32_e32 v41, v25
	s_nop 1
	v_permlane32_swap_b32_e32 v39, v41
	v_cndmask_b32_e64 v43, v39, v41, s[2:3]
	v_mov_b32_e32 v39, v27
	v_mov_b32_e32 v41, v27
	v_pk_mul_f32 v[28:29], v[132:133], v[28:29]
	v_permlane32_swap_b32_e32 v39, v41
	v_cndmask_b32_e64 v45, v39, v41, s[2:3]
	v_mov_b32_e32 v46, v135
	v_mov_b32_e32 v47, v139
	v_mov_b32_e32 v42, v25
	v_pk_fma_f32 v[28:29], v[136:137], v[34:35], v[28:29]
	v_mov_b32_e32 v34, v127
	v_mov_b32_e32 v35, v143
	v_mov_b32_e32 v44, v27
	v_pk_mul_f32 v[42:43], v[46:47], v[42:43]
	v_pk_mul_f32 v[34:35], v[34:35], v[44:45]
	v_pk_mul_f32 v[30:31], v[124:125], v[30:31]
	v_mul_f32_e32 v24, v134, v24
	v_mul_f32_e32 v38, v138, v38
	v_mul_f32_e32 v26, v126, v26
	v_mov_b32_e32 v25, v42
	v_mov_b32_e32 v39, v43
	v_mov_b32_e32 v27, v34
	v_mov_b32_e32 v41, v35
	v_pk_add_f32 v[24:25], v[24:25], v[38:39]
	v_pk_fma_f32 v[30:31], v[140:141], v[36:37], v[30:31]
	v_pk_add_f32 v[26:27], v[26:27], v[40:41]
.LBB0_431:
	v_cvt_pk_bf16_f32 v28, v28, v29
	v_cvt_pk_bf16_f32 v29, v24, v25
	v_add_u32_e32 v24, s57, v178
	v_cvt_pk_bf16_f32 v30, v30, v31
	v_cvt_pk_bf16_f32 v31, v26, v27
	ds_read_b128 v[24:27], v24 offset:16
	s_and_b64 vcc, exec, s[6:7]
	s_waitcnt lgkmcnt(0)
	v_mov_b32_e32 v34, v25
	v_mov_b32_e32 v35, v26
	v_mov_b32_e32 v25, v27
	v_pk_add_f32 v[24:25], v[34:35], v[24:25]
	s_nop 0
	v_add_f32_e32 v24, v24, v25
	v_fmamk_f32 v24, v24, 0x3c000000, v202
	v_rsq_f32_e32 v26, v24
	v_lshlrev_b64 v[24:25], 12, v[32:33]
	v_lshl_add_u64 v[24:25], v[144:145], 0, v[24:25]
	global_store_dwordx4 v[24:25], v[28:31], off nt
	s_nop 1
	v_mul_f32_e32 v28, v203, v26
	v_pk_mul_f32 v[26:27], v[16:17], v[28:29] op_sel_hi:[1,0]
	v_pk_mul_f32 v[16:17], v[18:19], v[28:29] op_sel_hi:[1,0]
	v_pk_mul_f32 v[20:21], v[20:21], v[28:29] op_sel_hi:[1,0]
	v_pk_mul_f32 v[18:19], v[22:23], v[28:29] op_sel_hi:[1,0]
	v_pk_mul_f32 v[16:17], v[118:119], v[16:17]
	v_pk_mul_f32 v[26:27], v[116:117], v[26:27]
	v_pk_mul_f32 v[18:19], v[114:115], v[18:19]
	v_pk_mul_f32 v[20:21], v[112:113], v[20:21]
	s_cbranch_vccnz .LBB0_433
	v_mov_b32_e32 v22, v26
	v_mov_b32_e32 v28, v26
	v_mov_b32_e32 v30, v20
	v_mov_b32_e32 v31, v20
	v_permlane32_swap_b32_e32 v22, v28
	s_nop 0
	v_permlane32_swap_b32_e32 v30, v31
	v_mov_b32_e32 v23, v27
	v_mov_b32_e32 v29, v27
	v_mov_b32_e32 v32, v21
	v_mov_b32_e32 v33, v21
	v_cndmask_b32_e64 v22, v22, v28, s[2:3]
	v_cndmask_b32_e64 v28, v30, v31, s[2:3]
	v_mov_b32_e32 v30, v16
	v_mov_b32_e32 v31, v16
	v_permlane32_swap_b32_e32 v23, v29
	v_permlane32_swap_b32_e32 v32, v33
	v_permlane32_swap_b32_e32 v30, v31
	v_cndmask_b32_e64 v23, v23, v29, s[2:3]
	v_cndmask_b32_e64 v29, v32, v33, s[2:3]
	v_cndmask_b32_e64 v30, v30, v31, s[2:3]
	v_mov_b32_e32 v31, v18
	v_mov_b32_e32 v32, v18
	s_nop 1
	v_permlane32_swap_b32_e32 v31, v32
	v_cndmask_b32_e64 v31, v31, v32, s[2:3]
	v_mul_f32_e32 v32, v142, v31
	v_mov_b32_e32 v31, v17
	v_mov_b32_e32 v33, v17
	s_nop 1
	v_permlane32_swap_b32_e32 v31, v33
	v_cndmask_b32_e64 v35, v31, v33, s[2:3]
	v_mov_b32_e32 v31, v19
	v_mov_b32_e32 v33, v19
	v_pk_mul_f32 v[26:27], v[132:133], v[26:27]
	v_permlane32_swap_b32_e32 v31, v33
	v_cndmask_b32_e64 v37, v31, v33, s[2:3]
	v_mov_b32_e32 v38, v135
	v_mov_b32_e32 v39, v139
	v_mov_b32_e32 v34, v17
	v_pk_fma_f32 v[26:27], v[136:137], v[22:23], v[26:27]
	v_mov_b32_e32 v22, v127
	v_mov_b32_e32 v23, v143
	v_mov_b32_e32 v36, v19
	v_pk_mul_f32 v[34:35], v[38:39], v[34:35]
	v_pk_mul_f32 v[22:23], v[22:23], v[36:37]
	v_pk_mul_f32 v[20:21], v[124:125], v[20:21]
	v_mul_f32_e32 v16, v134, v16
	v_mul_f32_e32 v30, v138, v30
	v_mul_f32_e32 v18, v126, v18
	v_mov_b32_e32 v17, v34
	v_mov_b32_e32 v31, v35
	v_mov_b32_e32 v19, v22
	v_mov_b32_e32 v33, v23
	v_pk_add_f32 v[16:17], v[16:17], v[30:31]
	v_pk_fma_f32 v[20:21], v[140:141], v[28:29], v[20:21]
	v_pk_add_f32 v[18:19], v[18:19], v[32:33]
.LBB0_433:
	v_cvt_pk_bf16_f32 v26, v26, v27
	v_cvt_pk_bf16_f32 v27, v16, v17
	v_add_u32_e32 v16, s25, v184
	s_and_b64 vcc, exec, s[6:7]
	v_ashrrev_i32_e32 v17, 31, v16
	v_cvt_pk_bf16_f32 v28, v20, v21
	v_cvt_pk_bf16_f32 v29, v18, v19
	global_store_dwordx4 v[24:25], v[26:29], off offset:256 nt
	s_cbranch_vccnz .LBB0_435
	s_waitcnt vmcnt(2)
	v_mov_b32_e32 v132, v224
	v_mov_b32_e32 v133, v225
	v_mov_b32_e32 v134, v226
	v_mov_b32_e32 v135, v227
	v_mov_b32_e32 v124, v228
	v_mov_b32_e32 v125, v229
	v_mov_b32_e32 v126, v230
	v_mov_b32_e32 v127, v231
	v_cndmask_b32_e64 v136, v216, -v216, s[2:3]
	v_cndmask_b32_e64 v137, v217, -v217, s[2:3]
	v_cndmask_b32_e64 v138, v218, -v218, s[2:3]
	v_cndmask_b32_e64 v139, v219, -v219, s[2:3]
	v_cndmask_b32_e64 v140, v220, -v220, s[2:3]
	v_cndmask_b32_e64 v141, v221, -v221, s[2:3]
	v_cndmask_b32_e64 v142, v222, -v222, s[2:3]
	v_cndmask_b32_e64 v143, v223, -v223, s[2:3]
.LBB0_435:
	v_add_u32_e32 v18, 0, v180
	v_add_u32_e32 v18, 0x20000, v18
	ds_read_b128 v[18:21], v18
	s_and_b64 vcc, exec, s[6:7]
	s_waitcnt lgkmcnt(0)
	v_mov_b32_e32 v22, v19
	v_mov_b32_e32 v23, v20
	v_mov_b32_e32 v19, v21
	v_pk_add_f32 v[18:19], v[22:23], v[18:19]
	s_nop 0
	v_add_f32_e32 v18, v18, v19
	v_fmamk_f32 v18, v18, 0x3c000000, v202
	v_rsq_f32_e32 v18, v18
	s_nop 0
	v_mul_f32_e32 v18, v203, v18
	v_pk_mul_f32 v[12:13], v[12:13], v[18:19] op_sel_hi:[1,0]
	v_pk_mul_f32 v[14:15], v[14:15], v[18:19] op_sel_hi:[1,0]
	v_pk_mul_f32 v[20:21], v[8:9], v[18:19] op_sel_hi:[1,0]
	v_pk_mul_f32 v[10:11], v[10:11], v[18:19] op_sel_hi:[1,0]
	v_pk_mul_f32 v[8:9], v[118:119], v[14:15]
	v_pk_mul_f32 v[12:13], v[116:117], v[12:13]
	v_pk_mul_f32 v[10:11], v[114:115], v[10:11]
	v_pk_mul_f32 v[14:15], v[112:113], v[20:21]
	s_cbranch_vccnz .LBB0_437
	v_mov_b32_e32 v18, v12
	v_mov_b32_e32 v20, v12
	v_mov_b32_e32 v22, v14
	v_mov_b32_e32 v23, v14
	v_permlane32_swap_b32_e32 v18, v20
	s_nop 0
	v_permlane32_swap_b32_e32 v22, v23
	v_mov_b32_e32 v19, v13
	v_mov_b32_e32 v21, v13
	v_mov_b32_e32 v24, v15
	v_mov_b32_e32 v25, v15
	v_cndmask_b32_e64 v18, v18, v20, s[2:3]
	v_cndmask_b32_e64 v20, v22, v23, s[2:3]
	v_mov_b32_e32 v22, v8
	v_mov_b32_e32 v23, v8
	v_permlane32_swap_b32_e32 v19, v21
	v_permlane32_swap_b32_e32 v24, v25
	v_permlane32_swap_b32_e32 v22, v23
	v_cndmask_b32_e64 v19, v19, v21, s[2:3]
	v_cndmask_b32_e64 v21, v24, v25, s[2:3]
	v_cndmask_b32_e64 v22, v22, v23, s[2:3]
	v_mov_b32_e32 v23, v10
	v_mov_b32_e32 v24, v10
	s_nop 1
	v_permlane32_swap_b32_e32 v23, v24
	v_cndmask_b32_e64 v23, v23, v24, s[2:3]
	v_mul_f32_e32 v24, v142, v23
	v_mov_b32_e32 v23, v9
	v_mov_b32_e32 v25, v9
	s_nop 1
	v_permlane32_swap_b32_e32 v23, v25
	v_cndmask_b32_e64 v27, v23, v25, s[2:3]
	v_mov_b32_e32 v23, v11
	v_mov_b32_e32 v25, v11
	v_pk_mul_f32 v[12:13], v[132:133], v[12:13]
	v_permlane32_swap_b32_e32 v23, v25
	v_cndmask_b32_e64 v29, v23, v25, s[2:3]
	v_mov_b32_e32 v30, v135
	v_mov_b32_e32 v31, v139
	v_mov_b32_e32 v26, v9
	v_pk_fma_f32 v[12:13], v[136:137], v[18:19], v[12:13]
	v_mov_b32_e32 v18, v127
	v_mov_b32_e32 v19, v143
	v_mov_b32_e32 v28, v11
	v_pk_mul_f32 v[26:27], v[30:31], v[26:27]
	v_pk_mul_f32 v[18:19], v[18:19], v[28:29]
	v_pk_mul_f32 v[14:15], v[124:125], v[14:15]
	v_mul_f32_e32 v8, v134, v8
	v_mul_f32_e32 v22, v138, v22
	v_mul_f32_e32 v10, v126, v10
	v_mov_b32_e32 v9, v26
	v_mov_b32_e32 v23, v27
	v_mov_b32_e32 v11, v18
	v_mov_b32_e32 v25, v19
	v_pk_add_f32 v[8:9], v[8:9], v[22:23]
	v_pk_fma_f32 v[14:15], v[140:141], v[20:21], v[14:15]
	v_pk_add_f32 v[10:11], v[10:11], v[24:25]
.LBB0_437:
	v_cvt_pk_bf16_f32 v12, v12, v13
	v_cvt_pk_bf16_f32 v13, v8, v9
	v_add_u32_e32 v8, s57, v180
	v_cvt_pk_bf16_f32 v14, v14, v15
	v_cvt_pk_bf16_f32 v15, v10, v11
	ds_read_b128 v[8:11], v8 offset:16
	s_and_b64 vcc, exec, s[6:7]
	s_waitcnt lgkmcnt(0)
	v_mov_b32_e32 v18, v9
	v_mov_b32_e32 v19, v10
	v_mov_b32_e32 v9, v11
	v_pk_add_f32 v[8:9], v[18:19], v[8:9]
	s_nop 0
	v_add_f32_e32 v8, v8, v9
	v_fmamk_f32 v8, v8, 0x3c000000, v202
	v_rsq_f32_e32 v10, v8
	v_lshlrev_b64 v[8:9], 12, v[16:17]
	v_lshl_add_u64 v[174:175], v[144:145], 0, v[8:9]
	global_store_dwordx4 v[174:175], v[12:15], off nt
	v_mul_f32_e32 v8, v203, v10
	v_pk_mul_f32 v[10:11], v[4:5], v[8:9] op_sel_hi:[1,0]
	v_pk_mul_f32 v[4:5], v[6:7], v[8:9] op_sel_hi:[1,0]
	v_pk_mul_f32 v[6:7], v[116:117], v[10:11]
	v_pk_mul_f32 v[10:11], v[0:1], v[8:9] op_sel_hi:[1,0]
	v_pk_mul_f32 v[0:1], v[2:3], v[8:9] op_sel_hi:[1,0]
	v_pk_mul_f32 v[4:5], v[118:119], v[4:5]
	v_pk_mul_f32 v[0:1], v[114:115], v[0:1]
	v_pk_mul_f32 v[2:3], v[112:113], v[10:11]
	s_cbranch_vccnz .LBB0_439
	v_mov_b32_e32 v8, v6
	v_mov_b32_e32 v10, v6
	v_mov_b32_e32 v12, v2
	v_mov_b32_e32 v13, v2
	v_permlane32_swap_b32_e32 v8, v10
	s_nop 0
	v_permlane32_swap_b32_e32 v12, v13
	v_mov_b32_e32 v9, v7
	v_mov_b32_e32 v11, v7
	v_mov_b32_e32 v14, v3
	v_mov_b32_e32 v15, v3
	v_cndmask_b32_e64 v8, v8, v10, s[2:3]
	v_cndmask_b32_e64 v10, v12, v13, s[2:3]
	v_mov_b32_e32 v12, v4
	v_mov_b32_e32 v13, v4
	v_permlane32_swap_b32_e32 v9, v11
	v_permlane32_swap_b32_e32 v14, v15
	v_permlane32_swap_b32_e32 v12, v13
	v_cndmask_b32_e64 v9, v9, v11, s[2:3]
	v_cndmask_b32_e64 v11, v14, v15, s[2:3]
	v_cndmask_b32_e64 v12, v12, v13, s[2:3]
	v_mov_b32_e32 v13, v0
	v_mov_b32_e32 v14, v0
	s_nop 1
	v_permlane32_swap_b32_e32 v13, v14
	v_cndmask_b32_e64 v13, v13, v14, s[2:3]
	v_mul_f32_e32 v14, v142, v13
	v_mov_b32_e32 v13, v5
	v_mov_b32_e32 v15, v5
	s_nop 1
	v_permlane32_swap_b32_e32 v13, v15
	v_cndmask_b32_e64 v17, v13, v15, s[2:3]
	v_mov_b32_e32 v13, v1
	v_mov_b32_e32 v15, v1
	s_nop 1
	v_permlane32_swap_b32_e32 v13, v15
	v_pk_mul_f32 v[6:7], v[132:133], v[6:7]
	v_mul_f32_e32 v12, v138, v12
	v_cndmask_b32_e64 v19, v13, v15, s[2:3]
	v_mov_b32_e32 v138, v135
	v_mov_b32_e32 v16, v5
	v_mov_b32_e32 v142, v127
	v_mov_b32_e32 v18, v1
	v_pk_mul_f32 v[16:17], v[138:139], v[16:17]
	v_pk_fma_f32 v[6:7], v[136:137], v[8:9], v[6:7]
	v_pk_mul_f32 v[8:9], v[142:143], v[18:19]
	v_pk_mul_f32 v[2:3], v[124:125], v[2:3]
	v_mul_f32_e32 v4, v134, v4
	v_mul_f32_e32 v0, v126, v0
	v_mov_b32_e32 v5, v16
	v_mov_b32_e32 v13, v17
	v_mov_b32_e32 v1, v8
	v_mov_b32_e32 v15, v9
	v_pk_add_f32 v[4:5], v[4:5], v[12:13]
	v_pk_fma_f32 v[2:3], v[140:141], v[10:11], v[2:3]
	v_pk_add_f32 v[0:1], v[0:1], v[14:15]

.LBB0_1184:
.LBB0_1185:
	s_nop 0
	s_cmp_lt_i32 s92, 6
	s_cselect_b64 s[0:1], -1, 0
	s_cmp_gt_i32 s93, 5
	s_cselect_b64 s[2:3], -1, 0
	s_and_b64 s[0:1], s[0:1], s[2:3]
	s_andn2_b64 vcc, exec, s[0:1]
	s_cbranch_vccnz .LBB0_1450
	s_andn2_b64 vcc, exec, s[8:9]
	s_cbranch_vccnz .LBB0_1194
	v_readlane_b32 s0, v254, 24
	s_cmp_gt_u32 s0, 63
	v_mbcnt_lo_u32_b32 v0, -1, 0
	v_mbcnt_hi_u32_b32 v0, -1, v0
	s_cbranch_scc1 .LBB0_1193
	v_readlane_b32 s0, v254, 0
	v_readlane_b32 s1, v254, 1
	v_readlane_b32 s2, v254, 2
	v_readlane_b32 s3, v254, 3
	v_readlane_b32 s4, v254, 4
	v_readlane_b32 s5, v254, 5
	v_readlane_b32 s6, v254, 6
	v_readlane_b32 s7, v254, 7
	s_waitcnt lgkmcnt(0)
	v_ashrrev_i32_e32 v1, 31, v0
	v_readlane_b32 s0, v254, 16
	v_lshlrev_b64 v[2:3], 2, v[0:1]
	v_readlane_b32 s14, v254, 14
	v_readlane_b32 s15, v254, 15
	v_readlane_b32 s1, v254, 17
	v_readlane_b32 s12, v254, 12
	v_lshl_add_u64 v[4:5], s[14:15], 0, v[2:3]
	v_lshl_add_u64 v[2:3], s[0:1], 0, v[2:3]
	global_load_dword v6, v[4:5], off
	global_load_dword v7, v[4:5], off offset:256
	s_nop 0
	global_load_dword v4, v[2:3], off offset:256
	global_load_dword v5, v[2:3], off
	v_mbcnt_lo_u32_b32 v2, -1, 0
	v_mbcnt_hi_u32_b32 v2, -1, v2
	v_and_b32_e32 v3, 64, v2
	v_xor_b32_e32 v8, 1, v2
	v_add_u32_e32 v3, 64, v3
	v_cmp_lt_i32_e32 vcc, v8, v3
	v_xor_b32_e32 v9, 2, v2
	v_xor_b32_e32 v10, 4, v2
	v_cndmask_b32_e32 v8, v2, v8, vcc
	v_lshlrev_b32_e32 v8, 2, v8
	v_cmp_lt_i32_e32 vcc, v9, v3
	v_xor_b32_e32 v11, 8, v2
	v_xor_b32_e32 v12, 16, v2
	v_xor_b32_e32 v13, 32, v2
	v_readlane_b32 s13, v254, 13
	v_readlane_b32 s8, v254, 8
	v_readlane_b32 s9, v254, 9
	v_readlane_b32 s10, v254, 10
	v_readlane_b32 s11, v254, 11
	v_readlane_b32 s2, v254, 18
	v_readlane_b32 s3, v254, 19
	v_readlane_b32 s4, v254, 20
	v_readlane_b32 s5, v254, 21
	v_readlane_b32 s6, v254, 22
	v_readlane_b32 s7, v254, 23
	s_waitcnt vmcnt(0)
	v_max_f32_e64 v6, |v6|, |v6|
	v_max_f32_e64 v7, |v7|, |v7|
	v_max_f32_e64 v4, |v4|, |v4|
	v_max_f32_e64 v5, |v5|, |v5|
	v_max_f32_e32 v6, v6, v7
	v_max_f32_e32 v4, v5, v4
	ds_bpermute_b32 v5, v8, v6
	ds_bpermute_b32 v7, v8, v4
	v_cndmask_b32_e32 v8, v2, v9, vcc
	v_lshlrev_b32_e32 v8, 2, v8
	v_cmp_lt_i32_e32 vcc, v10, v3
	s_waitcnt lgkmcnt(1)
	v_max_f32_e32 v5, v5, v5
	s_waitcnt lgkmcnt(0)
	v_max_f32_e32 v7, v7, v7
	v_max_f32_e32 v5, v6, v5
	v_max_f32_e32 v4, v4, v7
	ds_bpermute_b32 v6, v8, v5
	ds_bpermute_b32 v7, v8, v4
	v_cndmask_b32_e32 v8, v2, v10, vcc
	v_lshlrev_b32_e32 v8, 2, v8
	v_cmp_lt_i32_e32 vcc, v11, v3
	s_waitcnt lgkmcnt(1)
	v_max_f32_e32 v6, v6, v6
	s_waitcnt lgkmcnt(0)
	v_max_f32_e32 v7, v7, v7
	v_max_f32_e32 v5, v5, v6
	v_max_f32_e32 v4, v4, v7
	ds_bpermute_b32 v6, v8, v5
	ds_bpermute_b32 v7, v8, v4
	v_cndmask_b32_e32 v8, v2, v11, vcc
	v_lshlrev_b32_e32 v8, 2, v8
	v_cmp_lt_i32_e32 vcc, v12, v3
	s_waitcnt lgkmcnt(1)
	v_max_f32_e32 v6, v6, v6
	s_waitcnt lgkmcnt(0)
	v_max_f32_e32 v7, v7, v7
	v_max_f32_e32 v5, v5, v6
	v_max_f32_e32 v4, v4, v7
	ds_bpermute_b32 v6, v8, v5
	ds_bpermute_b32 v7, v8, v4
	v_cndmask_b32_e32 v8, v2, v12, vcc
	v_lshlrev_b32_e32 v8, 2, v8
	v_cmp_lt_i32_e32 vcc, v13, v3
	s_waitcnt lgkmcnt(1)
	v_max_f32_e32 v6, v6, v6
	s_waitcnt lgkmcnt(0)
	v_max_f32_e32 v7, v7, v7
	v_max_f32_e32 v5, v5, v6
	v_max_f32_e32 v4, v4, v7
	ds_bpermute_b32 v6, v8, v5
	ds_bpermute_b32 v7, v8, v4
	v_cndmask_b32_e32 v2, v2, v13, vcc
	v_lshlrev_b32_e32 v8, 2, v2
	v_cmp_gt_i32_e32 vcc, 16, v0
	s_waitcnt lgkmcnt(1)
	v_max_f32_e32 v2, v6, v6
	s_waitcnt lgkmcnt(0)
	v_max_f32_e32 v6, v7, v7
	v_max_f32_e32 v3, v5, v2
	v_max_f32_e32 v2, v4, v6
	ds_bpermute_b32 v5, v8, v3
	ds_bpermute_b32 v4, v8, v2
	s_and_saveexec_b64 s[78:79], vcc
	s_cbranch_execz .LBB0_1190
	v_lshl_add_u64 v[22:23], v[0:1], 2, s[12:13]
	v_mov_b32_e32 v24, 0
	global_load_dword v1, v[22:23], off
	global_load_dwordx4 v[6:9], v24, s[12:13]
	global_load_dwordx4 v[10:13], v24, s[12:13] offset:16
	global_load_dwordx4 v[14:17], v24, s[12:13] offset:32
	global_load_dwordx4 v[18:21], v24, s[12:13] offset:48
	v_cmp_lt_i32_e64 s[0:1], 1, v0
	v_cmp_lt_i32_e64 s[2:3], 2, v0
	v_cmp_lt_i32_e64 s[4:5], 3, v0
	v_cmp_lt_i32_e64 s[6:7], 4, v0
	v_cmp_lt_i32_e64 s[8:9], 5, v0
	v_cmp_lt_i32_e64 s[10:11], 6, v0
	v_cmp_lt_i32_e64 s[12:13], 7, v0
	v_cmp_lt_i32_e64 s[14:15], 8, v0
	v_cmp_lt_i32_e64 s[16:17], 9, v0
	v_cmp_lt_i32_e64 s[18:19], 10, v0
	v_cmp_lt_i32_e64 s[20:21], 11, v0
	v_cmp_lt_i32_e64 s[22:23], 12, v0
	v_cmp_lt_i32_e32 vcc, 0, v0
	s_waitcnt vmcnt(3)
	v_cmp_eq_f32_e64 s[30:31], v7, v1
	v_cmp_lt_f32_e64 s[28:29], v7, v1
	v_cmp_eq_f32_e64 s[36:37], v8, v1
	s_and_b64 s[0:1], s[0:1], s[30:31]
	v_cmp_lt_f32_e64 s[34:35], v8, v1
	v_cmp_eq_f32_e64 s[40:41], v9, v1
	s_and_b64 s[2:3], s[2:3], s[36:37]
	s_or_b64 s[0:1], s[28:29], s[0:1]
	v_cmp_lt_f32_e64 s[38:39], v9, v1
	s_waitcnt vmcnt(2)
	v_cmp_eq_f32_e64 s[44:45], v10, v1
	s_and_b64 s[4:5], s[4:5], s[40:41]
	v_cndmask_b32_e64 v7, 0, 1, s[0:1]
	s_or_b64 s[0:1], s[34:35], s[2:3]
	v_cmp_lt_f32_e64 s[42:43], v10, v1
	v_cmp_eq_f32_e64 s[48:49], v11, v1
	s_and_b64 s[6:7], s[6:7], s[44:45]
	v_cndmask_b32_e64 v8, 0, 1, s[0:1]
	s_or_b64 s[0:1], s[38:39], s[4:5]
	v_cmp_lt_f32_e64 s[46:47], v11, v1
	v_cmp_eq_f32_e64 s[52:53], v12, v1
	s_and_b64 s[8:9], s[8:9], s[48:49]
	v_cndmask_b32_e64 v9, 0, 1, s[0:1]
	s_or_b64 s[0:1], s[42:43], s[6:7]
	v_cmp_lt_f32_e64 s[50:51], v12, v1
	v_cmp_eq_f32_e64 s[56:57], v13, v1
	s_and_b64 s[10:11], s[10:11], s[52:53]
	v_cndmask_b32_e64 v10, 0, 1, s[0:1]
	s_or_b64 s[0:1], s[46:47], s[8:9]
	v_cmp_lt_f32_e64 s[54:55], v13, v1
	s_waitcnt vmcnt(1)
	v_cmp_eq_f32_e64 s[60:61], v14, v1
	s_and_b64 s[12:13], s[12:13], s[56:57]
	v_cndmask_b32_e64 v11, 0, 1, s[0:1]
	s_or_b64 s[0:1], s[50:51], s[10:11]
	v_cmp_lt_f32_e64 s[58:59], v14, v1
	v_cmp_eq_f32_e64 s[64:65], v15, v1
	s_and_b64 s[14:15], s[14:15], s[60:61]
	v_cndmask_b32_e64 v12, 0, 1, s[0:1]
	s_or_b64 s[0:1], s[54:55], s[12:13]
	v_cmp_lt_f32_e64 s[62:63], v15, v1
	v_cmp_eq_f32_e64 s[68:69], v16, v1
	s_and_b64 s[16:17], s[16:17], s[64:65]
	v_cndmask_b32_e64 v13, 0, 1, s[0:1]
	s_or_b64 s[0:1], s[58:59], s[14:15]
	v_cmp_lt_f32_e64 s[66:67], v16, v1
	v_cmp_eq_f32_e64 s[72:73], v17, v1
	s_and_b64 s[18:19], s[18:19], s[68:69]
	v_cndmask_b32_e64 v14, 0, 1, s[0:1]
	s_or_b64 s[0:1], s[62:63], s[16:17]
	v_cmp_lt_f32_e64 s[70:71], v17, v1
	s_waitcnt vmcnt(0)
	v_cmp_eq_f32_e64 s[76:77], v18, v1
	s_and_b64 s[20:21], s[20:21], s[72:73]
	v_cndmask_b32_e64 v15, 0, 1, s[0:1]
	s_or_b64 s[0:1], s[66:67], s[18:19]
	v_cmp_lt_f32_e64 s[74:75], v18, v1
	s_and_b64 s[22:23], s[22:23], s[76:77]
	v_cndmask_b32_e64 v16, 0, 1, s[0:1]
	s_or_b64 s[0:1], s[70:71], s[20:21]
	v_cndmask_b32_e64 v17, 0, 1, s[0:1]
	s_or_b64 s[0:1], s[74:75], s[22:23]
	v_cmp_eq_f32_e64 s[26:27], v6, v1
	v_cndmask_b32_e64 v18, 0, 1, s[0:1]
	v_cmp_eq_f32_e64 s[0:1], v19, v1
	v_cmp_lt_i32_e64 s[2:3], 13, v0
	s_and_b64 s[26:27], vcc, s[26:27]
	v_cmp_lt_f32_e32 vcc, v19, v1
	s_and_b64 s[0:1], s[2:3], s[0:1]
	s_or_b64 s[0:1], vcc, s[0:1]
	v_cmp_lt_f32_e64 s[24:25], v6, v1
	v_cndmask_b32_e64 v19, 0, 1, s[0:1]
	v_cmp_eq_f32_e64 s[0:1], v20, v1
	v_cmp_eq_u32_e64 s[2:3], 15, v0
	s_or_b64 s[24:25], s[24:25], s[26:27]
	v_cmp_lt_f32_e32 vcc, v20, v1
	s_and_b64 s[0:1], s[2:3], s[0:1]
	v_cndmask_b32_e64 v6, 0, 1, s[24:25]
	s_or_b64 s[0:1], vcc, s[0:1]
	v_cndmask_b32_e64 v20, 0, 1, s[0:1]
	v_lshlrev_b32_e32 v6, 2, v6
	s_add_i32 s0, 0, 0x12c40
	v_lshlrev_b32_e32 v7, 2, v7
	v_add3_u32 v6, s0, v6, v7
	v_lshlrev_b32_e32 v7, 2, v8
	v_lshlrev_b32_e32 v8, 2, v9
	v_add3_u32 v6, v6, v7, v8
	v_lshlrev_b32_e32 v7, 2, v10
	v_lshlrev_b32_e32 v8, 2, v11
	v_add3_u32 v6, v6, v7, v8
	v_lshlrev_b32_e32 v7, 2, v12
	v_lshlrev_b32_e32 v8, 2, v13
	v_add3_u32 v6, v6, v7, v8
	v_lshlrev_b32_e32 v7, 2, v14
	v_lshlrev_b32_e32 v8, 2, v15
	v_cmp_lt_f32_e32 vcc, v21, v1
	v_add3_u32 v6, v6, v7, v8
	v_lshlrev_b32_e32 v7, 2, v16
	v_lshlrev_b32_e32 v8, 2, v17
	v_cndmask_b32_e64 v1, 0, 1, vcc
	v_add3_u32 v6, v6, v7, v8
	v_lshlrev_b32_e32 v7, 2, v18
	v_lshlrev_b32_e32 v8, 2, v19
	v_add3_u32 v6, v6, v7, v8
	v_lshlrev_b32_e32 v7, 2, v20
	v_lshlrev_b32_e32 v1, 2, v1
	v_readlane_b32 s68, v254, 29
	v_readlane_b32 s69, v254, 28
	v_add3_u32 v1, v6, v7, v1
	ds_write_b32 v1, v0

.LBB0_1312:
	v_bfe_u32 v176, v32, 5, 1
	v_lshlrev_b32_e32 v172, 2, v176
	v_sub_u32_e32 v178, v0, v172
	s_add_i32 s0, 0, 0x10800
	v_bitop3_b32 v0, v176, v32, 15 bitop3:0x78
	v_writelane_b32 v254, s8, 44
	s_add_i32 s78, s75, 31
	v_lshl_add_u32 v190, v176, 4, s0
	v_lshlrev_b32_e32 v33, 8, v171
	v_lshlrev_b32_e32 v66, 4, v0
	v_or_b32_e32 v50, v66, v33
	s_setprio 1
	s_add_i32 s63, s80, 3
	v_lshl_add_u32 v16, s63, 8, v190
	ds_read_b128 v[0:3], v16
	ds_read_b128 v[4:7], v16 offset:32
	ds_read_b128 v[8:11], v16 offset:64
	ds_read_b128 v[12:15], v16 offset:96
	ds_read_b128 v[34:37], v16 offset:128
	ds_read_b128 v[38:41], v16 offset:160
	ds_read_b128 v[42:45], v16 offset:192
	ds_read_b128 v[46:49], v16 offset:224
	s_lshl_b32 s2, s63, 6
	s_waitcnt lgkmcnt(4)
	v_pk_add_f32 v[30:31], v[14:15], v[180:181] op_sel:[0,1] op_sel_hi:[1,1] neg_lo:[0,1] neg_hi:[0,1]
	v_pk_add_f32 v[28:29], v[12:13], v[180:181] op_sel:[0,1] op_sel_hi:[1,1] neg_lo:[0,1] neg_hi:[0,1]
	v_pk_add_f32 v[26:27], v[10:11], v[180:181] op_sel:[0,1] op_sel_hi:[1,1] neg_lo:[0,1] neg_hi:[0,1]
	v_pk_add_f32 v[24:25], v[8:9], v[180:181] op_sel:[0,1] op_sel_hi:[1,1] neg_lo:[0,1] neg_hi:[0,1]
	v_pk_add_f32 v[22:23], v[6:7], v[180:181] op_sel:[0,1] op_sel_hi:[1,1] neg_lo:[0,1] neg_hi:[0,1]
	v_pk_add_f32 v[20:21], v[4:5], v[180:181] op_sel:[0,1] op_sel_hi:[1,1] neg_lo:[0,1] neg_hi:[0,1]
	v_pk_add_f32 v[18:19], v[2:3], v[180:181] op_sel:[0,1] op_sel_hi:[1,1] neg_lo:[0,1] neg_hi:[0,1]
	v_pk_add_f32 v[16:17], v[0:1], v[180:181] op_sel:[0,1] op_sel_hi:[1,1] neg_lo:[0,1] neg_hi:[0,1]
	s_waitcnt lgkmcnt(0)
	v_pk_add_f32 v[14:15], v[48:49], v[180:181] op_sel:[0,1] op_sel_hi:[1,1] neg_lo:[0,1] neg_hi:[0,1]
	v_pk_add_f32 v[12:13], v[46:47], v[180:181] op_sel:[0,1] op_sel_hi:[1,1] neg_lo:[0,1] neg_hi:[0,1]
	v_pk_add_f32 v[10:11], v[44:45], v[180:181] op_sel:[0,1] op_sel_hi:[1,1] neg_lo:[0,1] neg_hi:[0,1]
	v_pk_add_f32 v[8:9], v[42:43], v[180:181] op_sel:[0,1] op_sel_hi:[1,1] neg_lo:[0,1] neg_hi:[0,1]
	v_pk_add_f32 v[6:7], v[40:41], v[180:181] op_sel:[0,1] op_sel_hi:[1,1] neg_lo:[0,1] neg_hi:[0,1]
	v_pk_add_f32 v[4:5], v[38:39], v[180:181] op_sel:[0,1] op_sel_hi:[1,1] neg_lo:[0,1] neg_hi:[0,1]
	v_pk_add_f32 v[2:3], v[36:37], v[180:181] op_sel:[0,1] op_sel_hi:[1,1] neg_lo:[0,1] neg_hi:[0,1]
	v_pk_add_f32 v[0:1], v[34:35], v[180:181] op_sel:[0,1] op_sel_hi:[1,1] neg_lo:[0,1] neg_hi:[0,1]
	s_cmp_lg_u32 0, -1
	s_cselect_b32 s0, 0, 0
	v_add_u32_e32 v189, s0, v50
	ds_read_b128 v[34:37], v189 offset:0x8000
	ds_read_b128 v[38:41], v189 offset:0xa000
	v_xad_u32 v188, v50, 32, s0
	ds_read_b128 v[42:45], v188 offset:0x8000
	ds_read_b128 v[46:49], v188 offset:0xa000
	v_xad_u32 v187, v50, 64, s0
	ds_read_b128 v[50:53], v187 offset:0x8000
	s_movk_i32 s1, 0x60
	ds_read_b128 v[54:57], v187 offset:0xa000
	v_bitop3_b32 v58, v66, s1, v33 bitop3:0x36
	v_add_u32_e32 v184, s0, v58
	ds_read_b128 v[58:61], v184 offset:0x8000
	ds_read_b128 v[62:65], v184 offset:0xa000
	s_waitcnt lgkmcnt(7)
	v_mfma_f32_32x32x16_bf16 v[16:31], v[34:37], v[144:147], v[16:31]
	s_movk_i32 s1, 0x80
	v_bitop3_b32 v34, v66, s1, v33 bitop3:0x36
	v_add_u32_e32 v182, s0, v34
	ds_read_b128 v[34:37], v182 offset:0x8000
	s_waitcnt lgkmcnt(7)
	v_mfma_f32_32x32x16_bf16 v[0:15], v[38:41], v[144:147], v[0:15]
	ds_read_b128 v[38:41], v182 offset:0xa000
	s_waitcnt lgkmcnt(7)
	v_mfma_f32_32x32x16_bf16 v[16:31], v[42:45], v[136:139], v[16:31]
	s_movk_i32 s1, 0xa0
	v_bitop3_b32 v42, v66, s1, v33 bitop3:0x36
	v_add_u32_e32 v183, s0, v42
	ds_read_b128 v[42:45], v183 offset:0x8000
	s_waitcnt lgkmcnt(7)
	v_mfma_f32_32x32x16_bf16 v[0:15], v[46:49], v[136:139], v[0:15]
	ds_read_b128 v[46:49], v183 offset:0xa000
	s_waitcnt lgkmcnt(7)
	v_mfma_f32_32x32x16_bf16 v[16:31], v[50:53], v[128:131], v[16:31]
	s_movk_i32 s1, 0xc0
	v_bitop3_b32 v50, v66, s1, v33 bitop3:0x36
	v_add_u32_e32 v185, s0, v50
	ds_read_b128 v[50:53], v185 offset:0x8000
	s_waitcnt lgkmcnt(7)
	v_mfma_f32_32x32x16_bf16 v[0:15], v[54:57], v[128:131], v[0:15]
	ds_read_b128 v[54:57], v185 offset:0xa000
	s_waitcnt lgkmcnt(7)
	v_mfma_f32_32x32x16_bf16 v[16:31], v[58:61], v[124:127], v[16:31]
	s_movk_i32 s1, 0xe0
	v_bitop3_b32 v33, v66, s1, v33 bitop3:0x36
	v_add_u32_e32 v186, s0, v33
	ds_read_b128 v[58:61], v186 offset:0x8000
	s_waitcnt lgkmcnt(7)
	v_mfma_f32_32x32x16_bf16 v[0:15], v[62:65], v[124:127], v[0:15]
	ds_read_b128 v[62:65], v186 offset:0xa000
	s_waitcnt lgkmcnt(7)
	v_mfma_f32_32x32x16_bf16 v[16:31], v[34:37], v[120:123], v[16:31]
	s_waitcnt lgkmcnt(6)
	v_mfma_f32_32x32x16_bf16 v[0:15], v[38:41], v[120:123], v[0:15]
	s_waitcnt lgkmcnt(5)
	v_mfma_f32_32x32x16_bf16 v[16:31], v[42:45], v[116:119], v[16:31]
	s_waitcnt lgkmcnt(4)
	v_mfma_f32_32x32x16_bf16 v[0:15], v[46:49], v[116:119], v[0:15]
	s_waitcnt lgkmcnt(3)
	s_waitcnt vmcnt(1)
	v_mfma_f32_32x32x16_bf16 v[16:31], v[50:53], v[140:143], v[16:31]
	s_waitcnt lgkmcnt(2)
	v_mfma_f32_32x32x16_bf16 v[0:15], v[54:57], v[140:143], v[0:15]
	s_waitcnt lgkmcnt(1)
	s_waitcnt vmcnt(0)
	v_mfma_f32_32x32x16_bf16 v[16:31], v[58:61], v[132:135], v[16:31]
	s_waitcnt lgkmcnt(0)
	v_mfma_f32_32x32x16_bf16 v[0:15], v[62:65], v[132:135], v[0:15]
	s_setprio 0
	s_waitcnt lgkmcnt(0)
	s_barrier
	s_cmp_le_i32 s2, s78
	s_mov_b64 s[0:1], -1
	s_cbranch_scc0 .LBB0_1316
	s_or_b32 s0, s2, 63
	s_cmp_le_u32 s0, s75
	s_cbranch_scc1 .LBB0_1315
	v_subrev_u32_e32 v33, s2, v178
	v_cmp_gt_i32_e64 s[58:59], 26, v33
	v_cmp_gt_i32_e64 s[60:61], 27, v33
	v_cmp_gt_i32_e64 s[56:57], 25, v33
	s_and_b64 s[58:59], s[60:61], s[58:59]
	v_cmp_gt_i32_e64 s[54:55], 24, v33
	s_and_b64 s[56:57], s[58:59], s[56:57]
	v_cmp_gt_i32_e64 s[52:53], 19, v33
	s_and_b64 s[54:55], s[56:57], s[54:55]
	v_cmp_gt_i32_e64 s[50:51], 18, v33
	s_and_b64 s[52:53], s[54:55], s[52:53]
	v_cmp_gt_i32_e64 s[48:49], 17, v33
	s_and_b64 s[50:51], s[52:53], s[50:51]
	v_cmp_gt_i32_e64 s[46:47], 16, v33
	s_and_b64 s[48:49], s[50:51], s[48:49]
	v_cmp_gt_i32_e64 s[44:45], 11, v33
	s_and_b64 s[46:47], s[48:49], s[46:47]
	v_cmp_gt_i32_e64 s[42:43], 10, v33
	s_and_b64 s[44:45], s[46:47], s[44:45]
	v_cmp_gt_i32_e64 s[40:41], 9, v33
	s_and_b64 s[42:43], s[44:45], s[42:43]
	v_cmp_gt_i32_e64 s[38:39], 8, v33
	s_and_b64 s[40:41], s[42:43], s[40:41]
	v_cmp_gt_i32_e64 s[36:37], 3, v33
	s_and_b64 s[38:39], s[40:41], s[38:39]
	v_cmp_gt_i32_e64 s[34:35], 2, v33
	s_and_b64 s[36:37], s[38:39], s[36:37]
	v_cmp_gt_i32_e64 s[30:31], 1, v33
	s_and_b64 s[34:35], s[36:37], s[34:35]
	v_cmp_gt_i32_e64 s[28:29], 0, v33
	s_and_b64 s[30:31], s[34:35], s[30:31]
	s_and_b64 s[28:29], s[30:31], s[28:29]
	v_cmp_gt_i32_e64 s[26:27], 58, v33
	v_cndmask_b32_e64 v16, v16, v169, s[28:29]
	v_cmp_gt_i32_e64 s[28:29], 59, v33
	v_cmp_gt_i32_e64 s[24:25], 57, v33
	s_and_b64 s[26:27], s[28:29], s[26:27]
	v_cmp_gt_i32_e64 s[22:23], 56, v33
	s_and_b64 s[24:25], s[26:27], s[24:25]
	v_cmp_gt_i32_e64 s[20:21], 51, v33
	s_and_b64 s[22:23], s[24:25], s[22:23]
	v_cmp_gt_i32_e64 s[18:19], 50, v33
	s_and_b64 s[20:21], s[22:23], s[20:21]
	v_cmp_gt_i32_e64 s[16:17], 49, v33
	s_and_b64 s[18:19], s[20:21], s[18:19]
	v_cmp_gt_i32_e64 s[14:15], 48, v33
	s_and_b64 s[16:17], s[18:19], s[16:17]
	v_cmp_gt_i32_e64 s[12:13], 43, v33
	s_and_b64 s[14:15], s[16:17], s[14:15]
	v_cmp_gt_i32_e64 s[10:11], 42, v33
	s_and_b64 s[12:13], s[14:15], s[12:13]
	v_cmp_gt_i32_e64 s[8:9], 41, v33
	s_and_b64 s[10:11], s[12:13], s[10:11]
	v_cmp_gt_i32_e64 s[6:7], 40, v33
	s_and_b64 s[8:9], s[10:11], s[8:9]
	v_cmp_gt_i32_e64 s[4:5], 35, v33
	s_and_b64 s[6:7], s[8:9], s[6:7]
	v_cmp_gt_i32_e64 s[2:3], 34, v33
	s_and_b64 s[4:5], s[6:7], s[4:5]
	v_cmp_gt_i32_e64 s[0:1], 33, v33
	s_and_b64 s[2:3], s[4:5], s[2:3]
	v_cmp_gt_i32_e32 vcc, 32, v33
	s_and_b64 s[0:1], s[2:3], s[0:1]
	s_and_b64 vcc, s[0:1], vcc
	v_cndmask_b32_e64 v31, v31, v169, s[60:61]
	v_cndmask_b32_e64 v30, v30, v169, s[58:59]
	v_cndmask_b32_e64 v29, v29, v169, s[56:57]
	v_cndmask_b32_e64 v28, v28, v169, s[54:55]
	v_cndmask_b32_e64 v27, v27, v169, s[52:53]
	v_cndmask_b32_e64 v26, v26, v169, s[50:51]
	v_cndmask_b32_e64 v25, v25, v169, s[48:49]
	v_cndmask_b32_e64 v24, v24, v169, s[46:47]
	v_cndmask_b32_e64 v23, v23, v169, s[44:45]
	v_cndmask_b32_e64 v22, v22, v169, s[42:43]
	v_cndmask_b32_e64 v21, v21, v169, s[40:41]
	v_cndmask_b32_e64 v20, v20, v169, s[38:39]
	v_cndmask_b32_e64 v19, v19, v169, s[36:37]
	v_cndmask_b32_e64 v18, v18, v169, s[34:35]
	v_cndmask_b32_e64 v17, v17, v169, s[30:31]
	v_cndmask_b32_e64 v15, v15, v169, s[28:29]
	v_cndmask_b32_e64 v14, v14, v169, s[26:27]
	v_cndmask_b32_e64 v13, v13, v169, s[24:25]
	v_cndmask_b32_e64 v12, v12, v169, s[22:23]
	v_cndmask_b32_e64 v11, v11, v169, s[20:21]
	v_cndmask_b32_e64 v10, v10, v169, s[18:19]
	v_cndmask_b32_e64 v9, v9, v169, s[16:17]
	v_cndmask_b32_e64 v8, v8, v169, s[14:15]
	v_cndmask_b32_e64 v7, v7, v169, s[12:13]
	v_cndmask_b32_e64 v6, v6, v169, s[10:11]
	v_cndmask_b32_e64 v5, v5, v169, s[8:9]
	v_cndmask_b32_e64 v4, v4, v169, s[6:7]
	v_cndmask_b32_e64 v3, v3, v169, s[4:5]
	v_cndmask_b32_e64 v2, v2, v169, s[2:3]
	v_cndmask_b32_e64 v1, v1, v169, s[0:1]
	v_cndmask_b32_e32 v0, v0, v169, vcc
.LBB0_1315:
	s_nop 2
	v_exp_f32_e32 v16, v16
	v_exp_f32_e32 v17, v17
	v_exp_f32_e32 v18, v18
	v_exp_f32_e32 v19, v19
	v_exp_f32_e32 v20, v20
	v_exp_f32_e32 v21, v21
	v_exp_f32_e32 v22, v22
	v_exp_f32_e32 v23, v23
	v_exp_f32_e32 v24, v24
	v_exp_f32_e32 v25, v25
	v_exp_f32_e32 v26, v26
	v_exp_f32_e32 v27, v27
	v_exp_f32_e32 v28, v28
	v_exp_f32_e32 v29, v29
	v_exp_f32_e32 v30, v30
	v_exp_f32_e32 v31, v31
	v_exp_f32_e32 v0, v0
	v_exp_f32_e32 v1, v1
	v_exp_f32_e32 v2, v2
	v_exp_f32_e32 v3, v3
	v_exp_f32_e32 v4, v4
	v_exp_f32_e32 v5, v5
	v_exp_f32_e32 v6, v6
	v_exp_f32_e32 v7, v7
	v_exp_f32_e32 v8, v8
	v_exp_f32_e32 v9, v9
	v_exp_f32_e32 v10, v10
	v_exp_f32_e32 v11, v11
	v_exp_f32_e32 v12, v12
	v_exp_f32_e32 v13, v13
	v_exp_f32_e32 v14, v14
	v_exp_f32_e32 v15, v15
	v_add_f32_e32 v148, v16, v17
	v_add_f32_e32 v149, v18, v19
	v_add_f32_e32 v150, v20, v21
	v_add_f32_e32 v151, v22, v23
	v_add_f32_e32 v152, v24, v25
	v_add_f32_e32 v153, v26, v27
	v_add_f32_e32 v154, v28, v29
	v_add_f32_e32 v155, v30, v31
	v_add_f32_e32 v156, v0, v1
	v_add_f32_e32 v157, v2, v3
	v_add_f32_e32 v158, v4, v5
	v_add_f32_e32 v159, v6, v7
	v_add_f32_e32 v160, v8, v9
	v_add_f32_e32 v161, v10, v11
	v_add_f32_e32 v162, v12, v13
	v_add_f32_e32 v163, v14, v15
	v_add_f32_e32 v148, v148, v156
	v_add_f32_e32 v149, v149, v157
	v_add_f32_e32 v150, v150, v158
	v_add_f32_e32 v151, v151, v159
	v_add_f32_e32 v152, v152, v160
	v_add_f32_e32 v153, v153, v161
	v_add_f32_e32 v154, v154, v162
	v_add_f32_e32 v155, v155, v163
	v_add_f32_e32 v148, v148, v152
	v_add_f32_e32 v149, v149, v153
	v_add_f32_e32 v150, v150, v154
	v_add_f32_e32 v151, v151, v155
	v_add_f32_e32 v148, v148, v150
	v_add_f32_e32 v149, v149, v151
	v_add_f32_e32 v33, v148, v149
	s_nop 0
	v_mov_b32_e32 v34, v33
	s_nop 1
	v_permlane32_swap_b32_e32 v33, v34
	v_add_f32_e32 v33, v33, v34
	v_add_f32_e32 v191, 0, v33
	v_cvt_pk_bf16_f32 v160, v16, v17
	v_cvt_pk_bf16_f32 v161, v18, v19
	v_cvt_pk_bf16_f32 v162, v20, v21
	v_cvt_pk_bf16_f32 v163, v22, v23
	v_cvt_pk_bf16_f32 v156, v24, v25
	v_cvt_pk_bf16_f32 v157, v26, v27
	v_cvt_pk_bf16_f32 v158, v28, v29
	v_cvt_pk_bf16_f32 v159, v30, v31
	v_cvt_pk_bf16_f32 v152, v0, v1
	v_cvt_pk_bf16_f32 v153, v2, v3
	v_cvt_pk_bf16_f32 v154, v4, v5
	v_cvt_pk_bf16_f32 v155, v6, v7
	v_cvt_pk_bf16_f32 v148, v8, v9
	v_cvt_pk_bf16_f32 v149, v10, v11
	v_cvt_pk_bf16_f32 v150, v12, v13
	v_cvt_pk_bf16_f32 v151, v14, v15
	s_mov_b64 s[0:1], 0

.LBB0_1328:
	s_setprio 1
	ds_read_b128 v[64:67], v194 offset:256
	ds_read_b128 v[68:71], v194 offset:288
	ds_read_b128 v[72:75], v194 offset:320
	ds_read_b128 v[76:79], v194 offset:352
	ds_read_b128 v[196:199], v194 offset:384
	ds_read_b128 v[200:203], v194 offset:416
	ds_read_b128 v[204:207], v194 offset:448
	ds_read_b128 v[208:211], v194 offset:480
	s_add_i32 s0, s84, 64
	s_waitcnt lgkmcnt(4)
	v_pk_add_f32 v[94:95], v[78:79], v[180:181] op_sel:[0,1] op_sel_hi:[1,1] neg_lo:[0,1] neg_hi:[0,1]
	v_pk_add_f32 v[92:93], v[76:77], v[180:181] op_sel:[0,1] op_sel_hi:[1,1] neg_lo:[0,1] neg_hi:[0,1]
	v_pk_add_f32 v[90:91], v[74:75], v[180:181] op_sel:[0,1] op_sel_hi:[1,1] neg_lo:[0,1] neg_hi:[0,1]
	v_pk_add_f32 v[88:89], v[72:73], v[180:181] op_sel:[0,1] op_sel_hi:[1,1] neg_lo:[0,1] neg_hi:[0,1]
	v_pk_add_f32 v[86:87], v[70:71], v[180:181] op_sel:[0,1] op_sel_hi:[1,1] neg_lo:[0,1] neg_hi:[0,1]
	v_pk_add_f32 v[84:85], v[68:69], v[180:181] op_sel:[0,1] op_sel_hi:[1,1] neg_lo:[0,1] neg_hi:[0,1]
	v_pk_add_f32 v[82:83], v[66:67], v[180:181] op_sel:[0,1] op_sel_hi:[1,1] neg_lo:[0,1] neg_hi:[0,1]
	v_pk_add_f32 v[80:81], v[64:65], v[180:181] op_sel:[0,1] op_sel_hi:[1,1] neg_lo:[0,1] neg_hi:[0,1]
	s_waitcnt lgkmcnt(0)
	v_pk_add_f32 v[78:79], v[210:211], v[180:181] op_sel:[0,1] op_sel_hi:[1,1] neg_lo:[0,1] neg_hi:[0,1]
	v_pk_add_f32 v[76:77], v[208:209], v[180:181] op_sel:[0,1] op_sel_hi:[1,1] neg_lo:[0,1] neg_hi:[0,1]
	v_pk_add_f32 v[74:75], v[206:207], v[180:181] op_sel:[0,1] op_sel_hi:[1,1] neg_lo:[0,1] neg_hi:[0,1]
	v_pk_add_f32 v[72:73], v[204:205], v[180:181] op_sel:[0,1] op_sel_hi:[1,1] neg_lo:[0,1] neg_hi:[0,1]
	v_pk_add_f32 v[70:71], v[202:203], v[180:181] op_sel:[0,1] op_sel_hi:[1,1] neg_lo:[0,1] neg_hi:[0,1]
	v_pk_add_f32 v[68:69], v[200:201], v[180:181] op_sel:[0,1] op_sel_hi:[1,1] neg_lo:[0,1] neg_hi:[0,1]
	v_pk_add_f32 v[66:67], v[198:199], v[180:181] op_sel:[0,1] op_sel_hi:[1,1] neg_lo:[0,1] neg_hi:[0,1]
	v_pk_add_f32 v[64:65], v[196:197], v[180:181] op_sel:[0,1] op_sel_hi:[1,1] neg_lo:[0,1] neg_hi:[0,1]
	ds_read_b64_tr_b16 v[196:197], v179 offset:0
	ds_read_b64_tr_b16 v[198:199], v179 offset:0x800
	ds_read_b64_tr_b16 v[200:201], v179 offset:0x1000
	ds_read_b64_tr_b16 v[202:203], v179 offset:0x1800
	ds_read_b64_tr_b16 v[204:205], v179 offset:0x2000
	ds_read_b64_tr_b16 v[206:207], v179 offset:0x2800
	ds_read_b64_tr_b16 v[208:209], v179 offset:0x3000
	ds_read_b64_tr_b16 v[210:211], v179 offset:0x3800
	ds_read_b64_tr_b16 v[212:213], v179 offset:0x200
	ds_read_b64_tr_b16 v[214:215], v179 offset:0xa00
	ds_read_b64_tr_b16 v[216:217], v179 offset:0x1200
	ds_read_b64_tr_b16 v[218:219], v179 offset:0x1a00
	ds_read_b64_tr_b16 v[220:221], v179 offset:0x2200
	ds_read_b64_tr_b16 v[222:223], v179 offset:0x2a00
	ds_read_b64_tr_b16 v[224:225], v179 offset:0x3200
	ds_read_b64_tr_b16 v[226:227], v179 offset:0x3a00
	s_waitcnt lgkmcnt(14)
	s_nop 0
	v_mfma_f32_32x32x16_bf16 v[0:15], v[160:163], v[196:199], v[0:15]
	ds_read_b64_tr_b16 v[196:197], v179 offset:0x400
	ds_read_b64_tr_b16 v[198:199], v179 offset:0xc00
	s_waitcnt lgkmcnt(14)
	v_mfma_f32_32x32x16_bf16 v[0:15], v[156:159], v[200:203], v[0:15]
	ds_read_b64_tr_b16 v[200:201], v179 offset:0x1400
	ds_read_b64_tr_b16 v[202:203], v179 offset:0x1c00
	s_waitcnt lgkmcnt(14)
	v_mfma_f32_32x32x16_bf16 v[0:15], v[152:155], v[204:207], v[0:15]
	ds_read_b64_tr_b16 v[204:205], v179 offset:0x2400
	ds_read_b64_tr_b16 v[206:207], v179 offset:0x2c00
	s_waitcnt lgkmcnt(14)
	v_mfma_f32_32x32x16_bf16 v[0:15], v[148:151], v[208:211], v[0:15]
	ds_read_b64_tr_b16 v[208:209], v179 offset:0x3400
	ds_read_b64_tr_b16 v[210:211], v179 offset:0x3c00
	s_waitcnt lgkmcnt(14)
	v_mfma_f32_32x32x16_bf16 v[48:63], v[160:163], v[212:215], v[48:63]
	ds_read_b64_tr_b16 v[212:213], v179 offset:0x600
	ds_read_b64_tr_b16 v[214:215], v179 offset:0xe00
	s_waitcnt lgkmcnt(14)
	v_mfma_f32_32x32x16_bf16 v[48:63], v[156:159], v[216:219], v[48:63]
	ds_read_b64_tr_b16 v[216:217], v179 offset:0x1600
	ds_read_b64_tr_b16 v[218:219], v179 offset:0x1e00
	s_waitcnt lgkmcnt(14)
	v_mfma_f32_32x32x16_bf16 v[48:63], v[152:155], v[220:223], v[48:63]
	ds_read_b64_tr_b16 v[220:221], v179 offset:0x2600
	ds_read_b64_tr_b16 v[222:223], v179 offset:0x2e00
	s_waitcnt lgkmcnt(14)
	v_mfma_f32_32x32x16_bf16 v[48:63], v[148:151], v[224:227], v[48:63]
	ds_read_b64_tr_b16 v[224:225], v179 offset:0x3600
	ds_read_b64_tr_b16 v[226:227], v179 offset:0x3e00
	s_waitcnt lgkmcnt(14)
	v_mfma_f32_32x32x16_bf16 v[32:47], v[160:163], v[196:199], v[32:47]
	ds_read_b128 v[196:199], v189 offset:0xc000
	s_waitcnt lgkmcnt(13)
	v_mfma_f32_32x32x16_bf16 v[32:47], v[156:159], v[200:203], v[32:47]
	ds_read_b128 v[200:203], v189 offset:0xe000
	s_waitcnt lgkmcnt(12)
	v_mfma_f32_32x32x16_bf16 v[32:47], v[152:155], v[204:207], v[32:47]
	ds_read_b128 v[204:207], v188 offset:0xc000
	s_waitcnt lgkmcnt(11)
	v_mfma_f32_32x32x16_bf16 v[32:47], v[148:151], v[208:211], v[32:47]
	ds_read_b128 v[208:211], v188 offset:0xe000
	s_waitcnt lgkmcnt(10)
	v_mfma_f32_32x32x16_bf16 v[16:31], v[160:163], v[212:215], v[16:31]
	ds_read_b128 v[160:163], v187 offset:0xc000
	s_waitcnt lgkmcnt(9)
	v_mfma_f32_32x32x16_bf16 v[16:31], v[156:159], v[216:219], v[16:31]
	ds_read_b128 v[156:159], v187 offset:0xe000
	s_waitcnt lgkmcnt(8)
	v_mfma_f32_32x32x16_bf16 v[16:31], v[152:155], v[220:223], v[16:31]
	ds_read_b128 v[152:155], v184 offset:0xc000
	s_waitcnt lgkmcnt(7)
	v_mfma_f32_32x32x16_bf16 v[16:31], v[148:151], v[224:227], v[16:31]
	ds_read_b128 v[148:151], v184 offset:0xe000
	s_waitcnt lgkmcnt(7)
	v_mfma_f32_32x32x16_bf16 v[80:95], v[196:199], v[144:147], v[80:95]
	ds_read_b128 v[196:199], v182 offset:0xc000
	s_waitcnt lgkmcnt(7)
	v_mfma_f32_32x32x16_bf16 v[64:79], v[200:203], v[144:147], v[64:79]
	ds_read_b128 v[200:203], v182 offset:0xe000
	s_waitcnt lgkmcnt(7)
	v_mfma_f32_32x32x16_bf16 v[80:95], v[204:207], v[136:139], v[80:95]
	ds_read_b128 v[204:207], v183 offset:0xc000
	s_waitcnt lgkmcnt(7)
	v_mfma_f32_32x32x16_bf16 v[64:79], v[208:211], v[136:139], v[64:79]
	ds_read_b128 v[208:211], v183 offset:0xe000
	s_waitcnt lgkmcnt(7)
	v_mfma_f32_32x32x16_bf16 v[80:95], v[160:163], v[128:131], v[80:95]
	ds_read_b128 v[160:163], v185 offset:0xc000
	s_waitcnt lgkmcnt(7)
	v_mfma_f32_32x32x16_bf16 v[64:79], v[156:159], v[128:131], v[64:79]
	ds_read_b128 v[156:159], v185 offset:0xe000
	s_waitcnt lgkmcnt(7)
	v_mfma_f32_32x32x16_bf16 v[80:95], v[152:155], v[124:127], v[80:95]
	ds_read_b128 v[152:155], v186 offset:0xc000
	s_waitcnt lgkmcnt(7)
	v_mfma_f32_32x32x16_bf16 v[64:79], v[148:151], v[124:127], v[64:79]
	ds_read_b128 v[148:151], v186 offset:0xe000
	s_waitcnt lgkmcnt(7)
	v_mfma_f32_32x32x16_bf16 v[80:95], v[196:199], v[120:123], v[80:95]
	s_waitcnt lgkmcnt(6)
	v_mfma_f32_32x32x16_bf16 v[64:79], v[200:203], v[120:123], v[64:79]
	s_waitcnt lgkmcnt(5)
	v_mfma_f32_32x32x16_bf16 v[80:95], v[204:207], v[116:119], v[80:95]
	s_waitcnt lgkmcnt(4)
	v_mfma_f32_32x32x16_bf16 v[64:79], v[208:211], v[116:119], v[64:79]
	s_waitcnt lgkmcnt(3)
	v_mfma_f32_32x32x16_bf16 v[80:95], v[160:163], v[140:143], v[80:95]
	s_waitcnt lgkmcnt(2)
	v_mfma_f32_32x32x16_bf16 v[64:79], v[156:159], v[140:143], v[64:79]
	s_waitcnt lgkmcnt(1)
	v_mfma_f32_32x32x16_bf16 v[80:95], v[152:155], v[132:135], v[80:95]
	s_waitcnt lgkmcnt(0)
	v_mfma_f32_32x32x16_bf16 v[64:79], v[148:151], v[132:135], v[64:79]
	s_setprio 0
	s_waitcnt lgkmcnt(0)
	s_barrier
	s_cmp_le_i32 s0, s78
	s_mov_b64 s[0:1], -1
	s_cbranch_scc0 .LBB0_1332
	s_add_i32 s0, s84, 0x7f
	s_cmp_le_i32 s0, s75
	s_cbranch_scc1 .LBB0_1331
	v_subrev_u32_e32 v97, 64, v193
	v_cmp_gt_i32_e64 s[58:59], 26, v97
	v_cmp_gt_i32_e64 s[60:61], 27, v97
	v_cmp_gt_i32_e64 s[56:57], 25, v97
	s_and_b64 s[58:59], s[60:61], s[58:59]
	v_cmp_gt_i32_e64 s[54:55], 24, v97
	s_and_b64 s[56:57], s[58:59], s[56:57]
	v_cmp_gt_i32_e64 s[52:53], 19, v97
	s_and_b64 s[54:55], s[56:57], s[54:55]
	v_cmp_gt_i32_e64 s[50:51], 18, v97
	s_and_b64 s[52:53], s[54:55], s[52:53]
	v_cmp_gt_i32_e64 s[48:49], 17, v97
	s_and_b64 s[50:51], s[52:53], s[50:51]
	v_cmp_gt_i32_e64 s[46:47], 16, v97
	s_and_b64 s[48:49], s[50:51], s[48:49]
	v_cmp_gt_i32_e64 s[44:45], 11, v97
	s_and_b64 s[46:47], s[48:49], s[46:47]
	v_cmp_gt_i32_e64 s[42:43], 10, v97
	s_and_b64 s[44:45], s[46:47], s[44:45]
	v_cmp_gt_i32_e64 s[40:41], 9, v97
	s_and_b64 s[42:43], s[44:45], s[42:43]
	v_cmp_gt_i32_e64 s[38:39], 8, v97
	s_and_b64 s[40:41], s[42:43], s[40:41]
	v_cmp_gt_i32_e64 s[36:37], 3, v97
	s_and_b64 s[38:39], s[40:41], s[38:39]
	v_cmp_gt_i32_e64 s[34:35], 2, v97
	s_and_b64 s[36:37], s[38:39], s[36:37]
	v_cmp_gt_i32_e64 s[30:31], 1, v97
	s_and_b64 s[34:35], s[36:37], s[34:35]
	v_cmp_gt_i32_e64 s[28:29], 0, v97
	s_and_b64 s[30:31], s[34:35], s[30:31]
	s_and_b64 s[28:29], s[30:31], s[28:29]
	v_cmp_gt_i32_e64 s[26:27], 58, v97
	v_cndmask_b32_e64 v80, v80, v169, s[28:29]
	v_cmp_gt_i32_e64 s[28:29], 59, v97
	v_cmp_gt_i32_e64 s[24:25], 57, v97
	s_and_b64 s[26:27], s[28:29], s[26:27]
	v_cmp_gt_i32_e64 s[22:23], 56, v97
	s_and_b64 s[24:25], s[26:27], s[24:25]
	v_cmp_gt_i32_e64 s[20:21], 51, v97
	s_and_b64 s[22:23], s[24:25], s[22:23]
	v_cmp_gt_i32_e64 s[18:19], 50, v97
	s_and_b64 s[20:21], s[22:23], s[20:21]
	v_cmp_gt_i32_e64 s[16:17], 49, v97
	s_and_b64 s[18:19], s[20:21], s[18:19]
	v_cmp_gt_i32_e64 s[14:15], 48, v97
	s_and_b64 s[16:17], s[18:19], s[16:17]
	v_cmp_gt_i32_e64 s[12:13], 43, v97
	s_and_b64 s[14:15], s[16:17], s[14:15]
	v_cmp_gt_i32_e64 s[10:11], 42, v97
	s_and_b64 s[12:13], s[14:15], s[12:13]
	v_cmp_gt_i32_e64 s[8:9], 41, v97
	s_and_b64 s[10:11], s[12:13], s[10:11]
	v_cmp_gt_i32_e64 s[6:7], 40, v97
	s_and_b64 s[8:9], s[10:11], s[8:9]
	v_cmp_gt_i32_e64 s[4:5], 35, v97
	s_and_b64 s[6:7], s[8:9], s[6:7]
	v_cmp_gt_i32_e64 s[2:3], 34, v97
	s_and_b64 s[4:5], s[6:7], s[4:5]
	v_cmp_gt_i32_e64 s[0:1], 33, v97
	s_and_b64 s[2:3], s[4:5], s[2:3]
	v_cmp_gt_i32_e32 vcc, 32, v97
	s_and_b64 s[0:1], s[2:3], s[0:1]
	s_and_b64 vcc, s[0:1], vcc
	v_cndmask_b32_e64 v95, v95, v169, s[60:61]
	v_cndmask_b32_e64 v94, v94, v169, s[58:59]
	v_cndmask_b32_e64 v93, v93, v169, s[56:57]
	v_cndmask_b32_e64 v92, v92, v169, s[54:55]
	v_cndmask_b32_e64 v91, v91, v169, s[52:53]
	v_cndmask_b32_e64 v90, v90, v169, s[50:51]
	v_cndmask_b32_e64 v89, v89, v169, s[48:49]
	v_cndmask_b32_e64 v88, v88, v169, s[46:47]
	v_cndmask_b32_e64 v87, v87, v169, s[44:45]
	v_cndmask_b32_e64 v86, v86, v169, s[42:43]
	v_cndmask_b32_e64 v85, v85, v169, s[40:41]
	v_cndmask_b32_e64 v84, v84, v169, s[38:39]
	v_cndmask_b32_e64 v83, v83, v169, s[36:37]
	v_cndmask_b32_e64 v82, v82, v169, s[34:35]
	v_cndmask_b32_e64 v81, v81, v169, s[30:31]
	v_cndmask_b32_e64 v79, v79, v169, s[28:29]
	v_cndmask_b32_e64 v78, v78, v169, s[26:27]
	v_cndmask_b32_e64 v77, v77, v169, s[24:25]
	v_cndmask_b32_e64 v76, v76, v169, s[22:23]
	v_cndmask_b32_e64 v75, v75, v169, s[20:21]
	v_cndmask_b32_e64 v74, v74, v169, s[18:19]
	v_cndmask_b32_e64 v73, v73, v169, s[16:17]
	v_cndmask_b32_e64 v72, v72, v169, s[14:15]
	v_cndmask_b32_e64 v71, v71, v169, s[12:13]
	v_cndmask_b32_e64 v70, v70, v169, s[10:11]
	v_cndmask_b32_e64 v69, v69, v169, s[8:9]
	v_cndmask_b32_e64 v68, v68, v169, s[6:7]
	v_cndmask_b32_e64 v67, v67, v169, s[4:5]
	v_cndmask_b32_e64 v66, v66, v169, s[2:3]
	v_cndmask_b32_e64 v65, v65, v169, s[0:1]
	v_cndmask_b32_e32 v64, v64, v169, vcc
.LBB0_1331:
	s_nop 2
	v_exp_f32_e32 v80, v80
	v_exp_f32_e32 v81, v81
	v_exp_f32_e32 v82, v82
	v_exp_f32_e32 v83, v83
	v_exp_f32_e32 v84, v84
	v_exp_f32_e32 v85, v85
	v_exp_f32_e32 v86, v86
	v_exp_f32_e32 v87, v87
	v_exp_f32_e32 v88, v88
	v_exp_f32_e32 v89, v89
	v_exp_f32_e32 v90, v90
	v_exp_f32_e32 v91, v91
	v_exp_f32_e32 v92, v92
	v_exp_f32_e32 v93, v93
	v_exp_f32_e32 v94, v94
	v_exp_f32_e32 v95, v95
	v_exp_f32_e32 v64, v64
	v_exp_f32_e32 v65, v65
	v_exp_f32_e32 v66, v66
	v_exp_f32_e32 v67, v67
	v_exp_f32_e32 v68, v68
	v_exp_f32_e32 v69, v69
	v_exp_f32_e32 v70, v70
	v_exp_f32_e32 v71, v71
	v_exp_f32_e32 v72, v72
	v_exp_f32_e32 v73, v73
	v_exp_f32_e32 v74, v74
	v_exp_f32_e32 v75, v75
	v_exp_f32_e32 v76, v76
	v_exp_f32_e32 v77, v77
	v_exp_f32_e32 v78, v78
	v_exp_f32_e32 v79, v79
	v_add_f32_e32 v148, v80, v81
	v_add_f32_e32 v149, v82, v83
	v_add_f32_e32 v150, v84, v85
	v_add_f32_e32 v151, v86, v87
	v_add_f32_e32 v152, v88, v89
	v_add_f32_e32 v153, v90, v91
	v_add_f32_e32 v154, v92, v93
	v_add_f32_e32 v155, v94, v95
	v_add_f32_e32 v156, v64, v65
	v_add_f32_e32 v157, v66, v67
	v_add_f32_e32 v158, v68, v69
	v_add_f32_e32 v159, v70, v71
	v_add_f32_e32 v160, v72, v73
	v_add_f32_e32 v161, v74, v75
	v_add_f32_e32 v162, v76, v77
	v_add_f32_e32 v163, v78, v79
	v_add_f32_e32 v148, v148, v156
	v_add_f32_e32 v149, v149, v157
	v_add_f32_e32 v150, v150, v158
	v_add_f32_e32 v151, v151, v159
	v_add_f32_e32 v152, v152, v160
	v_add_f32_e32 v153, v153, v161
	v_add_f32_e32 v154, v154, v162
	v_add_f32_e32 v155, v155, v163
	v_add_f32_e32 v148, v148, v152
	v_add_f32_e32 v149, v149, v153
	v_add_f32_e32 v150, v150, v154
	v_add_f32_e32 v151, v151, v155
	v_add_f32_e32 v148, v148, v150
	v_add_f32_e32 v149, v149, v151
	v_add_f32_e32 v97, v148, v149
	s_nop 0
	v_mov_b32_e32 v98, v97
	s_nop 1
	v_permlane32_swap_b32_e32 v97, v98
	v_add_f32_e32 v97, v97, v98
	v_add_f32_e32 v195, v191, v97
	v_cvt_pk_bf16_f32 v160, v80, v81
	v_cvt_pk_bf16_f32 v161, v82, v83
	v_cvt_pk_bf16_f32 v162, v84, v85
	v_cvt_pk_bf16_f32 v163, v86, v87
	v_cvt_pk_bf16_f32 v156, v88, v89
	v_cvt_pk_bf16_f32 v157, v90, v91
	v_cvt_pk_bf16_f32 v158, v92, v93
	v_cvt_pk_bf16_f32 v159, v94, v95
	v_cvt_pk_bf16_f32 v152, v64, v65
	v_cvt_pk_bf16_f32 v153, v66, v67
	v_cvt_pk_bf16_f32 v154, v68, v69
	v_cvt_pk_bf16_f32 v155, v70, v71
	v_cvt_pk_bf16_f32 v148, v72, v73
	v_cvt_pk_bf16_f32 v149, v74, v75
	v_cvt_pk_bf16_f32 v150, v76, v77
	v_cvt_pk_bf16_f32 v151, v78, v79
	s_mov_b64 s[0:1], 0

.LBB0_1336:
	v_lshl_add_u64 v[64:65], s[0:1], 0, v[164:165]
	v_lshl_add_u64 v[66:67], s[0:1], 0, v[166:167]
	global_load_dwordx4 v[100:103], v[64:65], off
	global_load_dwordx4 v[104:107], v[66:67], off
	v_lshl_add_u64 v[66:67], s[2:3], 0, v[164:165]
	v_lshl_add_u64 v[64:65], s[2:3], 0, v[166:167]
	global_load_dwordx4 v[112:115], v[66:67], off
	global_load_dwordx4 v[108:111], v[64:65], off
	s_waitcnt lgkmcnt(0)
	s_barrier
	s_setprio 1
	ds_read_b128 v[64:67], v194
	ds_read_b128 v[68:71], v194 offset:32
	ds_read_b128 v[72:75], v194 offset:64
	ds_read_b128 v[76:79], v194 offset:96
	ds_read_b128 v[196:199], v194 offset:128
	ds_read_b128 v[200:203], v194 offset:160
	ds_read_b128 v[204:207], v194 offset:192
	ds_read_b128 v[208:211], v194 offset:224
	s_waitcnt lgkmcnt(4)
	v_pk_add_f32 v[94:95], v[78:79], v[180:181] op_sel:[0,1] op_sel_hi:[1,1] neg_lo:[0,1] neg_hi:[0,1]
	v_pk_add_f32 v[92:93], v[76:77], v[180:181] op_sel:[0,1] op_sel_hi:[1,1] neg_lo:[0,1] neg_hi:[0,1]
	v_pk_add_f32 v[90:91], v[74:75], v[180:181] op_sel:[0,1] op_sel_hi:[1,1] neg_lo:[0,1] neg_hi:[0,1]
	v_pk_add_f32 v[88:89], v[72:73], v[180:181] op_sel:[0,1] op_sel_hi:[1,1] neg_lo:[0,1] neg_hi:[0,1]
	v_pk_add_f32 v[86:87], v[70:71], v[180:181] op_sel:[0,1] op_sel_hi:[1,1] neg_lo:[0,1] neg_hi:[0,1]
	v_pk_add_f32 v[84:85], v[68:69], v[180:181] op_sel:[0,1] op_sel_hi:[1,1] neg_lo:[0,1] neg_hi:[0,1]
	v_pk_add_f32 v[82:83], v[66:67], v[180:181] op_sel:[0,1] op_sel_hi:[1,1] neg_lo:[0,1] neg_hi:[0,1]
	v_pk_add_f32 v[80:81], v[64:65], v[180:181] op_sel:[0,1] op_sel_hi:[1,1] neg_lo:[0,1] neg_hi:[0,1]
	s_waitcnt lgkmcnt(0)
	v_pk_add_f32 v[78:79], v[210:211], v[180:181] op_sel:[0,1] op_sel_hi:[1,1] neg_lo:[0,1] neg_hi:[0,1]
	v_pk_add_f32 v[76:77], v[208:209], v[180:181] op_sel:[0,1] op_sel_hi:[1,1] neg_lo:[0,1] neg_hi:[0,1]
	v_pk_add_f32 v[74:75], v[206:207], v[180:181] op_sel:[0,1] op_sel_hi:[1,1] neg_lo:[0,1] neg_hi:[0,1]
	v_pk_add_f32 v[72:73], v[204:205], v[180:181] op_sel:[0,1] op_sel_hi:[1,1] neg_lo:[0,1] neg_hi:[0,1]
	v_pk_add_f32 v[70:71], v[202:203], v[180:181] op_sel:[0,1] op_sel_hi:[1,1] neg_lo:[0,1] neg_hi:[0,1]
	v_pk_add_f32 v[68:69], v[200:201], v[180:181] op_sel:[0,1] op_sel_hi:[1,1] neg_lo:[0,1] neg_hi:[0,1]
	v_pk_add_f32 v[66:67], v[198:199], v[180:181] op_sel:[0,1] op_sel_hi:[1,1] neg_lo:[0,1] neg_hi:[0,1]
	v_pk_add_f32 v[64:65], v[196:197], v[180:181] op_sel:[0,1] op_sel_hi:[1,1] neg_lo:[0,1] neg_hi:[0,1]
	ds_read_b64_tr_b16 v[196:197], v179 offset:0x4000
	ds_read_b64_tr_b16 v[198:199], v179 offset:0x4800
	ds_read_b64_tr_b16 v[200:201], v179 offset:0x5000
	ds_read_b64_tr_b16 v[202:203], v179 offset:0x5800
	ds_read_b64_tr_b16 v[204:205], v179 offset:0x6000
	ds_read_b64_tr_b16 v[206:207], v179 offset:0x6800
	ds_read_b64_tr_b16 v[208:209], v179 offset:0x7000
	ds_read_b64_tr_b16 v[210:211], v179 offset:0x7800
	ds_read_b64_tr_b16 v[212:213], v179 offset:0x4200
	ds_read_b64_tr_b16 v[214:215], v179 offset:0x4a00
	ds_read_b64_tr_b16 v[216:217], v179 offset:0x5200
	ds_read_b64_tr_b16 v[218:219], v179 offset:0x5a00
	ds_read_b64_tr_b16 v[220:221], v179 offset:0x6200
	ds_read_b64_tr_b16 v[222:223], v179 offset:0x6a00
	ds_read_b64_tr_b16 v[224:225], v179 offset:0x7200
	ds_read_b64_tr_b16 v[226:227], v179 offset:0x7a00
	s_waitcnt lgkmcnt(14)
	s_nop 0
	v_mfma_f32_32x32x16_bf16 v[0:15], v[160:163], v[196:199], v[0:15]
	ds_read_b64_tr_b16 v[196:197], v179 offset:0x4400
	ds_read_b64_tr_b16 v[198:199], v179 offset:0x4c00
	s_waitcnt lgkmcnt(14)
	v_mfma_f32_32x32x16_bf16 v[0:15], v[156:159], v[200:203], v[0:15]
	ds_read_b64_tr_b16 v[200:201], v179 offset:0x5400
	ds_read_b64_tr_b16 v[202:203], v179 offset:0x5c00
	s_waitcnt lgkmcnt(14)
	v_mfma_f32_32x32x16_bf16 v[0:15], v[152:155], v[204:207], v[0:15]
	ds_read_b64_tr_b16 v[204:205], v179 offset:0x6400
	ds_read_b64_tr_b16 v[206:207], v179 offset:0x6c00
	s_waitcnt lgkmcnt(14)
	v_mfma_f32_32x32x16_bf16 v[0:15], v[148:151], v[208:211], v[0:15]
	ds_read_b64_tr_b16 v[208:209], v179 offset:0x7400
	ds_read_b64_tr_b16 v[210:211], v179 offset:0x7c00
	s_waitcnt lgkmcnt(14)
	v_mfma_f32_32x32x16_bf16 v[48:63], v[160:163], v[212:215], v[48:63]
	ds_read_b64_tr_b16 v[212:213], v179 offset:0x4600
	ds_read_b64_tr_b16 v[214:215], v179 offset:0x4e00
	s_waitcnt lgkmcnt(14)
	v_mfma_f32_32x32x16_bf16 v[48:63], v[156:159], v[216:219], v[48:63]
	ds_read_b64_tr_b16 v[216:217], v179 offset:0x5600
	ds_read_b64_tr_b16 v[218:219], v179 offset:0x5e00
	s_waitcnt lgkmcnt(14)
	v_mfma_f32_32x32x16_bf16 v[48:63], v[152:155], v[220:223], v[48:63]
	ds_read_b64_tr_b16 v[220:221], v179 offset:0x6600
	ds_read_b64_tr_b16 v[222:223], v179 offset:0x6e00
	s_waitcnt lgkmcnt(14)
	v_mfma_f32_32x32x16_bf16 v[48:63], v[148:151], v[224:227], v[48:63]
	ds_read_b64_tr_b16 v[224:225], v179 offset:0x7600
	ds_read_b64_tr_b16 v[226:227], v179 offset:0x7e00
	s_waitcnt lgkmcnt(14)
	v_mfma_f32_32x32x16_bf16 v[32:47], v[160:163], v[196:199], v[32:47]
	ds_read_b128 v[196:199], v189 offset:0x8000
	s_waitcnt lgkmcnt(13)
	v_mfma_f32_32x32x16_bf16 v[32:47], v[156:159], v[200:203], v[32:47]
	ds_read_b128 v[200:203], v189 offset:0xa000
	s_waitcnt lgkmcnt(12)
	v_mfma_f32_32x32x16_bf16 v[32:47], v[152:155], v[204:207], v[32:47]
	ds_read_b128 v[204:207], v188 offset:0x8000
	s_waitcnt lgkmcnt(11)
	v_mfma_f32_32x32x16_bf16 v[32:47], v[148:151], v[208:211], v[32:47]
	ds_read_b128 v[208:211], v188 offset:0xa000
	s_waitcnt lgkmcnt(10)
	v_mfma_f32_32x32x16_bf16 v[16:31], v[160:163], v[212:215], v[16:31]
	ds_read_b128 v[160:163], v187 offset:0x8000
	s_waitcnt lgkmcnt(9)
	v_mfma_f32_32x32x16_bf16 v[16:31], v[156:159], v[216:219], v[16:31]
	ds_read_b128 v[156:159], v187 offset:0xa000
	s_waitcnt lgkmcnt(8)
	v_mfma_f32_32x32x16_bf16 v[16:31], v[152:155], v[220:223], v[16:31]
	ds_read_b128 v[152:155], v184 offset:0x8000
	s_waitcnt lgkmcnt(7)
	v_mfma_f32_32x32x16_bf16 v[16:31], v[148:151], v[224:227], v[16:31]
	ds_read_b128 v[148:151], v184 offset:0xa000
	s_waitcnt lgkmcnt(7)
	v_mfma_f32_32x32x16_bf16 v[80:95], v[196:199], v[144:147], v[80:95]
	ds_read_b128 v[196:199], v182 offset:0x8000
	s_waitcnt lgkmcnt(7)
	v_mfma_f32_32x32x16_bf16 v[64:79], v[200:203], v[144:147], v[64:79]
	ds_read_b128 v[200:203], v182 offset:0xa000
	s_waitcnt lgkmcnt(7)
	v_mfma_f32_32x32x16_bf16 v[80:95], v[204:207], v[136:139], v[80:95]
	ds_read_b128 v[204:207], v183 offset:0x8000
	s_waitcnt lgkmcnt(7)
	v_mfma_f32_32x32x16_bf16 v[64:79], v[208:211], v[136:139], v[64:79]
	ds_read_b128 v[208:211], v183 offset:0xa000
	s_waitcnt lgkmcnt(7)
	v_mfma_f32_32x32x16_bf16 v[80:95], v[160:163], v[128:131], v[80:95]
	ds_read_b128 v[160:163], v185 offset:0x8000
	s_waitcnt lgkmcnt(7)
	v_mfma_f32_32x32x16_bf16 v[64:79], v[156:159], v[128:131], v[64:79]
	ds_read_b128 v[156:159], v185 offset:0xa000
	s_waitcnt lgkmcnt(7)
	v_mfma_f32_32x32x16_bf16 v[80:95], v[152:155], v[124:127], v[80:95]
	ds_read_b128 v[152:155], v186 offset:0x8000
	s_waitcnt lgkmcnt(7)
	v_mfma_f32_32x32x16_bf16 v[64:79], v[148:151], v[124:127], v[64:79]
	ds_read_b128 v[148:151], v186 offset:0xa000
	s_waitcnt lgkmcnt(7)
	v_mfma_f32_32x32x16_bf16 v[80:95], v[196:199], v[120:123], v[80:95]
	s_waitcnt lgkmcnt(6)
	v_mfma_f32_32x32x16_bf16 v[64:79], v[200:203], v[120:123], v[64:79]
	s_waitcnt lgkmcnt(5)
	v_mfma_f32_32x32x16_bf16 v[80:95], v[204:207], v[116:119], v[80:95]
	s_waitcnt lgkmcnt(4)
	v_mfma_f32_32x32x16_bf16 v[64:79], v[208:211], v[116:119], v[64:79]
	s_waitcnt lgkmcnt(3)
	v_mfma_f32_32x32x16_bf16 v[80:95], v[160:163], v[140:143], v[80:95]
	s_waitcnt lgkmcnt(2)
	v_mfma_f32_32x32x16_bf16 v[64:79], v[156:159], v[140:143], v[64:79]
	s_waitcnt lgkmcnt(1)
	v_mfma_f32_32x32x16_bf16 v[80:95], v[152:155], v[132:135], v[80:95]
	s_waitcnt lgkmcnt(0)
	v_mfma_f32_32x32x16_bf16 v[64:79], v[148:151], v[132:135], v[64:79]
	s_setprio 0
	s_waitcnt lgkmcnt(0)
	s_barrier
	s_cmp_le_i32 s84, s78
	s_mov_b64 s[0:1], -1
	s_cbranch_scc0 .LBB0_1340
	s_add_i32 s0, s84, 63
	s_cmp_le_i32 s0, s75
	s_cbranch_scc1 .LBB0_1339
	v_cmp_gt_i32_e64 s[58:59], 26, v193
	v_cmp_gt_i32_e64 s[60:61], 27, v193
	v_cmp_gt_i32_e64 s[56:57], 25, v193
	s_and_b64 s[58:59], s[60:61], s[58:59]
	v_cmp_gt_i32_e64 s[54:55], 24, v193
	s_and_b64 s[56:57], s[58:59], s[56:57]
	v_cmp_gt_i32_e64 s[52:53], 19, v193
	s_and_b64 s[54:55], s[56:57], s[54:55]
	v_cmp_gt_i32_e64 s[50:51], 18, v193
	s_and_b64 s[52:53], s[54:55], s[52:53]
	v_cmp_gt_i32_e64 s[48:49], 17, v193
	s_and_b64 s[50:51], s[52:53], s[50:51]
	v_cmp_gt_i32_e64 s[46:47], 16, v193
	s_and_b64 s[48:49], s[50:51], s[48:49]
	v_cmp_gt_i32_e64 s[44:45], 11, v193
	s_and_b64 s[46:47], s[48:49], s[46:47]
	v_cmp_gt_i32_e64 s[42:43], 10, v193
	s_and_b64 s[44:45], s[46:47], s[44:45]
	v_cmp_gt_i32_e64 s[40:41], 9, v193
	s_and_b64 s[42:43], s[44:45], s[42:43]
	v_cmp_gt_i32_e64 s[38:39], 8, v193
	s_and_b64 s[40:41], s[42:43], s[40:41]
	v_cmp_gt_i32_e64 s[36:37], 3, v193
	s_and_b64 s[38:39], s[40:41], s[38:39]
	v_cmp_gt_i32_e64 s[34:35], 2, v193
	s_and_b64 s[36:37], s[38:39], s[36:37]
	v_cmp_gt_i32_e64 s[30:31], 1, v193
	s_and_b64 s[34:35], s[36:37], s[34:35]
	v_cmp_gt_i32_e64 s[28:29], 0, v193
	s_and_b64 s[30:31], s[34:35], s[30:31]
	s_and_b64 s[28:29], s[30:31], s[28:29]
	v_cmp_gt_i32_e64 s[26:27], 58, v193
	v_cndmask_b32_e64 v80, v80, v169, s[28:29]
	v_cmp_gt_i32_e64 s[28:29], 59, v193
	v_cmp_gt_i32_e64 s[24:25], 57, v193
	s_and_b64 s[26:27], s[28:29], s[26:27]
	v_cmp_gt_i32_e64 s[22:23], 56, v193
	s_and_b64 s[24:25], s[26:27], s[24:25]
	v_cmp_gt_i32_e64 s[20:21], 51, v193
	s_and_b64 s[22:23], s[24:25], s[22:23]
	v_cmp_gt_i32_e64 s[18:19], 50, v193
	s_and_b64 s[20:21], s[22:23], s[20:21]
	v_cmp_gt_i32_e64 s[16:17], 49, v193
	s_and_b64 s[18:19], s[20:21], s[18:19]
	v_cmp_gt_i32_e64 s[14:15], 48, v193
	s_and_b64 s[16:17], s[18:19], s[16:17]
	v_cmp_gt_i32_e64 s[12:13], 43, v193
	s_and_b64 s[14:15], s[16:17], s[14:15]
	v_cmp_gt_i32_e64 s[10:11], 42, v193
	s_and_b64 s[12:13], s[14:15], s[12:13]
	v_cmp_gt_i32_e64 s[8:9], 41, v193
	s_and_b64 s[10:11], s[12:13], s[10:11]
	v_cmp_gt_i32_e64 s[6:7], 40, v193
	s_and_b64 s[8:9], s[10:11], s[8:9]
	v_cmp_gt_i32_e64 s[4:5], 35, v193
	s_and_b64 s[6:7], s[8:9], s[6:7]
	v_cmp_gt_i32_e64 s[2:3], 34, v193
	s_and_b64 s[4:5], s[6:7], s[4:5]
	v_cmp_gt_i32_e64 s[0:1], 33, v193
	s_and_b64 s[2:3], s[4:5], s[2:3]
	v_cmp_gt_i32_e32 vcc, 32, v193
	s_and_b64 s[0:1], s[2:3], s[0:1]
	s_and_b64 vcc, s[0:1], vcc
	v_cndmask_b32_e64 v95, v95, v169, s[60:61]
	v_cndmask_b32_e64 v94, v94, v169, s[58:59]
	v_cndmask_b32_e64 v93, v93, v169, s[56:57]
	v_cndmask_b32_e64 v92, v92, v169, s[54:55]
	v_cndmask_b32_e64 v91, v91, v169, s[52:53]
	v_cndmask_b32_e64 v90, v90, v169, s[50:51]
	v_cndmask_b32_e64 v89, v89, v169, s[48:49]
	v_cndmask_b32_e64 v88, v88, v169, s[46:47]
	v_cndmask_b32_e64 v87, v87, v169, s[44:45]
	v_cndmask_b32_e64 v86, v86, v169, s[42:43]
	v_cndmask_b32_e64 v85, v85, v169, s[40:41]
	v_cndmask_b32_e64 v84, v84, v169, s[38:39]
	v_cndmask_b32_e64 v83, v83, v169, s[36:37]
	v_cndmask_b32_e64 v82, v82, v169, s[34:35]
	v_cndmask_b32_e64 v81, v81, v169, s[30:31]
	v_cndmask_b32_e64 v79, v79, v169, s[28:29]
	v_cndmask_b32_e64 v78, v78, v169, s[26:27]
	v_cndmask_b32_e64 v77, v77, v169, s[24:25]
	v_cndmask_b32_e64 v76, v76, v169, s[22:23]
	v_cndmask_b32_e64 v75, v75, v169, s[20:21]
	v_cndmask_b32_e64 v74, v74, v169, s[18:19]
	v_cndmask_b32_e64 v73, v73, v169, s[16:17]
	v_cndmask_b32_e64 v72, v72, v169, s[14:15]
	v_cndmask_b32_e64 v71, v71, v169, s[12:13]
	v_cndmask_b32_e64 v70, v70, v169, s[10:11]
	v_cndmask_b32_e64 v69, v69, v169, s[8:9]
	v_cndmask_b32_e64 v68, v68, v169, s[6:7]
	v_cndmask_b32_e64 v67, v67, v169, s[4:5]
	v_cndmask_b32_e64 v66, v66, v169, s[2:3]
	v_cndmask_b32_e64 v65, v65, v169, s[0:1]
	v_cndmask_b32_e32 v64, v64, v169, vcc
.LBB0_1339:
	s_nop 2
	v_exp_f32_e32 v80, v80
	v_exp_f32_e32 v81, v81
	v_exp_f32_e32 v82, v82
	v_exp_f32_e32 v83, v83
	v_exp_f32_e32 v84, v84
	v_exp_f32_e32 v85, v85
	v_exp_f32_e32 v86, v86
	v_exp_f32_e32 v87, v87
	v_exp_f32_e32 v88, v88
	v_exp_f32_e32 v89, v89
	v_exp_f32_e32 v90, v90
	v_exp_f32_e32 v91, v91
	v_exp_f32_e32 v92, v92
	v_exp_f32_e32 v93, v93
	v_exp_f32_e32 v94, v94
	v_exp_f32_e32 v95, v95
	v_exp_f32_e32 v64, v64
	v_exp_f32_e32 v65, v65
	v_exp_f32_e32 v66, v66
	v_exp_f32_e32 v67, v67
	v_exp_f32_e32 v68, v68
	v_exp_f32_e32 v69, v69
	v_exp_f32_e32 v70, v70
	v_exp_f32_e32 v71, v71
	v_exp_f32_e32 v72, v72
	v_exp_f32_e32 v73, v73
	v_exp_f32_e32 v74, v74
	v_exp_f32_e32 v75, v75
	v_exp_f32_e32 v76, v76
	v_exp_f32_e32 v77, v77
	v_exp_f32_e32 v78, v78
	v_exp_f32_e32 v79, v79
	v_add_f32_e32 v148, v80, v81
	v_add_f32_e32 v149, v82, v83
	v_add_f32_e32 v150, v84, v85
	v_add_f32_e32 v151, v86, v87
	v_add_f32_e32 v152, v88, v89
	v_add_f32_e32 v153, v90, v91
	v_add_f32_e32 v154, v92, v93
	v_add_f32_e32 v155, v94, v95
	v_add_f32_e32 v156, v64, v65
	v_add_f32_e32 v157, v66, v67
	v_add_f32_e32 v158, v68, v69
	v_add_f32_e32 v159, v70, v71
	v_add_f32_e32 v160, v72, v73
	v_add_f32_e32 v161, v74, v75
	v_add_f32_e32 v162, v76, v77
	v_add_f32_e32 v163, v78, v79
	v_add_f32_e32 v148, v148, v156
	v_add_f32_e32 v149, v149, v157
	v_add_f32_e32 v150, v150, v158
	v_add_f32_e32 v151, v151, v159
	v_add_f32_e32 v152, v152, v160
	v_add_f32_e32 v153, v153, v161
	v_add_f32_e32 v154, v154, v162
	v_add_f32_e32 v155, v155, v163
	v_add_f32_e32 v148, v148, v152
	v_add_f32_e32 v149, v149, v153
	v_add_f32_e32 v150, v150, v154
	v_add_f32_e32 v151, v151, v155
	v_add_f32_e32 v148, v148, v150
	v_add_f32_e32 v149, v149, v151
	v_add_f32_e32 v97, v148, v149
	s_nop 0
	v_mov_b32_e32 v98, v97
	s_nop 1
	v_permlane32_swap_b32_e32 v97, v98
	v_add_f32_e32 v97, v97, v98
	v_add_f32_e32 v191, v195, v97
	v_cvt_pk_bf16_f32 v160, v80, v81
	v_cvt_pk_bf16_f32 v161, v82, v83
	v_cvt_pk_bf16_f32 v162, v84, v85
	v_cvt_pk_bf16_f32 v163, v86, v87
	v_cvt_pk_bf16_f32 v156, v88, v89
	v_cvt_pk_bf16_f32 v157, v90, v91
	v_cvt_pk_bf16_f32 v158, v92, v93
	v_cvt_pk_bf16_f32 v159, v94, v95
	v_cvt_pk_bf16_f32 v152, v64, v65
	v_cvt_pk_bf16_f32 v153, v66, v67
	v_cvt_pk_bf16_f32 v154, v68, v69
	v_cvt_pk_bf16_f32 v155, v70, v71
	v_cvt_pk_bf16_f32 v148, v72, v73
	v_cvt_pk_bf16_f32 v149, v74, v75
	v_cvt_pk_bf16_f32 v150, v76, v77
	v_cvt_pk_bf16_f32 v151, v78, v79
	s_mov_b64 s[0:1], 0

.LBB0_1350:
	s_setprio 1
	v_lshl_add_u32 v80, s82, 8, v190
	ds_read_b128 v[64:67], v80
	ds_read_b128 v[68:71], v80 offset:32
	ds_read_b128 v[72:75], v80 offset:64
	ds_read_b128 v[76:79], v80 offset:96
	ds_read_b128 v[192:195], v80 offset:128
	ds_read_b128 v[196:199], v80 offset:160
	ds_read_b128 v[200:203], v80 offset:192
	ds_read_b128 v[204:207], v80 offset:224
	s_lshl_b32 s2, s82, 6
	s_waitcnt lgkmcnt(4)
	v_pk_add_f32 v[94:95], v[78:79], v[180:181] op_sel:[0,1] op_sel_hi:[1,1] neg_lo:[0,1] neg_hi:[0,1]
	v_pk_add_f32 v[92:93], v[76:77], v[180:181] op_sel:[0,1] op_sel_hi:[1,1] neg_lo:[0,1] neg_hi:[0,1]
	v_pk_add_f32 v[90:91], v[74:75], v[180:181] op_sel:[0,1] op_sel_hi:[1,1] neg_lo:[0,1] neg_hi:[0,1]
	v_pk_add_f32 v[88:89], v[72:73], v[180:181] op_sel:[0,1] op_sel_hi:[1,1] neg_lo:[0,1] neg_hi:[0,1]
	v_pk_add_f32 v[86:87], v[70:71], v[180:181] op_sel:[0,1] op_sel_hi:[1,1] neg_lo:[0,1] neg_hi:[0,1]
	v_pk_add_f32 v[84:85], v[68:69], v[180:181] op_sel:[0,1] op_sel_hi:[1,1] neg_lo:[0,1] neg_hi:[0,1]
	v_pk_add_f32 v[82:83], v[66:67], v[180:181] op_sel:[0,1] op_sel_hi:[1,1] neg_lo:[0,1] neg_hi:[0,1]
	v_pk_add_f32 v[80:81], v[64:65], v[180:181] op_sel:[0,1] op_sel_hi:[1,1] neg_lo:[0,1] neg_hi:[0,1]
	s_waitcnt lgkmcnt(0)
	v_pk_add_f32 v[78:79], v[206:207], v[180:181] op_sel:[0,1] op_sel_hi:[1,1] neg_lo:[0,1] neg_hi:[0,1]
	v_pk_add_f32 v[76:77], v[204:205], v[180:181] op_sel:[0,1] op_sel_hi:[1,1] neg_lo:[0,1] neg_hi:[0,1]
	v_pk_add_f32 v[74:75], v[202:203], v[180:181] op_sel:[0,1] op_sel_hi:[1,1] neg_lo:[0,1] neg_hi:[0,1]
	v_pk_add_f32 v[72:73], v[200:201], v[180:181] op_sel:[0,1] op_sel_hi:[1,1] neg_lo:[0,1] neg_hi:[0,1]
	v_pk_add_f32 v[70:71], v[198:199], v[180:181] op_sel:[0,1] op_sel_hi:[1,1] neg_lo:[0,1] neg_hi:[0,1]
	v_pk_add_f32 v[68:69], v[196:197], v[180:181] op_sel:[0,1] op_sel_hi:[1,1] neg_lo:[0,1] neg_hi:[0,1]
	v_pk_add_f32 v[66:67], v[194:195], v[180:181] op_sel:[0,1] op_sel_hi:[1,1] neg_lo:[0,1] neg_hi:[0,1]
	v_pk_add_f32 v[64:65], v[192:193], v[180:181] op_sel:[0,1] op_sel_hi:[1,1] neg_lo:[0,1] neg_hi:[0,1]
	ds_read_b64_tr_b16 v[192:193], v179 offset:0
	ds_read_b64_tr_b16 v[194:195], v179 offset:0x800
	ds_read_b64_tr_b16 v[196:197], v179 offset:0x1000
	ds_read_b64_tr_b16 v[198:199], v179 offset:0x1800
	ds_read_b64_tr_b16 v[200:201], v179 offset:0x2000
	ds_read_b64_tr_b16 v[202:203], v179 offset:0x2800
	ds_read_b64_tr_b16 v[204:205], v179 offset:0x3000
	ds_read_b64_tr_b16 v[206:207], v179 offset:0x3800
	ds_read_b64_tr_b16 v[208:209], v179 offset:0x200
	ds_read_b64_tr_b16 v[210:211], v179 offset:0xa00
	ds_read_b64_tr_b16 v[212:213], v179 offset:0x1200
	ds_read_b64_tr_b16 v[214:215], v179 offset:0x1a00
	ds_read_b64_tr_b16 v[216:217], v179 offset:0x2200
	ds_read_b64_tr_b16 v[218:219], v179 offset:0x2a00
	ds_read_b64_tr_b16 v[220:221], v179 offset:0x3200
	ds_read_b64_tr_b16 v[222:223], v179 offset:0x3a00
	s_waitcnt lgkmcnt(14)
	s_nop 0
	v_mfma_f32_32x32x16_bf16 v[0:15], v[160:163], v[192:195], v[0:15]
	ds_read_b64_tr_b16 v[192:193], v179 offset:0x400
	ds_read_b64_tr_b16 v[194:195], v179 offset:0xc00
	s_waitcnt lgkmcnt(14)
	v_mfma_f32_32x32x16_bf16 v[0:15], v[156:159], v[196:199], v[0:15]
	ds_read_b64_tr_b16 v[196:197], v179 offset:0x1400
	ds_read_b64_tr_b16 v[198:199], v179 offset:0x1c00
	s_waitcnt lgkmcnt(14)
	v_mfma_f32_32x32x16_bf16 v[0:15], v[152:155], v[200:203], v[0:15]
	ds_read_b64_tr_b16 v[200:201], v179 offset:0x2400
	ds_read_b64_tr_b16 v[202:203], v179 offset:0x2c00
	s_waitcnt lgkmcnt(14)
	v_mfma_f32_32x32x16_bf16 v[0:15], v[148:151], v[204:207], v[0:15]
	ds_read_b64_tr_b16 v[204:205], v179 offset:0x3400
	ds_read_b64_tr_b16 v[206:207], v179 offset:0x3c00
	s_waitcnt lgkmcnt(14)
	v_mfma_f32_32x32x16_bf16 v[48:63], v[160:163], v[208:211], v[48:63]
	ds_read_b64_tr_b16 v[208:209], v179 offset:0x600
	ds_read_b64_tr_b16 v[210:211], v179 offset:0xe00
	s_waitcnt lgkmcnt(14)
	v_mfma_f32_32x32x16_bf16 v[48:63], v[156:159], v[212:215], v[48:63]
	ds_read_b64_tr_b16 v[212:213], v179 offset:0x1600
	ds_read_b64_tr_b16 v[214:215], v179 offset:0x1e00
	s_waitcnt lgkmcnt(14)
	v_mfma_f32_32x32x16_bf16 v[48:63], v[152:155], v[216:219], v[48:63]
	ds_read_b64_tr_b16 v[216:217], v179 offset:0x2600
	ds_read_b64_tr_b16 v[218:219], v179 offset:0x2e00
	s_waitcnt lgkmcnt(14)
	v_mfma_f32_32x32x16_bf16 v[48:63], v[148:151], v[220:223], v[48:63]
	ds_read_b64_tr_b16 v[220:221], v179 offset:0x3600
	ds_read_b64_tr_b16 v[222:223], v179 offset:0x3e00
	s_waitcnt lgkmcnt(14)
	v_mfma_f32_32x32x16_bf16 v[32:47], v[160:163], v[192:195], v[32:47]
	ds_read_b128 v[192:195], v189 offset:0xc000
	s_waitcnt lgkmcnt(13)
	v_mfma_f32_32x32x16_bf16 v[32:47], v[156:159], v[196:199], v[32:47]
	ds_read_b128 v[196:199], v189 offset:0xe000
	s_waitcnt lgkmcnt(12)
	v_mfma_f32_32x32x16_bf16 v[32:47], v[152:155], v[200:203], v[32:47]
	ds_read_b128 v[200:203], v188 offset:0xc000
	s_waitcnt lgkmcnt(11)
	v_mfma_f32_32x32x16_bf16 v[32:47], v[148:151], v[204:207], v[32:47]
	ds_read_b128 v[204:207], v188 offset:0xe000
	s_waitcnt lgkmcnt(10)
	v_mfma_f32_32x32x16_bf16 v[16:31], v[160:163], v[208:211], v[16:31]
	ds_read_b128 v[160:163], v187 offset:0xc000
	s_waitcnt lgkmcnt(9)
	v_mfma_f32_32x32x16_bf16 v[16:31], v[156:159], v[212:215], v[16:31]
	ds_read_b128 v[156:159], v187 offset:0xe000
	s_waitcnt lgkmcnt(8)
	v_mfma_f32_32x32x16_bf16 v[16:31], v[152:155], v[216:219], v[16:31]
	ds_read_b128 v[152:155], v184 offset:0xc000
	s_waitcnt lgkmcnt(7)
	v_mfma_f32_32x32x16_bf16 v[16:31], v[148:151], v[220:223], v[16:31]
	ds_read_b128 v[148:151], v184 offset:0xe000
	s_waitcnt lgkmcnt(7)
	v_mfma_f32_32x32x16_bf16 v[80:95], v[192:195], v[144:147], v[80:95]
	ds_read_b128 v[192:195], v182 offset:0xc000
	s_waitcnt lgkmcnt(7)
	v_mfma_f32_32x32x16_bf16 v[64:79], v[196:199], v[144:147], v[64:79]
	ds_read_b128 v[144:147], v182 offset:0xe000
	s_waitcnt lgkmcnt(7)
	v_mfma_f32_32x32x16_bf16 v[80:95], v[200:203], v[136:139], v[80:95]
	ds_read_b128 v[196:199], v183 offset:0xc000
	s_waitcnt lgkmcnt(7)
	v_mfma_f32_32x32x16_bf16 v[64:79], v[204:207], v[136:139], v[64:79]
	ds_read_b128 v[136:139], v183 offset:0xe000
	s_waitcnt lgkmcnt(7)
	v_mfma_f32_32x32x16_bf16 v[80:95], v[160:163], v[128:131], v[80:95]
	ds_read_b128 v[160:163], v185 offset:0xc000
	s_waitcnt lgkmcnt(7)
	v_mfma_f32_32x32x16_bf16 v[64:79], v[156:159], v[128:131], v[64:79]
	ds_read_b128 v[128:131], v185 offset:0xe000
	s_waitcnt lgkmcnt(7)
	v_mfma_f32_32x32x16_bf16 v[80:95], v[152:155], v[124:127], v[80:95]
	ds_read_b128 v[152:155], v186 offset:0xc000
	s_waitcnt lgkmcnt(7)
	v_mfma_f32_32x32x16_bf16 v[64:79], v[148:151], v[124:127], v[64:79]
	ds_read_b128 v[124:127], v186 offset:0xe000
	s_waitcnt lgkmcnt(7)
	v_mfma_f32_32x32x16_bf16 v[80:95], v[192:195], v[120:123], v[80:95]
	s_waitcnt lgkmcnt(6)
	v_mfma_f32_32x32x16_bf16 v[64:79], v[144:147], v[120:123], v[64:79]
	s_waitcnt lgkmcnt(5)
	v_mfma_f32_32x32x16_bf16 v[80:95], v[196:199], v[116:119], v[80:95]
	s_waitcnt lgkmcnt(4)
	v_mfma_f32_32x32x16_bf16 v[64:79], v[136:139], v[116:119], v[64:79]
	s_waitcnt lgkmcnt(3)
	v_mfma_f32_32x32x16_bf16 v[80:95], v[160:163], v[140:143], v[80:95]
	s_waitcnt lgkmcnt(2)
	v_mfma_f32_32x32x16_bf16 v[64:79], v[128:131], v[140:143], v[64:79]
	s_waitcnt lgkmcnt(1)
	v_mfma_f32_32x32x16_bf16 v[80:95], v[152:155], v[132:135], v[80:95]
	s_waitcnt lgkmcnt(0)
	v_mfma_f32_32x32x16_bf16 v[64:79], v[124:127], v[132:135], v[64:79]
	s_setprio 0
	s_waitcnt lgkmcnt(0)
	s_barrier
	s_cmp_le_i32 s2, s78
	s_mov_b64 s[0:1], -1
	s_cbranch_scc0 .LBB0_1354
	s_or_b32 s0, s2, 63
	s_cmp_le_i32 s0, s75
	s_cbranch_scc1 .LBB0_1353
	v_subrev_u32_e32 v97, s2, v178
	v_cmp_gt_i32_e64 s[58:59], 26, v97
	v_cmp_gt_i32_e64 s[60:61], 27, v97
	v_cmp_gt_i32_e64 s[56:57], 25, v97
	s_and_b64 s[58:59], s[60:61], s[58:59]
	v_cmp_gt_i32_e64 s[54:55], 24, v97
	s_and_b64 s[56:57], s[58:59], s[56:57]
	v_cmp_gt_i32_e64 s[52:53], 19, v97
	s_and_b64 s[54:55], s[56:57], s[54:55]
	v_cmp_gt_i32_e64 s[50:51], 18, v97
	s_and_b64 s[52:53], s[54:55], s[52:53]
	v_cmp_gt_i32_e64 s[48:49], 17, v97
	s_and_b64 s[50:51], s[52:53], s[50:51]
	v_cmp_gt_i32_e64 s[46:47], 16, v97
	s_and_b64 s[48:49], s[50:51], s[48:49]
	v_cmp_gt_i32_e64 s[44:45], 11, v97
	s_and_b64 s[46:47], s[48:49], s[46:47]
	v_cmp_gt_i32_e64 s[42:43], 10, v97
	s_and_b64 s[44:45], s[46:47], s[44:45]
	v_cmp_gt_i32_e64 s[40:41], 9, v97
	s_and_b64 s[42:43], s[44:45], s[42:43]
	v_cmp_gt_i32_e64 s[38:39], 8, v97
	s_and_b64 s[40:41], s[42:43], s[40:41]
	v_cmp_gt_i32_e64 s[36:37], 3, v97
	s_and_b64 s[38:39], s[40:41], s[38:39]
	v_cmp_gt_i32_e64 s[34:35], 2, v97
	s_and_b64 s[36:37], s[38:39], s[36:37]
	v_cmp_gt_i32_e64 s[30:31], 1, v97
	s_and_b64 s[34:35], s[36:37], s[34:35]
	v_cmp_gt_i32_e64 s[28:29], 0, v97
	s_and_b64 s[30:31], s[34:35], s[30:31]
	s_and_b64 s[28:29], s[30:31], s[28:29]
	v_cmp_gt_i32_e64 s[26:27], 58, v97
	v_cndmask_b32_e64 v80, v80, v169, s[28:29]
	v_cmp_gt_i32_e64 s[28:29], 59, v97
	v_cmp_gt_i32_e64 s[24:25], 57, v97
	s_and_b64 s[26:27], s[28:29], s[26:27]
	v_cmp_gt_i32_e64 s[22:23], 56, v97
	s_and_b64 s[24:25], s[26:27], s[24:25]
	v_cmp_gt_i32_e64 s[20:21], 51, v97
	s_and_b64 s[22:23], s[24:25], s[22:23]
	v_cmp_gt_i32_e64 s[18:19], 50, v97
	s_and_b64 s[20:21], s[22:23], s[20:21]
	v_cmp_gt_i32_e64 s[16:17], 49, v97
	s_and_b64 s[18:19], s[20:21], s[18:19]
	v_cmp_gt_i32_e64 s[14:15], 48, v97
	s_and_b64 s[16:17], s[18:19], s[16:17]
	v_cmp_gt_i32_e64 s[12:13], 43, v97
	s_and_b64 s[14:15], s[16:17], s[14:15]
	v_cmp_gt_i32_e64 s[10:11], 42, v97
	s_and_b64 s[12:13], s[14:15], s[12:13]
	v_cmp_gt_i32_e64 s[8:9], 41, v97
	s_and_b64 s[10:11], s[12:13], s[10:11]
	v_cmp_gt_i32_e64 s[6:7], 40, v97
	s_and_b64 s[8:9], s[10:11], s[8:9]
	v_cmp_gt_i32_e64 s[4:5], 35, v97
	s_and_b64 s[6:7], s[8:9], s[6:7]
	v_cmp_gt_i32_e64 s[2:3], 34, v97
	s_and_b64 s[4:5], s[6:7], s[4:5]
	v_cmp_gt_i32_e64 s[0:1], 33, v97
	s_and_b64 s[2:3], s[4:5], s[2:3]
	v_cmp_gt_i32_e32 vcc, 32, v97
	s_and_b64 s[0:1], s[2:3], s[0:1]
	s_and_b64 vcc, s[0:1], vcc
	v_cndmask_b32_e64 v95, v95, v169, s[60:61]
	v_cndmask_b32_e64 v94, v94, v169, s[58:59]
	v_cndmask_b32_e64 v93, v93, v169, s[56:57]
	v_cndmask_b32_e64 v92, v92, v169, s[54:55]
	v_cndmask_b32_e64 v91, v91, v169, s[52:53]
	v_cndmask_b32_e64 v90, v90, v169, s[50:51]
	v_cndmask_b32_e64 v89, v89, v169, s[48:49]
	v_cndmask_b32_e64 v88, v88, v169, s[46:47]
	v_cndmask_b32_e64 v87, v87, v169, s[44:45]
	v_cndmask_b32_e64 v86, v86, v169, s[42:43]
	v_cndmask_b32_e64 v85, v85, v169, s[40:41]
	v_cndmask_b32_e64 v84, v84, v169, s[38:39]
	v_cndmask_b32_e64 v83, v83, v169, s[36:37]
	v_cndmask_b32_e64 v82, v82, v169, s[34:35]
	v_cndmask_b32_e64 v81, v81, v169, s[30:31]
	v_cndmask_b32_e64 v79, v79, v169, s[28:29]
	v_cndmask_b32_e64 v78, v78, v169, s[26:27]
	v_cndmask_b32_e64 v77, v77, v169, s[24:25]
	v_cndmask_b32_e64 v76, v76, v169, s[22:23]
	v_cndmask_b32_e64 v75, v75, v169, s[20:21]
	v_cndmask_b32_e64 v74, v74, v169, s[18:19]
	v_cndmask_b32_e64 v73, v73, v169, s[16:17]
	v_cndmask_b32_e64 v72, v72, v169, s[14:15]
	v_cndmask_b32_e64 v71, v71, v169, s[12:13]
	v_cndmask_b32_e64 v70, v70, v169, s[10:11]
	v_cndmask_b32_e64 v69, v69, v169, s[8:9]
	v_cndmask_b32_e64 v68, v68, v169, s[6:7]
	v_cndmask_b32_e64 v67, v67, v169, s[4:5]
	v_cndmask_b32_e64 v66, v66, v169, s[2:3]
	v_cndmask_b32_e64 v65, v65, v169, s[0:1]
	v_cndmask_b32_e32 v64, v64, v169, vcc
.LBB0_1353:
	s_nop 2
	v_exp_f32_e32 v80, v80
	v_exp_f32_e32 v81, v81
	v_exp_f32_e32 v82, v82
	v_exp_f32_e32 v83, v83
	v_exp_f32_e32 v84, v84
	v_exp_f32_e32 v85, v85
	v_exp_f32_e32 v86, v86
	v_exp_f32_e32 v87, v87
	v_exp_f32_e32 v88, v88
	v_exp_f32_e32 v89, v89
	v_exp_f32_e32 v90, v90
	v_exp_f32_e32 v91, v91
	v_exp_f32_e32 v92, v92
	v_exp_f32_e32 v93, v93
	v_exp_f32_e32 v94, v94
	v_exp_f32_e32 v95, v95
	v_exp_f32_e32 v64, v64
	v_exp_f32_e32 v65, v65
	v_exp_f32_e32 v66, v66
	v_exp_f32_e32 v67, v67
	v_exp_f32_e32 v68, v68
	v_exp_f32_e32 v69, v69
	v_exp_f32_e32 v70, v70
	v_exp_f32_e32 v71, v71
	v_exp_f32_e32 v72, v72
	v_exp_f32_e32 v73, v73
	v_exp_f32_e32 v74, v74
	v_exp_f32_e32 v75, v75
	v_exp_f32_e32 v76, v76
	v_exp_f32_e32 v77, v77
	v_exp_f32_e32 v78, v78
	v_exp_f32_e32 v79, v79
	v_add_f32_e32 v148, v80, v81
	v_add_f32_e32 v149, v82, v83
	v_add_f32_e32 v150, v84, v85
	v_add_f32_e32 v151, v86, v87
	v_add_f32_e32 v152, v88, v89
	v_add_f32_e32 v153, v90, v91
	v_add_f32_e32 v154, v92, v93
	v_add_f32_e32 v155, v94, v95
	v_add_f32_e32 v156, v64, v65
	v_add_f32_e32 v157, v66, v67
	v_add_f32_e32 v158, v68, v69
	v_add_f32_e32 v159, v70, v71
	v_add_f32_e32 v160, v72, v73
	v_add_f32_e32 v161, v74, v75
	v_add_f32_e32 v162, v76, v77
	v_add_f32_e32 v163, v78, v79
	v_add_f32_e32 v148, v148, v156
	v_add_f32_e32 v149, v149, v157
	v_add_f32_e32 v150, v150, v158
	v_add_f32_e32 v151, v151, v159
	v_add_f32_e32 v152, v152, v160
	v_add_f32_e32 v153, v153, v161
	v_add_f32_e32 v154, v154, v162
	v_add_f32_e32 v155, v155, v163
	v_add_f32_e32 v148, v148, v152
	v_add_f32_e32 v149, v149, v153
	v_add_f32_e32 v150, v150, v154
	v_add_f32_e32 v151, v151, v155
	v_add_f32_e32 v148, v148, v150
	v_add_f32_e32 v149, v149, v151
	v_add_f32_e32 v97, v148, v149
	s_nop 0
	v_mov_b32_e32 v98, v97
	s_nop 1
	v_permlane32_swap_b32_e32 v97, v98
	v_add_f32_e32 v97, v97, v98
	v_add_f32_e32 v97, v191, v97
	v_cvt_pk_bf16_f32 v160, v80, v81
	v_cvt_pk_bf16_f32 v161, v82, v83
	v_cvt_pk_bf16_f32 v162, v84, v85
	v_cvt_pk_bf16_f32 v163, v86, v87
	v_cvt_pk_bf16_f32 v156, v88, v89
	v_cvt_pk_bf16_f32 v157, v90, v91
	v_cvt_pk_bf16_f32 v158, v92, v93
	v_cvt_pk_bf16_f32 v159, v94, v95
	v_cvt_pk_bf16_f32 v152, v64, v65
	v_cvt_pk_bf16_f32 v153, v66, v67
	v_cvt_pk_bf16_f32 v154, v68, v69
	v_cvt_pk_bf16_f32 v155, v70, v71
	v_cvt_pk_bf16_f32 v148, v72, v73
	v_cvt_pk_bf16_f32 v149, v74, v75
	v_cvt_pk_bf16_f32 v150, v76, v77
	v_cvt_pk_bf16_f32 v151, v78, v79
	s_mov_b64 s[0:1], 0
